# L slots: the m0-to-LDS-DMA wait state is a ds_read instead of an s_nop (16 fewer s_nops per loop iteration per role)
# baseline (speedup 1.0000x reference)
; #define PG8_STAGE(bufoff, gbase, voff) do { _Pragma("unroll") for (int _i = 0; _i < 2; ++_i) \
;         __builtin_amdgcn_global_load_lds((const unsigned*)((const char*)(gbase) + (voff)[_i]), (PG8_LAS unsigned*)(lds + (bufoff) + ldsw + _i * 8192), 16, 0, 0); } while (0)
; #define PG8_LDA(dst, b, h) do { _Pragma("unroll") for (int m = 0; m < 4; ++m) _Pragma("unroll") for (int k = 0; k < 2; ++k) dst[m][k] = *(const PG8_LAS bf16x8*)(lds + PG8_SA(b, h) + aoff + m * 2048 + k * 1024); } while (0)
; #define PG8_LDB(dst, b, h) do { _Pragma("unroll") for (int n = 0; n < 2; ++n) _Pragma("unroll") for (int k = 0; k < 2; ++k) dst[n][k] = *(const PG8_LAS bf16x8*)(lds + PG8_SB(b, h) + boff + n * 2048 + k * 1024); } while (0)
; #define PG8_MMA(ai, bj, At, Bt) do { __builtin_amdgcn_s_setprio(1); _Pragma("unroll") for (int m = 0; m < 4; ++m) _Pragma("unroll") for (int n = 0; n < 2; ++n) _Pragma("unroll") for (int k = 0; k < 2; ++k) \
;         acc[ai][bj][m][n] = __builtin_amdgcn_mfma_f32_16x16x32_bf16(Bt[n][k], At[m][k], acc[ai][bj][m][n], 0, 0, 0); __builtin_amdgcn_s_setprio(0); } while (0)
; #define PG8_WAIT_V(n) asm volatile("s_waitcnt vmcnt(" #n ")" ::: "memory")
; template <class Epi, class Sched, bool ALIGN_EPI>
; __device__ __forceinline__ void gemm_phase(PG8_LAS unsigned char* lds, const Gemm g, const Sched& S, const Epi& E) {
;     ...
;             PG8_LDB(B0, 0, 0); PG8_LDB(B1, 0, 1); PG8_SCHED; PG8_LDA(At, 0, 0); PG8_STAGE(PG8_SA(1, 1), a1 + hstepA, voffA);
;             PG8_WAIT_V(8); PG8_WAIT_L(0); PG8_BAR; PG8_MMA(0, 0, At, B0); PG8_MMA(0, 1, At, B1); PG8_BAR; PG8_SCHED;
;             PG8_LDA(At, 0, 1); PG8_STAGE(PG8_SB(0, 0), b2, voffB); PG8_STAGE(PG8_SB(0, 1), b2 + hstepB, voffB); PG8_STAGE(PG8_SA(0, 0), a2, voffA);
;             PG8_WAIT_V(8); PG8_WAIT_L(0); PG8_BAR; PG8_MMA(1, 0, At, B0); PG8_MMA(1, 1, At, B1); PG8_BAR; PG8_SCHED;
;             PG8_LDB(B0, 1, 0); PG8_LDB(B1, 1, 1); PG8_SCHED; PG8_LDA(At, 1, 0); PG8_STAGE(PG8_SA(0, 1), a2 + hstepA, voffA);
;             PG8_WAIT_V(8); PG8_WAIT_L(0); PG8_BAR; PG8_MMA(0, 0, At, B0); PG8_MMA(0, 1, At, B1); PG8_BAR; PG8_SCHED;
;             PG8_LDA(At, 1, 1); PG8_STAGE(PG8_SB(1, 0), b3, voffB); PG8_STAGE(PG8_SB(1, 1), b3 + hstepB, voffB); PG8_STAGE(PG8_SA(1, 0), a3, voffA);
;             PG8_WAIT_V(8); PG8_WAIT_L(0); PG8_BAR; PG8_MMA(1, 0, At, B0); PG8_MMA(1, 1, At, B1); PG8_BAR; PG8_SCHED;
.Lp8k_A_first:
	s_add_u32 s28, s30, 0x80
	s_addc_u32 s29, s31, 0
	ds_read_b128 v[190:193], v155 offset:0
	ds_read_b128 v[194:197], v155 offset:1024
	s_add_i32 m0, s2, 0x18000
	ds_read_b128 v[198:201], v155 offset:2048
	global_load_lds_dwordx4 v134, s[28:29]
	ds_read_b128 v[202:205], v155 offset:3072
	ds_read_b128 v[206:209], v155 offset:4096
	s_add_i32 m0, s2, 0x1a000
	ds_read_b128 v[210:213], v155 offset:5120
	global_load_lds_dwordx4 v130, s[28:29]
	ds_read_b128 v[214:217], v155 offset:6144
	ds_read_b128 v[218:221], v155 offset:7168
	s_add_u32 s30, s28, 0x20000
	s_addc_u32 s31, s29, 0
	s_add_i32 m0, s2, 0x19000
	ds_read_b128 v[156:159], v153 offset:0
	global_load_lds_dwordx4 v134, s[30:31]
	ds_read_b128 v[160:163], v153 offset:1024
	ds_read_b128 v[164:167], v153 offset:2048
	s_add_i32 m0, s2, 0x1b000
	ds_read_b128 v[168:171], v153 offset:3072
	global_load_lds_dwordx4 v130, s[30:31]
	ds_read_b128 v[174:177], v153 offset:16384
	ds_read_b128 v[178:181], v153 offset:17408
	s_add_u32 s30, s28, 0x80000
	s_addc_u32 s31, s29, 0
	s_add_i32 m0, s2, 0x1c000
	ds_read_b128 v[182:185], v153 offset:18432
	global_load_lds_dwordx4 v134, s[30:31]
	ds_read_b128 v[186:189], v153 offset:19456
	ds_read_b128 v[222:225], v155 offset:16384
	s_add_i32 m0, s2, 0x1e000
	ds_read_b128 v[226:229], v155 offset:17408
	global_load_lds_dwordx4 v130, s[30:31]
	ds_read_b128 v[230:233], v155 offset:18432
	ds_read_b128 v[234:237], v155 offset:19456
	s_add_u32 s30, s28, 0xa0000
	s_addc_u32 s31, s29, 0
	s_add_i32 m0, s2, 0x1d000
	ds_read_b128 v[238:241], v155 offset:20480
	global_load_lds_dwordx4 v134, s[30:31]
	ds_read_b128 v[242:245], v155 offset:21504
	ds_read_b128 v[246:249], v155 offset:22528
	s_add_i32 m0, s2, 0x1f000
	ds_read_b128 v[250:253], v155 offset:23552
	global_load_lds_dwordx4 v130, s[30:31]
	s_add_u32 s28, s28, 0x80
	s_addc_u32 s29, s29, 0
.Lp8k_A_entry:
	s_waitcnt vmcnt(8) lgkmcnt(0)
	s_barrier
	v_mfma_f32_16x16x32_bf16 v[126:129], v[156:159], v[190:193], 0
	v_mfma_f32_16x16x32_bf16 v[126:129], v[160:163], v[194:197], v[126:129]
	v_mfma_f32_16x16x32_bf16 v[122:125], v[168:171], v[194:197], 0
	v_mfma_f32_16x16x32_bf16 v[122:125], v[164:167], v[190:193], v[122:125]
	v_mfma_f32_16x16x32_bf16 v[118:121], v[174:177], v[190:193], 0
	v_mfma_f32_16x16x32_bf16 v[118:121], v[178:181], v[194:197], v[118:121]
	v_mfma_f32_16x16x32_bf16 v[114:117], v[186:189], v[194:197], 0
	v_mfma_f32_16x16x32_bf16 v[114:117], v[182:185], v[190:193], v[114:117]
	v_mfma_f32_16x16x32_bf16 v[98:101], v[182:185], v[198:201], 0
	v_mfma_f32_16x16x32_bf16 v[98:101], v[186:189], v[202:205], v[98:101]
	v_mfma_f32_16x16x32_bf16 v[102:105], v[178:181], v[202:205], 0
	v_mfma_f32_16x16x32_bf16 v[102:105], v[174:177], v[198:201], v[102:105]
	v_mfma_f32_16x16x32_bf16 v[106:109], v[164:167], v[198:201], 0
	v_mfma_f32_16x16x32_bf16 v[106:109], v[168:171], v[202:205], v[106:109]
	v_mfma_f32_16x16x32_bf16 v[110:113], v[160:163], v[202:205], 0
	v_mfma_f32_16x16x32_bf16 v[110:113], v[156:159], v[198:201], v[110:113]
	v_mfma_f32_16x16x32_bf16 v[94:97], v[156:159], v[206:209], 0
	v_mfma_f32_16x16x32_bf16 v[94:97], v[160:163], v[210:213], v[94:97]
	v_mfma_f32_16x16x32_bf16 v[90:93], v[168:171], v[210:213], 0
	v_mfma_f32_16x16x32_bf16 v[90:93], v[164:167], v[206:209], v[90:93]
	v_mfma_f32_16x16x32_bf16 v[86:89], v[174:177], v[206:209], 0
	v_mfma_f32_16x16x32_bf16 v[86:89], v[178:181], v[210:213], v[86:89]
	v_mfma_f32_16x16x32_bf16 v[82:85], v[186:189], v[210:213], 0
	v_mfma_f32_16x16x32_bf16 v[82:85], v[182:185], v[206:209], v[82:85]
	v_mfma_f32_16x16x32_bf16 v[66:69], v[182:185], v[214:217], 0
	v_mfma_f32_16x16x32_bf16 v[66:69], v[186:189], v[218:221], v[66:69]
	v_mfma_f32_16x16x32_bf16 v[70:73], v[178:181], v[218:221], 0
	v_mfma_f32_16x16x32_bf16 v[70:73], v[174:177], v[214:217], v[70:73]
	v_mfma_f32_16x16x32_bf16 v[74:77], v[164:167], v[214:217], 0
	v_mfma_f32_16x16x32_bf16 v[74:77], v[168:171], v[218:221], v[74:77]
	v_mfma_f32_16x16x32_bf16 v[78:81], v[160:163], v[218:221], 0
	v_mfma_f32_16x16x32_bf16 v[78:81], v[156:159], v[214:217], v[78:81]
	v_mfma_f32_16x16x32_bf16 v[62:65], v[156:159], v[222:225], 0
	v_mfma_f32_16x16x32_bf16 v[62:65], v[160:163], v[226:229], v[62:65]
	v_mfma_f32_16x16x32_bf16 v[58:61], v[168:171], v[226:229], 0
	v_mfma_f32_16x16x32_bf16 v[58:61], v[164:167], v[222:225], v[58:61]
	v_mfma_f32_16x16x32_bf16 v[54:57], v[174:177], v[222:225], 0
	v_mfma_f32_16x16x32_bf16 v[54:57], v[178:181], v[226:229], v[54:57]
	v_mfma_f32_16x16x32_bf16 v[50:53], v[186:189], v[226:229], 0
	v_mfma_f32_16x16x32_bf16 v[50:53], v[182:185], v[222:225], v[50:53]
	v_mfma_f32_16x16x32_bf16 v[34:37], v[182:185], v[230:233], 0
	v_mfma_f32_16x16x32_bf16 v[34:37], v[186:189], v[234:237], v[34:37]
	v_mfma_f32_16x16x32_bf16 v[38:41], v[178:181], v[234:237], 0
	v_mfma_f32_16x16x32_bf16 v[38:41], v[174:177], v[230:233], v[38:41]
	v_mfma_f32_16x16x32_bf16 v[42:45], v[164:167], v[230:233], 0
	v_mfma_f32_16x16x32_bf16 v[42:45], v[168:171], v[234:237], v[42:45]
	v_mfma_f32_16x16x32_bf16 v[46:49], v[160:163], v[234:237], 0
	v_mfma_f32_16x16x32_bf16 v[46:49], v[156:159], v[230:233], v[46:49]
	v_mfma_f32_16x16x32_bf16 v[30:33], v[156:159], v[238:241], 0
	v_mfma_f32_16x16x32_bf16 v[30:33], v[160:163], v[242:245], v[30:33]
	v_mfma_f32_16x16x32_bf16 v[26:29], v[168:171], v[242:245], 0
	v_mfma_f32_16x16x32_bf16 v[26:29], v[164:167], v[238:241], v[26:29]
	v_mfma_f32_16x16x32_bf16 v[22:25], v[174:177], v[238:241], 0
	v_mfma_f32_16x16x32_bf16 v[22:25], v[178:181], v[242:245], v[22:25]
	v_mfma_f32_16x16x32_bf16 v[18:21], v[186:189], v[242:245], 0
	v_mfma_f32_16x16x32_bf16 v[18:21], v[182:185], v[238:241], v[18:21]
	v_mfma_f32_16x16x32_bf16 v[2:5], v[182:185], v[246:249], 0
	v_mfma_f32_16x16x32_bf16 v[2:5], v[186:189], v[250:253], v[2:5]
	v_mfma_f32_16x16x32_bf16 v[6:9], v[178:181], v[250:253], 0
	v_mfma_f32_16x16x32_bf16 v[6:9], v[174:177], v[246:249], v[6:9]
	v_mfma_f32_16x16x32_bf16 v[10:13], v[164:167], v[246:249], 0
	v_mfma_f32_16x16x32_bf16 v[10:13], v[168:171], v[250:253], v[10:13]
	v_mfma_f32_16x16x32_bf16 v[14:17], v[160:163], v[250:253], 0
	v_mfma_f32_16x16x32_bf16 v[14:17], v[156:159], v[246:249], v[14:17]
	s_waitcnt vmcnt(0)
	s_barrier
; #define PG8_STAGE(bufoff, gbase, voff) do { _Pragma("unroll") for (int _i = 0; _i < 2; ++_i) \
;         __builtin_amdgcn_global_load_lds((const unsigned*)((const char*)(gbase) + (voff)[_i]), (PG8_LAS unsigned*)(lds + (bufoff) + ldsw + _i * 8192), 16, 0, 0); } while (0)
; #define PG8_LDA(dst, b, h) do { _Pragma("unroll") for (int m = 0; m < 4; ++m) _Pragma("unroll") for (int k = 0; k < 2; ++k) dst[m][k] = *(const PG8_LAS bf16x8*)(lds + PG8_SA(b, h) + aoff + m * 2048 + k * 1024); } while (0)
; #define PG8_LDB(dst, b, h) do { _Pragma("unroll") for (int n = 0; n < 2; ++n) _Pragma("unroll") for (int k = 0; k < 2; ++k) dst[n][k] = *(const PG8_LAS bf16x8*)(lds + PG8_SB(b, h) + boff + n * 2048 + k * 1024); } while (0)
; #define PG8_MMA(ai, bj, At, Bt) do { __builtin_amdgcn_s_setprio(1); _Pragma("unroll") for (int m = 0; m < 4; ++m) _Pragma("unroll") for (int n = 0; n < 2; ++n) _Pragma("unroll") for (int k = 0; k < 2; ++k) \
;         acc[ai][bj][m][n] = __builtin_amdgcn_mfma_f32_16x16x32_bf16(Bt[n][k], At[m][k], acc[ai][bj][m][n], 0, 0, 0); __builtin_amdgcn_s_setprio(0); } while (0)
; #define PG8_WAIT_V(n) asm volatile("s_waitcnt vmcnt(" #n ")" ::: "memory")
; template <class Epi, class Sched, bool ALIGN_EPI>
; __device__ __forceinline__ void gemm_phase(PG8_LAS unsigned char* lds, const Gemm g, const Sched& S, const Epi& E) {
;     ...
;             PG8_LDB(B0, 0, 0); PG8_LDB(B1, 0, 1); PG8_SCHED; PG8_LDA(At, 0, 0); PG8_STAGE(PG8_SA(1, 1), a1 + hstepA, voffA);
;             PG8_WAIT_V(8); PG8_WAIT_L(0); PG8_BAR; PG8_MMA(0, 0, At, B0); PG8_MMA(0, 1, At, B1); PG8_BAR; PG8_SCHED;
;             PG8_LDA(At, 0, 1); PG8_STAGE(PG8_SB(0, 0), b2, voffB); PG8_STAGE(PG8_SB(0, 1), b2 + hstepB, voffB); PG8_STAGE(PG8_SA(0, 0), a2, voffA);
;             PG8_WAIT_V(8); PG8_WAIT_L(0); PG8_BAR; PG8_MMA(1, 0, At, B0); PG8_MMA(1, 1, At, B1); PG8_BAR; PG8_SCHED;
;             PG8_LDB(B0, 1, 0); PG8_LDB(B1, 1, 1); PG8_SCHED; PG8_LDA(At, 1, 0); PG8_STAGE(PG8_SA(0, 1), a2 + hstepA, voffA);
;             PG8_WAIT_V(8); PG8_WAIT_L(0); PG8_BAR; PG8_MMA(0, 0, At, B0); PG8_MMA(0, 1, At, B1); PG8_BAR; PG8_SCHED;
;             PG8_LDA(At, 1, 1); PG8_STAGE(PG8_SB(1, 0), b3, voffB); PG8_STAGE(PG8_SB(1, 1), b3 + hstepB, voffB); PG8_STAGE(PG8_SA(1, 0), a3, voffA);
;             PG8_WAIT_V(8); PG8_WAIT_L(0); PG8_BAR; PG8_MMA(1, 0, At, B0); PG8_MMA(1, 1, At, B1); PG8_BAR; PG8_SCHED;
	ds_read_b128 v[190:193], v155 offset:32768
	ds_read_b128 v[194:197], v155 offset:33792
	s_cmp_eq_u32 s49, 15
	s_cselect_b32 s28, s50, s28
	s_cselect_b32 s29, s51, s29
	s_add_i32 m0, s2, 0x10000
	ds_read_b128 v[198:201], v155 offset:34816
	global_load_lds_dwordx4 v134, s[28:29]
	ds_read_b128 v[202:205], v155 offset:35840
	ds_read_b128 v[206:209], v155 offset:36864
	s_add_i32 m0, s2, 0x12000
	ds_read_b128 v[210:213], v155 offset:37888
	global_load_lds_dwordx4 v130, s[28:29]
	ds_read_b128 v[214:217], v155 offset:38912
	ds_read_b128 v[218:221], v155 offset:39936
	s_add_u32 s30, s28, 0x20000
	s_addc_u32 s31, s29, 0
	s_add_i32 m0, s2, 0x11000
	ds_read_b128 v[156:159], v153 offset:32768
	global_load_lds_dwordx4 v134, s[30:31]
	ds_read_b128 v[160:163], v153 offset:33792
	ds_read_b128 v[164:167], v153 offset:34816
	s_add_i32 m0, s2, 0x13000
	ds_read_b128 v[168:171], v153 offset:35840
	global_load_lds_dwordx4 v130, s[30:31]
	ds_read_b128 v[174:177], v153 offset:49152
	ds_read_b128 v[178:181], v153 offset:50176
	s_add_u32 s30, s28, 0x80000
	s_addc_u32 s31, s29, 0
	s_add_i32 m0, s2, 0x14000
	ds_read_b128 v[182:185], v153 offset:51200
	global_load_lds_dwordx4 v134, s[30:31]
	ds_read_b128 v[186:189], v153 offset:52224
	ds_read_b128 v[222:225], v155 offset:49152
	s_add_i32 m0, s2, 0x16000
	ds_read_b128 v[226:229], v155 offset:50176
	global_load_lds_dwordx4 v130, s[30:31]
	ds_read_b128 v[230:233], v155 offset:51200
	ds_read_b128 v[234:237], v155 offset:52224
	s_add_u32 s30, s28, 0xa0000
	s_addc_u32 s31, s29, 0
	s_add_i32 m0, s2, 0x15000
	ds_read_b128 v[238:241], v155 offset:53248
	global_load_lds_dwordx4 v134, s[30:31]
	ds_read_b128 v[242:245], v155 offset:54272
	ds_read_b128 v[246:249], v155 offset:55296
	s_add_i32 m0, s2, 0x17000
	ds_read_b128 v[250:253], v155 offset:56320
	global_load_lds_dwordx4 v130, s[30:31]
	s_add_u32 s28, s28, 0x80
	s_addc_u32 s29, s29, 0
	s_waitcnt vmcnt(8) lgkmcnt(0)
	s_barrier
	v_mfma_f32_16x16x32_bf16 v[126:129], v[156:159], v[190:193], v[126:129]
	v_mfma_f32_16x16x32_bf16 v[126:129], v[160:163], v[194:197], v[126:129]
	v_mfma_f32_16x16x32_bf16 v[122:125], v[168:171], v[194:197], v[122:125]
	v_mfma_f32_16x16x32_bf16 v[122:125], v[164:167], v[190:193], v[122:125]
	v_mfma_f32_16x16x32_bf16 v[118:121], v[174:177], v[190:193], v[118:121]
	v_mfma_f32_16x16x32_bf16 v[118:121], v[178:181], v[194:197], v[118:121]
	v_mfma_f32_16x16x32_bf16 v[114:117], v[186:189], v[194:197], v[114:117]
	v_mfma_f32_16x16x32_bf16 v[114:117], v[182:185], v[190:193], v[114:117]
	v_mfma_f32_16x16x32_bf16 v[98:101], v[182:185], v[198:201], v[98:101]
	v_mfma_f32_16x16x32_bf16 v[98:101], v[186:189], v[202:205], v[98:101]
	v_mfma_f32_16x16x32_bf16 v[102:105], v[178:181], v[202:205], v[102:105]
	v_mfma_f32_16x16x32_bf16 v[102:105], v[174:177], v[198:201], v[102:105]
	v_mfma_f32_16x16x32_bf16 v[106:109], v[164:167], v[198:201], v[106:109]
	v_mfma_f32_16x16x32_bf16 v[106:109], v[168:171], v[202:205], v[106:109]
	v_mfma_f32_16x16x32_bf16 v[110:113], v[160:163], v[202:205], v[110:113]
	v_mfma_f32_16x16x32_bf16 v[110:113], v[156:159], v[198:201], v[110:113]
	v_mfma_f32_16x16x32_bf16 v[94:97], v[156:159], v[206:209], v[94:97]
	v_mfma_f32_16x16x32_bf16 v[94:97], v[160:163], v[210:213], v[94:97]
	v_mfma_f32_16x16x32_bf16 v[90:93], v[168:171], v[210:213], v[90:93]
	v_mfma_f32_16x16x32_bf16 v[90:93], v[164:167], v[206:209], v[90:93]
	v_mfma_f32_16x16x32_bf16 v[86:89], v[174:177], v[206:209], v[86:89]
	v_mfma_f32_16x16x32_bf16 v[86:89], v[178:181], v[210:213], v[86:89]
	v_mfma_f32_16x16x32_bf16 v[82:85], v[186:189], v[210:213], v[82:85]
	v_mfma_f32_16x16x32_bf16 v[82:85], v[182:185], v[206:209], v[82:85]
	v_mfma_f32_16x16x32_bf16 v[66:69], v[182:185], v[214:217], v[66:69]
	v_mfma_f32_16x16x32_bf16 v[66:69], v[186:189], v[218:221], v[66:69]
	v_mfma_f32_16x16x32_bf16 v[70:73], v[178:181], v[218:221], v[70:73]
	v_mfma_f32_16x16x32_bf16 v[70:73], v[174:177], v[214:217], v[70:73]
	v_mfma_f32_16x16x32_bf16 v[74:77], v[164:167], v[214:217], v[74:77]
	v_mfma_f32_16x16x32_bf16 v[74:77], v[168:171], v[218:221], v[74:77]
	v_mfma_f32_16x16x32_bf16 v[78:81], v[160:163], v[218:221], v[78:81]
	v_mfma_f32_16x16x32_bf16 v[78:81], v[156:159], v[214:217], v[78:81]
	v_mfma_f32_16x16x32_bf16 v[62:65], v[156:159], v[222:225], v[62:65]
	v_mfma_f32_16x16x32_bf16 v[62:65], v[160:163], v[226:229], v[62:65]
	v_mfma_f32_16x16x32_bf16 v[58:61], v[168:171], v[226:229], v[58:61]
	v_mfma_f32_16x16x32_bf16 v[58:61], v[164:167], v[222:225], v[58:61]
	v_mfma_f32_16x16x32_bf16 v[54:57], v[174:177], v[222:225], v[54:57]
	v_mfma_f32_16x16x32_bf16 v[54:57], v[178:181], v[226:229], v[54:57]
	v_mfma_f32_16x16x32_bf16 v[50:53], v[186:189], v[226:229], v[50:53]
	v_mfma_f32_16x16x32_bf16 v[50:53], v[182:185], v[222:225], v[50:53]
	v_mfma_f32_16x16x32_bf16 v[34:37], v[182:185], v[230:233], v[34:37]
	v_mfma_f32_16x16x32_bf16 v[34:37], v[186:189], v[234:237], v[34:37]
	v_mfma_f32_16x16x32_bf16 v[38:41], v[178:181], v[234:237], v[38:41]
	v_mfma_f32_16x16x32_bf16 v[38:41], v[174:177], v[230:233], v[38:41]
	v_mfma_f32_16x16x32_bf16 v[42:45], v[164:167], v[230:233], v[42:45]
	v_mfma_f32_16x16x32_bf16 v[42:45], v[168:171], v[234:237], v[42:45]
	v_mfma_f32_16x16x32_bf16 v[46:49], v[160:163], v[234:237], v[46:49]
	v_mfma_f32_16x16x32_bf16 v[46:49], v[156:159], v[230:233], v[46:49]
	v_mfma_f32_16x16x32_bf16 v[30:33], v[156:159], v[238:241], v[30:33]
	v_mfma_f32_16x16x32_bf16 v[30:33], v[160:163], v[242:245], v[30:33]
	v_mfma_f32_16x16x32_bf16 v[26:29], v[168:171], v[242:245], v[26:29]
	v_mfma_f32_16x16x32_bf16 v[26:29], v[164:167], v[238:241], v[26:29]
	v_mfma_f32_16x16x32_bf16 v[22:25], v[174:177], v[238:241], v[22:25]
	v_mfma_f32_16x16x32_bf16 v[22:25], v[178:181], v[242:245], v[22:25]
	v_mfma_f32_16x16x32_bf16 v[18:21], v[186:189], v[242:245], v[18:21]
	v_mfma_f32_16x16x32_bf16 v[18:21], v[182:185], v[238:241], v[18:21]
	v_mfma_f32_16x16x32_bf16 v[2:5], v[182:185], v[246:249], v[2:5]
	v_mfma_f32_16x16x32_bf16 v[2:5], v[186:189], v[250:253], v[2:5]
	v_mfma_f32_16x16x32_bf16 v[6:9], v[178:181], v[250:253], v[6:9]
	v_mfma_f32_16x16x32_bf16 v[6:9], v[174:177], v[246:249], v[6:9]
	v_mfma_f32_16x16x32_bf16 v[10:13], v[164:167], v[246:249], v[10:13]
	v_mfma_f32_16x16x32_bf16 v[10:13], v[168:171], v[250:253], v[10:13]
	v_mfma_f32_16x16x32_bf16 v[14:17], v[160:163], v[250:253], v[14:17]
	v_mfma_f32_16x16x32_bf16 v[14:17], v[156:159], v[246:249], v[14:17]
	s_waitcnt vmcnt(0)
	s_barrier
	s_add_i32 s49, s49, 1
; #define PG8_STAGE(bufoff, gbase, voff) do { _Pragma("unroll") for (int _i = 0; _i < 2; ++_i) \
;         __builtin_amdgcn_global_load_lds((const unsigned*)((const char*)(gbase) + (voff)[_i]), (PG8_LAS unsigned*)(lds + (bufoff) + ldsw + _i * 8192), 16, 0, 0); } while (0)
; #define PG8_LDA(dst, b, h) do { _Pragma("unroll") for (int m = 0; m < 4; ++m) _Pragma("unroll") for (int k = 0; k < 2; ++k) dst[m][k] = *(const PG8_LAS bf16x8*)(lds + PG8_SA(b, h) + aoff + m * 2048 + k * 1024); } while (0)
; #define PG8_LDB(dst, b, h) do { _Pragma("unroll") for (int n = 0; n < 2; ++n) _Pragma("unroll") for (int k = 0; k < 2; ++k) dst[n][k] = *(const PG8_LAS bf16x8*)(lds + PG8_SB(b, h) + boff + n * 2048 + k * 1024); } while (0)
; template <class Epi, class Sched, bool ALIGN_EPI>
; __device__ __forceinline__ void gemm_phase(PG8_LAS unsigned char* lds, const Gemm g, const Sched& S, const Epi& E) {
;     ...
;         for (int t = 0; t < nt; t += 2) {
;             if constexpr (Epi::MIDK) { if (t == (nt >> 1)) E.midk(acc, cur, wr, fr); }
;             const bool last = (t == nt - 2);
;             const char* a1 = cA + (size_t)(t + 1) * kstepA;
;             const char* a2 = last ? nA : cA + (size_t)(t + 2) * kstepA; const char* b2 = last ? nB : cB + (size_t)(t + 2) * kstep;
;             const char* a3 = a2 + kstepA; const char* b3 = b2 + kstep;
;             PG8_LDB(B0, 0, 0); PG8_LDB(B1, 0, 1); PG8_SCHED; PG8_LDA(At, 0, 0); PG8_STAGE(PG8_SA(1, 1), a1 + hstepA, voffA);
;             PG8_WAIT_V(8); PG8_WAIT_L(0); PG8_BAR; PG8_MMA(0, 0, At, B0); PG8_MMA(0, 1, At, B1); PG8_BAR; PG8_SCHED;
;             PG8_LDA(At, 0, 1); PG8_STAGE(PG8_SB(0, 0), b2, voffB); PG8_STAGE(PG8_SB(0, 1), b2 + hstepB, voffB); PG8_STAGE(PG8_SA(0, 0), a2, voffA);
;             PG8_WAIT_V(8); PG8_WAIT_L(0); PG8_BAR; PG8_MMA(1, 0, At, B0); PG8_MMA(1, 1, At, B1); PG8_BAR; PG8_SCHED;
;             PG8_LDB(B0, 1, 0); PG8_LDB(B1, 1, 1); PG8_SCHED; PG8_LDA(At, 1, 0); PG8_STAGE(PG8_SA(0, 1), a2 + hstepA, voffA);
;             PG8_WAIT_V(8); PG8_WAIT_L(0); PG8_BAR; PG8_MMA(0, 0, At, B0); PG8_MMA(0, 1, At, B1); PG8_BAR; PG8_SCHED;
;             PG8_LDA(At, 1, 1); PG8_STAGE(PG8_SB(1, 0), b3, voffB); PG8_STAGE(PG8_SB(1, 1), b3 + hstepB, voffB); PG8_STAGE(PG8_SA(1, 0), a3, voffA);
;             PG8_WAIT_V(8); PG8_WAIT_L(0); PG8_BAR; PG8_MMA(1, 0, At, B0); PG8_MMA(1, 1, At, B1); PG8_BAR; PG8_SCHED;
.Lp8k_A_loop:
	ds_read_b128 v[190:193], v155 offset:0
	ds_read_b128 v[194:197], v155 offset:1024
	s_add_i32 m0, s2, 0x18000
	ds_read_b128 v[198:201], v155 offset:2048
	global_load_lds_dwordx4 v134, s[28:29]
	ds_read_b128 v[202:205], v155 offset:3072
	ds_read_b128 v[206:209], v155 offset:4096
	s_add_i32 m0, s2, 0x1a000
	ds_read_b128 v[210:213], v155 offset:5120
	global_load_lds_dwordx4 v130, s[28:29]
	ds_read_b128 v[214:217], v155 offset:6144
	ds_read_b128 v[218:221], v155 offset:7168
	s_add_u32 s30, s28, 0x20000
	s_addc_u32 s31, s29, 0
	s_add_i32 m0, s2, 0x19000
	ds_read_b128 v[156:159], v153 offset:0
	global_load_lds_dwordx4 v134, s[30:31]
	ds_read_b128 v[160:163], v153 offset:1024
	ds_read_b128 v[164:167], v153 offset:2048
	s_add_i32 m0, s2, 0x1b000
	ds_read_b128 v[168:171], v153 offset:3072
	global_load_lds_dwordx4 v130, s[30:31]
	ds_read_b128 v[174:177], v153 offset:16384
	ds_read_b128 v[178:181], v153 offset:17408
	s_add_u32 s30, s28, 0x80000
	s_addc_u32 s31, s29, 0
	s_add_i32 m0, s2, 0x1c000
	ds_read_b128 v[182:185], v153 offset:18432
	global_load_lds_dwordx4 v134, s[30:31]
	ds_read_b128 v[186:189], v153 offset:19456
	ds_read_b128 v[222:225], v155 offset:16384
	s_add_i32 m0, s2, 0x1e000
	ds_read_b128 v[226:229], v155 offset:17408
	global_load_lds_dwordx4 v130, s[30:31]
	ds_read_b128 v[230:233], v155 offset:18432
	ds_read_b128 v[234:237], v155 offset:19456
	s_add_u32 s30, s28, 0xa0000
	s_addc_u32 s31, s29, 0
	s_add_i32 m0, s2, 0x1d000
	ds_read_b128 v[238:241], v155 offset:20480
	global_load_lds_dwordx4 v134, s[30:31]
	ds_read_b128 v[242:245], v155 offset:21504
	ds_read_b128 v[246:249], v155 offset:22528
	s_add_i32 m0, s2, 0x1f000
	ds_read_b128 v[250:253], v155 offset:23552
	global_load_lds_dwordx4 v130, s[30:31]
	s_add_u32 s28, s28, 0x80
	s_addc_u32 s29, s29, 0
	s_waitcnt vmcnt(8) lgkmcnt(0)
	s_barrier
	v_mfma_f32_16x16x32_bf16 v[126:129], v[156:159], v[190:193], v[126:129]
	v_mfma_f32_16x16x32_bf16 v[126:129], v[160:163], v[194:197], v[126:129]
	v_mfma_f32_16x16x32_bf16 v[122:125], v[168:171], v[194:197], v[122:125]
	v_mfma_f32_16x16x32_bf16 v[122:125], v[164:167], v[190:193], v[122:125]
	v_mfma_f32_16x16x32_bf16 v[118:121], v[174:177], v[190:193], v[118:121]
	v_mfma_f32_16x16x32_bf16 v[118:121], v[178:181], v[194:197], v[118:121]
	v_mfma_f32_16x16x32_bf16 v[114:117], v[186:189], v[194:197], v[114:117]
	v_mfma_f32_16x16x32_bf16 v[114:117], v[182:185], v[190:193], v[114:117]
	v_mfma_f32_16x16x32_bf16 v[98:101], v[182:185], v[198:201], v[98:101]
	v_mfma_f32_16x16x32_bf16 v[98:101], v[186:189], v[202:205], v[98:101]
	v_mfma_f32_16x16x32_bf16 v[102:105], v[178:181], v[202:205], v[102:105]
	v_mfma_f32_16x16x32_bf16 v[102:105], v[174:177], v[198:201], v[102:105]
	v_mfma_f32_16x16x32_bf16 v[106:109], v[164:167], v[198:201], v[106:109]
	v_mfma_f32_16x16x32_bf16 v[106:109], v[168:171], v[202:205], v[106:109]
	v_mfma_f32_16x16x32_bf16 v[110:113], v[160:163], v[202:205], v[110:113]
	v_mfma_f32_16x16x32_bf16 v[110:113], v[156:159], v[198:201], v[110:113]
	v_mfma_f32_16x16x32_bf16 v[94:97], v[156:159], v[206:209], v[94:97]
	v_mfma_f32_16x16x32_bf16 v[94:97], v[160:163], v[210:213], v[94:97]
	v_mfma_f32_16x16x32_bf16 v[90:93], v[168:171], v[210:213], v[90:93]
	v_mfma_f32_16x16x32_bf16 v[90:93], v[164:167], v[206:209], v[90:93]
	v_mfma_f32_16x16x32_bf16 v[86:89], v[174:177], v[206:209], v[86:89]
	v_mfma_f32_16x16x32_bf16 v[86:89], v[178:181], v[210:213], v[86:89]
	v_mfma_f32_16x16x32_bf16 v[82:85], v[186:189], v[210:213], v[82:85]
	v_mfma_f32_16x16x32_bf16 v[82:85], v[182:185], v[206:209], v[82:85]
	v_mfma_f32_16x16x32_bf16 v[66:69], v[182:185], v[214:217], v[66:69]
	v_mfma_f32_16x16x32_bf16 v[66:69], v[186:189], v[218:221], v[66:69]
	v_mfma_f32_16x16x32_bf16 v[70:73], v[178:181], v[218:221], v[70:73]
	v_mfma_f32_16x16x32_bf16 v[70:73], v[174:177], v[214:217], v[70:73]
	v_mfma_f32_16x16x32_bf16 v[74:77], v[164:167], v[214:217], v[74:77]
	v_mfma_f32_16x16x32_bf16 v[74:77], v[168:171], v[218:221], v[74:77]
	v_mfma_f32_16x16x32_bf16 v[78:81], v[160:163], v[218:221], v[78:81]
	v_mfma_f32_16x16x32_bf16 v[78:81], v[156:159], v[214:217], v[78:81]
	v_mfma_f32_16x16x32_bf16 v[62:65], v[156:159], v[222:225], v[62:65]
	v_mfma_f32_16x16x32_bf16 v[62:65], v[160:163], v[226:229], v[62:65]
	v_mfma_f32_16x16x32_bf16 v[58:61], v[168:171], v[226:229], v[58:61]
	v_mfma_f32_16x16x32_bf16 v[58:61], v[164:167], v[222:225], v[58:61]
	v_mfma_f32_16x16x32_bf16 v[54:57], v[174:177], v[222:225], v[54:57]
	v_mfma_f32_16x16x32_bf16 v[54:57], v[178:181], v[226:229], v[54:57]
	v_mfma_f32_16x16x32_bf16 v[50:53], v[186:189], v[226:229], v[50:53]
	v_mfma_f32_16x16x32_bf16 v[50:53], v[182:185], v[222:225], v[50:53]
	v_mfma_f32_16x16x32_bf16 v[34:37], v[182:185], v[230:233], v[34:37]
	v_mfma_f32_16x16x32_bf16 v[34:37], v[186:189], v[234:237], v[34:37]
	v_mfma_f32_16x16x32_bf16 v[38:41], v[178:181], v[234:237], v[38:41]
	v_mfma_f32_16x16x32_bf16 v[38:41], v[174:177], v[230:233], v[38:41]
	v_mfma_f32_16x16x32_bf16 v[42:45], v[164:167], v[230:233], v[42:45]
	v_mfma_f32_16x16x32_bf16 v[42:45], v[168:171], v[234:237], v[42:45]
	v_mfma_f32_16x16x32_bf16 v[46:49], v[160:163], v[234:237], v[46:49]
	v_mfma_f32_16x16x32_bf16 v[46:49], v[156:159], v[230:233], v[46:49]
	v_mfma_f32_16x16x32_bf16 v[30:33], v[156:159], v[238:241], v[30:33]
	v_mfma_f32_16x16x32_bf16 v[30:33], v[160:163], v[242:245], v[30:33]
	v_mfma_f32_16x16x32_bf16 v[26:29], v[168:171], v[242:245], v[26:29]
	v_mfma_f32_16x16x32_bf16 v[26:29], v[164:167], v[238:241], v[26:29]
	v_mfma_f32_16x16x32_bf16 v[22:25], v[174:177], v[238:241], v[22:25]
	v_mfma_f32_16x16x32_bf16 v[22:25], v[178:181], v[242:245], v[22:25]
	v_mfma_f32_16x16x32_bf16 v[18:21], v[186:189], v[242:245], v[18:21]
	v_mfma_f32_16x16x32_bf16 v[18:21], v[182:185], v[238:241], v[18:21]
	v_mfma_f32_16x16x32_bf16 v[2:5], v[182:185], v[246:249], v[2:5]
	v_mfma_f32_16x16x32_bf16 v[2:5], v[186:189], v[250:253], v[2:5]
	v_mfma_f32_16x16x32_bf16 v[6:9], v[178:181], v[250:253], v[6:9]
	v_mfma_f32_16x16x32_bf16 v[6:9], v[174:177], v[246:249], v[6:9]
	v_mfma_f32_16x16x32_bf16 v[10:13], v[164:167], v[246:249], v[10:13]
	v_mfma_f32_16x16x32_bf16 v[10:13], v[168:171], v[250:253], v[10:13]
	v_mfma_f32_16x16x32_bf16 v[14:17], v[160:163], v[250:253], v[14:17]
	v_mfma_f32_16x16x32_bf16 v[14:17], v[156:159], v[246:249], v[14:17]
	s_waitcnt vmcnt(0)
	s_barrier
; #define PG8_STAGE(bufoff, gbase, voff) do { _Pragma("unroll") for (int _i = 0; _i < 2; ++_i) \
;         __builtin_amdgcn_global_load_lds((const unsigned*)((const char*)(gbase) + (voff)[_i]), (PG8_LAS unsigned*)(lds + (bufoff) + ldsw + _i * 8192), 16, 0, 0); } while (0)
; #define PG8_LDA(dst, b, h) do { _Pragma("unroll") for (int m = 0; m < 4; ++m) _Pragma("unroll") for (int k = 0; k < 2; ++k) dst[m][k] = *(const PG8_LAS bf16x8*)(lds + PG8_SA(b, h) + aoff + m * 2048 + k * 1024); } while (0)
; #define PG8_LDB(dst, b, h) do { _Pragma("unroll") for (int n = 0; n < 2; ++n) _Pragma("unroll") for (int k = 0; k < 2; ++k) dst[n][k] = *(const PG8_LAS bf16x8*)(lds + PG8_SB(b, h) + boff + n * 2048 + k * 1024); } while (0)
; #define PG8_MMA(ai, bj, At, Bt) do { __builtin_amdgcn_s_setprio(1); _Pragma("unroll") for (int m = 0; m < 4; ++m) _Pragma("unroll") for (int n = 0; n < 2; ++n) _Pragma("unroll") for (int k = 0; k < 2; ++k) \
;         acc[ai][bj][m][n] = __builtin_amdgcn_mfma_f32_16x16x32_bf16(Bt[n][k], At[m][k], acc[ai][bj][m][n], 0, 0, 0); __builtin_amdgcn_s_setprio(0); } while (0)
; #define PG8_WAIT_V(n) asm volatile("s_waitcnt vmcnt(" #n ")" ::: "memory")
; template <class Epi, class Sched, bool ALIGN_EPI>
; __device__ __forceinline__ void gemm_phase(PG8_LAS unsigned char* lds, const Gemm g, const Sched& S, const Epi& E) {
;     ...
;             PG8_LDB(B0, 0, 0); PG8_LDB(B1, 0, 1); PG8_SCHED; PG8_LDA(At, 0, 0); PG8_STAGE(PG8_SA(1, 1), a1 + hstepA, voffA);
;             PG8_WAIT_V(8); PG8_WAIT_L(0); PG8_BAR; PG8_MMA(0, 0, At, B0); PG8_MMA(0, 1, At, B1); PG8_BAR; PG8_SCHED;
;             PG8_LDA(At, 0, 1); PG8_STAGE(PG8_SB(0, 0), b2, voffB); PG8_STAGE(PG8_SB(0, 1), b2 + hstepB, voffB); PG8_STAGE(PG8_SA(0, 0), a2, voffA);
;             PG8_WAIT_V(8); PG8_WAIT_L(0); PG8_BAR; PG8_MMA(1, 0, At, B0); PG8_MMA(1, 1, At, B1); PG8_BAR; PG8_SCHED;
;             PG8_LDB(B0, 1, 0); PG8_LDB(B1, 1, 1); PG8_SCHED; PG8_LDA(At, 1, 0); PG8_STAGE(PG8_SA(0, 1), a2 + hstepA, voffA);
;             PG8_WAIT_V(8); PG8_WAIT_L(0); PG8_BAR; PG8_MMA(0, 0, At, B0); PG8_MMA(0, 1, At, B1); PG8_BAR; PG8_SCHED;
;             PG8_LDA(At, 1, 1); PG8_STAGE(PG8_SB(1, 0), b3, voffB); PG8_STAGE(PG8_SB(1, 1), b3 + hstepB, voffB); PG8_STAGE(PG8_SA(1, 0), a3, voffA);
;             PG8_WAIT_V(8); PG8_WAIT_L(0); PG8_BAR; PG8_MMA(1, 0, At, B0); PG8_MMA(1, 1, At, B1); PG8_BAR; PG8_SCHED;
	ds_read_b128 v[190:193], v155 offset:32768
	ds_read_b128 v[194:197], v155 offset:33792
	s_cmp_eq_u32 s49, 15
	s_cselect_b32 s28, s50, s28
	s_cselect_b32 s29, s51, s29
	s_add_i32 m0, s2, 0x10000
	ds_read_b128 v[198:201], v155 offset:34816
	global_load_lds_dwordx4 v134, s[28:29]
	ds_read_b128 v[202:205], v155 offset:35840
	ds_read_b128 v[206:209], v155 offset:36864
	s_add_i32 m0, s2, 0x12000
	ds_read_b128 v[210:213], v155 offset:37888
	global_load_lds_dwordx4 v130, s[28:29]
	ds_read_b128 v[214:217], v155 offset:38912
	ds_read_b128 v[218:221], v155 offset:39936
	s_add_u32 s30, s28, 0x20000
	s_addc_u32 s31, s29, 0
	s_add_i32 m0, s2, 0x11000
	ds_read_b128 v[156:159], v153 offset:32768
	global_load_lds_dwordx4 v134, s[30:31]
	ds_read_b128 v[160:163], v153 offset:33792
	ds_read_b128 v[164:167], v153 offset:34816
	s_add_i32 m0, s2, 0x13000
	ds_read_b128 v[168:171], v153 offset:35840
	global_load_lds_dwordx4 v130, s[30:31]
	ds_read_b128 v[174:177], v153 offset:49152
	ds_read_b128 v[178:181], v153 offset:50176
	s_add_u32 s30, s28, 0x80000
	s_addc_u32 s31, s29, 0
	s_add_i32 m0, s2, 0x14000
	ds_read_b128 v[182:185], v153 offset:51200
	global_load_lds_dwordx4 v134, s[30:31]
	ds_read_b128 v[186:189], v153 offset:52224
	ds_read_b128 v[222:225], v155 offset:49152
	s_add_i32 m0, s2, 0x16000
	ds_read_b128 v[226:229], v155 offset:50176
	global_load_lds_dwordx4 v130, s[30:31]
	ds_read_b128 v[230:233], v155 offset:51200
	ds_read_b128 v[234:237], v155 offset:52224
	s_add_u32 s30, s28, 0xa0000
	s_addc_u32 s31, s29, 0
	s_add_i32 m0, s2, 0x15000
	ds_read_b128 v[238:241], v155 offset:53248
	global_load_lds_dwordx4 v134, s[30:31]
	ds_read_b128 v[242:245], v155 offset:54272
	ds_read_b128 v[246:249], v155 offset:55296
	s_add_i32 m0, s2, 0x17000
	ds_read_b128 v[250:253], v155 offset:56320
	global_load_lds_dwordx4 v130, s[30:31]
	s_add_u32 s28, s28, 0x80
	s_addc_u32 s29, s29, 0
	s_waitcnt vmcnt(8) lgkmcnt(0)
	s_barrier
; #define PG8_STAGE(bufoff, gbase, voff) do { _Pragma("unroll") for (int _i = 0; _i < 2; ++_i) \
;         __builtin_amdgcn_global_load_lds((const unsigned*)((const char*)(gbase) + (voff)[_i]), (PG8_LAS unsigned*)(lds + (bufoff) + ldsw + _i * 8192), 16, 0, 0); } while (0)
; #define PG8_LDA(dst, b, h) do { _Pragma("unroll") for (int m = 0; m < 4; ++m) _Pragma("unroll") for (int k = 0; k < 2; ++k) dst[m][k] = *(const PG8_LAS bf16x8*)(lds + PG8_SA(b, h) + aoff + m * 2048 + k * 1024); } while (0)
; #define PG8_LDB(dst, b, h) do { _Pragma("unroll") for (int n = 0; n < 2; ++n) _Pragma("unroll") for (int k = 0; k < 2; ++k) dst[n][k] = *(const PG8_LAS bf16x8*)(lds + PG8_SB(b, h) + boff + n * 2048 + k * 1024); } while (0)
; #define PG8_MMA(ai, bj, At, Bt) do { __builtin_amdgcn_s_setprio(1); _Pragma("unroll") for (int m = 0; m < 4; ++m) _Pragma("unroll") for (int n = 0; n < 2; ++n) _Pragma("unroll") for (int k = 0; k < 2; ++k) \
;         acc[ai][bj][m][n] = __builtin_amdgcn_mfma_f32_16x16x32_bf16(Bt[n][k], At[m][k], acc[ai][bj][m][n], 0, 0, 0); __builtin_amdgcn_s_setprio(0); } while (0)
; #define PG8_WAIT_V(n) asm volatile("s_waitcnt vmcnt(" #n ")" ::: "memory")
; template <class Epi, class Sched, bool ALIGN_EPI>
; __device__ __forceinline__ void gemm_phase(PG8_LAS unsigned char* lds, const Gemm g, const Sched& S, const Epi& E) {
;     ...
;             PG8_LDB(B0, 0, 0); PG8_LDB(B1, 0, 1); PG8_SCHED; PG8_LDA(At, 0, 0); PG8_STAGE(PG8_SA(1, 1), a1 + hstepA, voffA);
;             PG8_WAIT_V(8); PG8_WAIT_L(0); PG8_BAR; PG8_MMA(0, 0, At, B0); PG8_MMA(0, 1, At, B1); PG8_BAR; PG8_SCHED;
;             PG8_LDA(At, 0, 1); PG8_STAGE(PG8_SB(0, 0), b2, voffB); PG8_STAGE(PG8_SB(0, 1), b2 + hstepB, voffB); PG8_STAGE(PG8_SA(0, 0), a2, voffA);
;             PG8_WAIT_V(8); PG8_WAIT_L(0); PG8_BAR; PG8_MMA(1, 0, At, B0); PG8_MMA(1, 1, At, B1); PG8_BAR; PG8_SCHED;
;             PG8_LDB(B0, 1, 0); PG8_LDB(B1, 1, 1); PG8_SCHED; PG8_LDA(At, 1, 0); PG8_STAGE(PG8_SA(0, 1), a2 + hstepA, voffA);
;             PG8_WAIT_V(8); PG8_WAIT_L(0); PG8_BAR; PG8_MMA(0, 0, At, B0); PG8_MMA(0, 1, At, B1); PG8_BAR; PG8_SCHED;
;             PG8_LDA(At, 1, 1); PG8_STAGE(PG8_SB(1, 0), b3, voffB); PG8_STAGE(PG8_SB(1, 1), b3 + hstepB, voffB); PG8_STAGE(PG8_SA(1, 0), a3, voffA);
;             PG8_WAIT_V(8); PG8_WAIT_L(0); PG8_BAR; PG8_MMA(1, 0, At, B0); PG8_MMA(1, 1, At, B1); PG8_BAR; PG8_SCHED;
;         }
	v_mfma_f32_16x16x32_bf16 v[126:129], v[156:159], v[190:193], v[126:129]
	v_mfma_f32_16x16x32_bf16 v[126:129], v[160:163], v[194:197], v[126:129]
	v_mfma_f32_16x16x32_bf16 v[122:125], v[168:171], v[194:197], v[122:125]
	v_mfma_f32_16x16x32_bf16 v[122:125], v[164:167], v[190:193], v[122:125]
	v_mfma_f32_16x16x32_bf16 v[118:121], v[174:177], v[190:193], v[118:121]
	v_mfma_f32_16x16x32_bf16 v[118:121], v[178:181], v[194:197], v[118:121]
	v_mfma_f32_16x16x32_bf16 v[114:117], v[186:189], v[194:197], v[114:117]
	v_mfma_f32_16x16x32_bf16 v[114:117], v[182:185], v[190:193], v[114:117]
	v_mfma_f32_16x16x32_bf16 v[98:101], v[182:185], v[198:201], v[98:101]
	v_mfma_f32_16x16x32_bf16 v[98:101], v[186:189], v[202:205], v[98:101]
	v_mfma_f32_16x16x32_bf16 v[102:105], v[178:181], v[202:205], v[102:105]
	v_mfma_f32_16x16x32_bf16 v[102:105], v[174:177], v[198:201], v[102:105]
	v_mfma_f32_16x16x32_bf16 v[106:109], v[164:167], v[198:201], v[106:109]
	v_mfma_f32_16x16x32_bf16 v[106:109], v[168:171], v[202:205], v[106:109]
	v_mfma_f32_16x16x32_bf16 v[110:113], v[160:163], v[202:205], v[110:113]
	v_mfma_f32_16x16x32_bf16 v[110:113], v[156:159], v[198:201], v[110:113]
	v_mfma_f32_16x16x32_bf16 v[94:97], v[156:159], v[206:209], v[94:97]
	v_mfma_f32_16x16x32_bf16 v[94:97], v[160:163], v[210:213], v[94:97]
	v_mfma_f32_16x16x32_bf16 v[90:93], v[168:171], v[210:213], v[90:93]
	v_mfma_f32_16x16x32_bf16 v[90:93], v[164:167], v[206:209], v[90:93]
	v_mfma_f32_16x16x32_bf16 v[86:89], v[174:177], v[206:209], v[86:89]
	v_mfma_f32_16x16x32_bf16 v[86:89], v[178:181], v[210:213], v[86:89]
	v_mfma_f32_16x16x32_bf16 v[82:85], v[186:189], v[210:213], v[82:85]
	v_mfma_f32_16x16x32_bf16 v[82:85], v[182:185], v[206:209], v[82:85]
	v_mfma_f32_16x16x32_bf16 v[66:69], v[182:185], v[214:217], v[66:69]
	v_mfma_f32_16x16x32_bf16 v[66:69], v[186:189], v[218:221], v[66:69]
	v_mfma_f32_16x16x32_bf16 v[70:73], v[178:181], v[218:221], v[70:73]
	v_mfma_f32_16x16x32_bf16 v[70:73], v[174:177], v[214:217], v[70:73]
	v_mfma_f32_16x16x32_bf16 v[74:77], v[164:167], v[214:217], v[74:77]
	v_mfma_f32_16x16x32_bf16 v[74:77], v[168:171], v[218:221], v[74:77]
	v_mfma_f32_16x16x32_bf16 v[78:81], v[160:163], v[218:221], v[78:81]
	v_mfma_f32_16x16x32_bf16 v[78:81], v[156:159], v[214:217], v[78:81]
	v_mfma_f32_16x16x32_bf16 v[62:65], v[156:159], v[222:225], v[62:65]
	v_mfma_f32_16x16x32_bf16 v[62:65], v[160:163], v[226:229], v[62:65]
	v_mfma_f32_16x16x32_bf16 v[58:61], v[168:171], v[226:229], v[58:61]
	v_mfma_f32_16x16x32_bf16 v[58:61], v[164:167], v[222:225], v[58:61]
	v_mfma_f32_16x16x32_bf16 v[54:57], v[174:177], v[222:225], v[54:57]
	v_mfma_f32_16x16x32_bf16 v[54:57], v[178:181], v[226:229], v[54:57]
	v_mfma_f32_16x16x32_bf16 v[50:53], v[186:189], v[226:229], v[50:53]
	v_mfma_f32_16x16x32_bf16 v[50:53], v[182:185], v[222:225], v[50:53]
	v_mfma_f32_16x16x32_bf16 v[34:37], v[182:185], v[230:233], v[34:37]
	v_mfma_f32_16x16x32_bf16 v[34:37], v[186:189], v[234:237], v[34:37]
	v_mfma_f32_16x16x32_bf16 v[38:41], v[178:181], v[234:237], v[38:41]
	v_mfma_f32_16x16x32_bf16 v[38:41], v[174:177], v[230:233], v[38:41]
	v_mfma_f32_16x16x32_bf16 v[42:45], v[164:167], v[230:233], v[42:45]
	v_mfma_f32_16x16x32_bf16 v[42:45], v[168:171], v[234:237], v[42:45]
	v_mfma_f32_16x16x32_bf16 v[46:49], v[160:163], v[234:237], v[46:49]
	v_mfma_f32_16x16x32_bf16 v[46:49], v[156:159], v[230:233], v[46:49]
	v_mfma_f32_16x16x32_bf16 v[30:33], v[156:159], v[238:241], v[30:33]
	v_mfma_f32_16x16x32_bf16 v[30:33], v[160:163], v[242:245], v[30:33]
	v_mfma_f32_16x16x32_bf16 v[26:29], v[168:171], v[242:245], v[26:29]
	v_mfma_f32_16x16x32_bf16 v[26:29], v[164:167], v[238:241], v[26:29]
	v_mfma_f32_16x16x32_bf16 v[22:25], v[174:177], v[238:241], v[22:25]
	v_mfma_f32_16x16x32_bf16 v[22:25], v[178:181], v[242:245], v[22:25]
	v_mfma_f32_16x16x32_bf16 v[18:21], v[186:189], v[242:245], v[18:21]
	v_mfma_f32_16x16x32_bf16 v[18:21], v[182:185], v[238:241], v[18:21]
	v_mfma_f32_16x16x32_bf16 v[2:5], v[182:185], v[246:249], v[2:5]
	v_mfma_f32_16x16x32_bf16 v[2:5], v[186:189], v[250:253], v[2:5]
	v_mfma_f32_16x16x32_bf16 v[6:9], v[178:181], v[250:253], v[6:9]
	v_mfma_f32_16x16x32_bf16 v[6:9], v[174:177], v[246:249], v[6:9]
	v_mfma_f32_16x16x32_bf16 v[10:13], v[164:167], v[246:249], v[10:13]
	v_mfma_f32_16x16x32_bf16 v[10:13], v[168:171], v[250:253], v[10:13]
	v_mfma_f32_16x16x32_bf16 v[14:17], v[160:163], v[250:253], v[14:17]
	v_mfma_f32_16x16x32_bf16 v[14:17], v[156:159], v[246:249], v[14:17]
	s_waitcnt vmcnt(0)
	s_barrier
	s_add_i32 s49, s49, 1
	s_cmp_lt_u32 s49, 16
	s_cbranch_scc1 .Lp8k_A_loop
	ds_read_b128 v[190:193], v155 offset:0
	ds_read_b128 v[194:197], v155 offset:1024
	s_add_i32 m0, s2, 0x18000
	ds_read_b128 v[198:201], v155 offset:2048
	global_load_lds_dwordx4 v134, s[28:29]
	ds_read_b128 v[202:205], v155 offset:3072
	ds_read_b128 v[206:209], v155 offset:4096
	s_add_i32 m0, s2, 0x1a000
	ds_read_b128 v[210:213], v155 offset:5120
	global_load_lds_dwordx4 v130, s[28:29]
	ds_read_b128 v[214:217], v155 offset:6144
	ds_read_b128 v[218:221], v155 offset:7168
	s_add_u32 s30, s28, 0x20000
	s_addc_u32 s31, s29, 0
	s_add_i32 m0, s2, 0x19000
	ds_read_b128 v[164:167], v153 offset:2048
	global_load_lds_dwordx4 v134, s[30:31]
	ds_read_b128 v[168:171], v153 offset:3072
	ds_read_b128 v[174:177], v153 offset:16384
	s_add_i32 m0, s2, 0x1b000
	ds_read_b128 v[178:181], v153 offset:17408
	global_load_lds_dwordx4 v130, s[30:31]
	ds_read_b128 v[182:185], v153 offset:18432
	ds_read_b128 v[186:189], v153 offset:19456
	s_add_u32 s30, s28, 0x80000
	s_addc_u32 s31, s29, 0
	s_add_i32 m0, s2, 0x1c000
	ds_read_b128 v[222:225], v155 offset:16384
	global_load_lds_dwordx4 v134, s[30:31]
	ds_read_b128 v[226:229], v155 offset:17408
	ds_read_b128 v[230:233], v155 offset:18432
	s_add_i32 m0, s2, 0x1e000
	ds_read_b128 v[234:237], v155 offset:19456
	global_load_lds_dwordx4 v130, s[30:31]
	ds_read_b128 v[238:241], v155 offset:20480
	ds_read_b128 v[242:245], v155 offset:21504
	s_add_u32 s30, s28, 0xa0000
	s_addc_u32 s31, s29, 0
	s_add_i32 m0, s2, 0x1d000
	ds_read_b128 v[246:249], v155 offset:22528
	global_load_lds_dwordx4 v134, s[30:31]
	s_add_i32 m0, s2, 0x1f000
	ds_read_b128 v[250:253], v155 offset:23552
	global_load_lds_dwordx4 v130, s[30:31]
	s_add_u32 s28, s28, 0x80
	s_addc_u32 s29, s29, 0
	s_branch .Lp8k_done

; #define PG8_STAGE(bufoff, gbase, voff) do { _Pragma("unroll") for (int _i = 0; _i < 2; ++_i) \
;         __builtin_amdgcn_global_load_lds((const unsigned*)((const char*)(gbase) + (voff)[_i]), (PG8_LAS unsigned*)(lds + (bufoff) + ldsw + _i * 8192), 16, 0, 0); } while (0)
; #define PG8_LDA(dst, b, h) do { _Pragma("unroll") for (int m = 0; m < 4; ++m) _Pragma("unroll") for (int k = 0; k < 2; ++k) dst[m][k] = *(const PG8_LAS bf16x8*)(lds + PG8_SA(b, h) + aoff + m * 2048 + k * 1024); } while (0)
; #define PG8_LDB(dst, b, h) do { _Pragma("unroll") for (int n = 0; n < 2; ++n) _Pragma("unroll") for (int k = 0; k < 2; ++k) dst[n][k] = *(const PG8_LAS bf16x8*)(lds + PG8_SB(b, h) + boff + n * 2048 + k * 1024); } while (0)
; #define PG8_MMA(ai, bj, At, Bt) do { __builtin_amdgcn_s_setprio(1); _Pragma("unroll") for (int m = 0; m < 4; ++m) _Pragma("unroll") for (int n = 0; n < 2; ++n) _Pragma("unroll") for (int k = 0; k < 2; ++k) \
;         acc[ai][bj][m][n] = __builtin_amdgcn_mfma_f32_16x16x32_bf16(Bt[n][k], At[m][k], acc[ai][bj][m][n], 0, 0, 0); __builtin_amdgcn_s_setprio(0); } while (0)
; #define PG8_WAIT_V(n) asm volatile("s_waitcnt vmcnt(" #n ")" ::: "memory")
; template <class Epi, class Sched, bool ALIGN_EPI>
; __device__ __forceinline__ void gemm_phase(PG8_LAS unsigned char* lds, const Gemm g, const Sched& S, const Epi& E) {
;     ...
;             PG8_LDB(B0, 0, 0); PG8_LDB(B1, 0, 1); PG8_SCHED; PG8_LDA(At, 0, 0); PG8_STAGE(PG8_SA(1, 1), a1 + hstepA, voffA);
;             PG8_WAIT_V(8); PG8_WAIT_L(0); PG8_BAR; PG8_MMA(0, 0, At, B0); PG8_MMA(0, 1, At, B1); PG8_BAR; PG8_SCHED;
;             PG8_LDA(At, 0, 1); PG8_STAGE(PG8_SB(0, 0), b2, voffB); PG8_STAGE(PG8_SB(0, 1), b2 + hstepB, voffB); PG8_STAGE(PG8_SA(0, 0), a2, voffA);
;             PG8_WAIT_V(8); PG8_WAIT_L(0); PG8_BAR; PG8_MMA(1, 0, At, B0); PG8_MMA(1, 1, At, B1); PG8_BAR; PG8_SCHED;
;             PG8_LDB(B0, 1, 0); PG8_LDB(B1, 1, 1); PG8_SCHED; PG8_LDA(At, 1, 0); PG8_STAGE(PG8_SA(0, 1), a2 + hstepA, voffA);
;             PG8_WAIT_V(8); PG8_WAIT_L(0); PG8_BAR; PG8_MMA(0, 0, At, B0); PG8_MMA(0, 1, At, B1); PG8_BAR; PG8_SCHED;
;             PG8_LDA(At, 1, 1); PG8_STAGE(PG8_SB(1, 0), b3, voffB); PG8_STAGE(PG8_SB(1, 1), b3 + hstepB, voffB); PG8_STAGE(PG8_SA(1, 0), a3, voffA);
;             PG8_WAIT_V(8); PG8_WAIT_L(0); PG8_BAR; PG8_MMA(1, 0, At, B0); PG8_MMA(1, 1, At, B1); PG8_BAR; PG8_SCHED;
.Lp8k_B_nobar:
	ds_read_b128 v[190:193], v155 offset:0
	ds_read_b128 v[194:197], v155 offset:1024
	s_add_i32 m0, s2, 0xa000
	ds_read_b128 v[198:201], v155 offset:2048
	global_load_lds_dwordx4 v132, s[28:29]
	ds_read_b128 v[202:205], v155 offset:3072
	ds_read_b128 v[206:209], v155 offset:4096
	s_add_u32 s30, s28, 0x20000
	s_addc_u32 s31, s29, 0
	s_add_i32 m0, s2, 0xb000
	ds_read_b128 v[210:213], v155 offset:5120
	global_load_lds_dwordx4 v132, s[30:31]
	ds_read_b128 v[214:217], v155 offset:6144
	ds_read_b128 v[218:221], v155 offset:7168
	s_add_u32 s30, s28, 0x80000
	s_addc_u32 s31, s29, 0
	s_add_i32 m0, s2, 0xe000
	ds_read_b128 v[156:159], v153 offset:0
	global_load_lds_dwordx4 v132, s[30:31]
	ds_read_b128 v[160:163], v153 offset:1024
	ds_read_b128 v[164:167], v153 offset:2048
	s_add_u32 s30, s28, 0xa0000
	s_addc_u32 s31, s29, 0
	s_add_i32 m0, s2, 0xf000
	ds_read_b128 v[168:171], v153 offset:3072
	global_load_lds_dwordx4 v132, s[30:31]
	ds_read_b128 v[174:177], v153 offset:16384
	ds_read_b128 v[178:181], v153 offset:17408
	s_add_u32 s34, s28, 0x80
	s_addc_u32 s35, s29, 0
	s_cmp_eq_u32 s49, 15
	s_cselect_b32 s34, s50, s34
	s_cselect_b32 s35, s51, s35
	s_add_i32 m0, s2, 0x0
	ds_read_b128 v[182:185], v153 offset:18432
	global_load_lds_dwordx4 v136, s[34:35]
	ds_read_b128 v[186:189], v153 offset:19456
	ds_read_b128 v[222:225], v155 offset:16384
	s_add_u32 s30, s34, 0x20000
	s_addc_u32 s31, s35, 0
	s_add_i32 m0, s2, 0x1000
	ds_read_b128 v[226:229], v155 offset:17408
	global_load_lds_dwordx4 v136, s[30:31]
	ds_read_b128 v[230:233], v155 offset:18432
	ds_read_b128 v[234:237], v155 offset:19456
	s_add_u32 s30, s34, 0x80000
	s_addc_u32 s31, s35, 0
	s_add_i32 m0, s2, 0x4000
	ds_read_b128 v[238:241], v155 offset:20480
	global_load_lds_dwordx4 v136, s[30:31]
	ds_read_b128 v[242:245], v155 offset:21504
	ds_read_b128 v[246:249], v155 offset:22528
	s_add_u32 s30, s34, 0xa0000
	s_addc_u32 s31, s35, 0
	s_add_i32 m0, s2, 0x5000
	ds_read_b128 v[250:253], v155 offset:23552
	global_load_lds_dwordx4 v136, s[30:31]
	s_add_u32 s28, s28, 0x80
	s_addc_u32 s29, s29, 0
	s_waitcnt vmcnt(8) lgkmcnt(0)
	s_barrier
	v_mfma_f32_16x16x32_bf16 v[126:129], v[156:159], v[190:193], 0
	v_mfma_f32_16x16x32_bf16 v[126:129], v[160:163], v[194:197], v[126:129]
	v_mfma_f32_16x16x32_bf16 v[122:125], v[168:171], v[194:197], 0
	v_mfma_f32_16x16x32_bf16 v[122:125], v[164:167], v[190:193], v[122:125]
	v_mfma_f32_16x16x32_bf16 v[118:121], v[174:177], v[190:193], 0
	v_mfma_f32_16x16x32_bf16 v[118:121], v[178:181], v[194:197], v[118:121]
	v_mfma_f32_16x16x32_bf16 v[114:117], v[186:189], v[194:197], 0
	v_mfma_f32_16x16x32_bf16 v[114:117], v[182:185], v[190:193], v[114:117]
	v_mfma_f32_16x16x32_bf16 v[98:101], v[182:185], v[198:201], 0
	v_mfma_f32_16x16x32_bf16 v[98:101], v[186:189], v[202:205], v[98:101]
	v_mfma_f32_16x16x32_bf16 v[102:105], v[178:181], v[202:205], 0
	v_mfma_f32_16x16x32_bf16 v[102:105], v[174:177], v[198:201], v[102:105]
	v_mfma_f32_16x16x32_bf16 v[106:109], v[164:167], v[198:201], 0
	v_mfma_f32_16x16x32_bf16 v[106:109], v[168:171], v[202:205], v[106:109]
	v_mfma_f32_16x16x32_bf16 v[110:113], v[160:163], v[202:205], 0
	v_mfma_f32_16x16x32_bf16 v[110:113], v[156:159], v[198:201], v[110:113]
	v_mfma_f32_16x16x32_bf16 v[94:97], v[156:159], v[206:209], 0
	v_mfma_f32_16x16x32_bf16 v[94:97], v[160:163], v[210:213], v[94:97]
	v_mfma_f32_16x16x32_bf16 v[90:93], v[168:171], v[210:213], 0
	v_mfma_f32_16x16x32_bf16 v[90:93], v[164:167], v[206:209], v[90:93]
	v_mfma_f32_16x16x32_bf16 v[86:89], v[174:177], v[206:209], 0
	v_mfma_f32_16x16x32_bf16 v[86:89], v[178:181], v[210:213], v[86:89]
	v_mfma_f32_16x16x32_bf16 v[82:85], v[186:189], v[210:213], 0
	v_mfma_f32_16x16x32_bf16 v[82:85], v[182:185], v[206:209], v[82:85]
	v_mfma_f32_16x16x32_bf16 v[66:69], v[182:185], v[214:217], 0
	v_mfma_f32_16x16x32_bf16 v[66:69], v[186:189], v[218:221], v[66:69]
	v_mfma_f32_16x16x32_bf16 v[70:73], v[178:181], v[218:221], 0
	v_mfma_f32_16x16x32_bf16 v[70:73], v[174:177], v[214:217], v[70:73]
	v_mfma_f32_16x16x32_bf16 v[74:77], v[164:167], v[214:217], 0
	v_mfma_f32_16x16x32_bf16 v[74:77], v[168:171], v[218:221], v[74:77]
	v_mfma_f32_16x16x32_bf16 v[78:81], v[160:163], v[218:221], 0
	v_mfma_f32_16x16x32_bf16 v[78:81], v[156:159], v[214:217], v[78:81]
	v_mfma_f32_16x16x32_bf16 v[62:65], v[156:159], v[222:225], 0
	v_mfma_f32_16x16x32_bf16 v[62:65], v[160:163], v[226:229], v[62:65]
	v_mfma_f32_16x16x32_bf16 v[58:61], v[168:171], v[226:229], 0
	v_mfma_f32_16x16x32_bf16 v[58:61], v[164:167], v[222:225], v[58:61]
	v_mfma_f32_16x16x32_bf16 v[54:57], v[174:177], v[222:225], 0
	v_mfma_f32_16x16x32_bf16 v[54:57], v[178:181], v[226:229], v[54:57]
	v_mfma_f32_16x16x32_bf16 v[50:53], v[186:189], v[226:229], 0
	v_mfma_f32_16x16x32_bf16 v[50:53], v[182:185], v[222:225], v[50:53]
	v_mfma_f32_16x16x32_bf16 v[34:37], v[182:185], v[230:233], 0
	v_mfma_f32_16x16x32_bf16 v[34:37], v[186:189], v[234:237], v[34:37]
	v_mfma_f32_16x16x32_bf16 v[38:41], v[178:181], v[234:237], 0
	v_mfma_f32_16x16x32_bf16 v[38:41], v[174:177], v[230:233], v[38:41]
	v_mfma_f32_16x16x32_bf16 v[42:45], v[164:167], v[230:233], 0
	v_mfma_f32_16x16x32_bf16 v[42:45], v[168:171], v[234:237], v[42:45]
	v_mfma_f32_16x16x32_bf16 v[46:49], v[160:163], v[234:237], 0
	v_mfma_f32_16x16x32_bf16 v[46:49], v[156:159], v[230:233], v[46:49]
	v_mfma_f32_16x16x32_bf16 v[30:33], v[156:159], v[238:241], 0
	v_mfma_f32_16x16x32_bf16 v[30:33], v[160:163], v[242:245], v[30:33]
	v_mfma_f32_16x16x32_bf16 v[26:29], v[168:171], v[242:245], 0
	v_mfma_f32_16x16x32_bf16 v[26:29], v[164:167], v[238:241], v[26:29]
	v_mfma_f32_16x16x32_bf16 v[22:25], v[174:177], v[238:241], 0
	v_mfma_f32_16x16x32_bf16 v[22:25], v[178:181], v[242:245], v[22:25]
	v_mfma_f32_16x16x32_bf16 v[18:21], v[186:189], v[242:245], 0
	v_mfma_f32_16x16x32_bf16 v[18:21], v[182:185], v[238:241], v[18:21]
	v_mfma_f32_16x16x32_bf16 v[2:5], v[182:185], v[246:249], 0
	v_mfma_f32_16x16x32_bf16 v[2:5], v[186:189], v[250:253], v[2:5]
	v_mfma_f32_16x16x32_bf16 v[6:9], v[178:181], v[250:253], 0
	v_mfma_f32_16x16x32_bf16 v[6:9], v[174:177], v[246:249], v[6:9]
	v_mfma_f32_16x16x32_bf16 v[10:13], v[164:167], v[246:249], 0
	v_mfma_f32_16x16x32_bf16 v[10:13], v[168:171], v[250:253], v[10:13]
	v_mfma_f32_16x16x32_bf16 v[14:17], v[160:163], v[250:253], 0
	v_mfma_f32_16x16x32_bf16 v[14:17], v[156:159], v[246:249], v[14:17]
	s_waitcnt vmcnt(0)
	s_barrier
; #define PG8_STAGE(bufoff, gbase, voff) do { _Pragma("unroll") for (int _i = 0; _i < 2; ++_i) \
;         __builtin_amdgcn_global_load_lds((const unsigned*)((const char*)(gbase) + (voff)[_i]), (PG8_LAS unsigned*)(lds + (bufoff) + ldsw + _i * 8192), 16, 0, 0); } while (0)
; #define PG8_LDA(dst, b, h) do { _Pragma("unroll") for (int m = 0; m < 4; ++m) _Pragma("unroll") for (int k = 0; k < 2; ++k) dst[m][k] = *(const PG8_LAS bf16x8*)(lds + PG8_SA(b, h) + aoff + m * 2048 + k * 1024); } while (0)
; #define PG8_LDB(dst, b, h) do { _Pragma("unroll") for (int n = 0; n < 2; ++n) _Pragma("unroll") for (int k = 0; k < 2; ++k) dst[n][k] = *(const PG8_LAS bf16x8*)(lds + PG8_SB(b, h) + boff + n * 2048 + k * 1024); } while (0)
; #define PG8_MMA(ai, bj, At, Bt) do { __builtin_amdgcn_s_setprio(1); _Pragma("unroll") for (int m = 0; m < 4; ++m) _Pragma("unroll") for (int n = 0; n < 2; ++n) _Pragma("unroll") for (int k = 0; k < 2; ++k) \
;         acc[ai][bj][m][n] = __builtin_amdgcn_mfma_f32_16x16x32_bf16(Bt[n][k], At[m][k], acc[ai][bj][m][n], 0, 0, 0); __builtin_amdgcn_s_setprio(0); } while (0)
; #define PG8_WAIT_V(n) asm volatile("s_waitcnt vmcnt(" #n ")" ::: "memory")
; #define PG8_WAIT_L(n) asm volatile("s_waitcnt lgkmcnt(" #n ")" ::: "memory")
; #define PG8_BAR __builtin_amdgcn_s_barrier()
; #define PG8_SCHED __builtin_amdgcn_sched_barrier(0)
; template <class Epi, class Sched, bool ALIGN_EPI>
; __device__ __forceinline__ void gemm_phase(PG8_LAS unsigned char* lds, const Gemm g, const Sched& S, const Epi& E) {
;     ...
;             PG8_LDA(At, 0, 1); PG8_STAGE(PG8_SB(0, 0), b2, voffB); PG8_STAGE(PG8_SB(0, 1), b2 + hstepB, voffB); PG8_STAGE(PG8_SA(0, 0), a2, voffA);
;             PG8_WAIT_V(8); PG8_WAIT_L(0); PG8_BAR; PG8_MMA(1, 0, At, B0); PG8_MMA(1, 1, At, B1); PG8_BAR; PG8_SCHED;
;             PG8_LDB(B0, 1, 0); PG8_LDB(B1, 1, 1); PG8_SCHED; PG8_LDA(At, 1, 0); PG8_STAGE(PG8_SA(0, 1), a2 + hstepA, voffA);
;             PG8_WAIT_V(8); PG8_WAIT_L(0); PG8_BAR; PG8_MMA(0, 0, At, B0); PG8_MMA(0, 1, At, B1); PG8_BAR; PG8_SCHED;
;             PG8_LDA(At, 1, 1); PG8_STAGE(PG8_SB(1, 0), b3, voffB); PG8_STAGE(PG8_SB(1, 1), b3 + hstepB, voffB); PG8_STAGE(PG8_SA(1, 0), a3, voffA);
;             PG8_WAIT_V(8); PG8_WAIT_L(0); PG8_BAR; PG8_MMA(1, 0, At, B0); PG8_MMA(1, 1, At, B1); PG8_BAR; PG8_SCHED;
	ds_read_b128 v[190:193], v155 offset:32768
	ds_read_b128 v[194:197], v155 offset:33792
	s_cmp_eq_u32 s49, 15
	s_cselect_b32 s28, s50, s28
	s_cselect_b32 s29, s51, s29
	s_add_i32 m0, s2, 0x2000
	ds_read_b128 v[198:201], v155 offset:34816
	global_load_lds_dwordx4 v132, s[28:29]
	ds_read_b128 v[202:205], v155 offset:35840
	ds_read_b128 v[206:209], v155 offset:36864
	s_add_u32 s30, s28, 0x20000
	s_addc_u32 s31, s29, 0
	s_add_i32 m0, s2, 0x3000
	ds_read_b128 v[210:213], v155 offset:37888
	global_load_lds_dwordx4 v132, s[30:31]
	ds_read_b128 v[214:217], v155 offset:38912
	ds_read_b128 v[218:221], v155 offset:39936
	s_add_u32 s30, s28, 0x80000
	s_addc_u32 s31, s29, 0
	s_add_i32 m0, s2, 0x6000
	ds_read_b128 v[156:159], v153 offset:32768
	global_load_lds_dwordx4 v132, s[30:31]
	ds_read_b128 v[160:163], v153 offset:33792
	ds_read_b128 v[164:167], v153 offset:34816
	s_add_u32 s30, s28, 0xa0000
	s_addc_u32 s31, s29, 0
	s_add_i32 m0, s2, 0x7000
	ds_read_b128 v[168:171], v153 offset:35840
	global_load_lds_dwordx4 v132, s[30:31]
	ds_read_b128 v[174:177], v153 offset:49152
	ds_read_b128 v[178:181], v153 offset:50176
	s_add_u32 s34, s28, 0x80
	s_addc_u32 s35, s29, 0
	s_add_i32 m0, s2, 0x8000
	ds_read_b128 v[182:185], v153 offset:51200
	global_load_lds_dwordx4 v136, s[34:35]
	ds_read_b128 v[186:189], v153 offset:52224
	ds_read_b128 v[222:225], v155 offset:49152
	s_add_u32 s30, s34, 0x20000
	s_addc_u32 s31, s35, 0
	s_add_i32 m0, s2, 0x9000
	ds_read_b128 v[226:229], v155 offset:50176
	global_load_lds_dwordx4 v136, s[30:31]
	ds_read_b128 v[230:233], v155 offset:51200
	ds_read_b128 v[234:237], v155 offset:52224
	s_add_u32 s30, s34, 0x80000
	s_addc_u32 s31, s35, 0
	s_add_i32 m0, s2, 0xc000
	ds_read_b128 v[238:241], v155 offset:53248
	global_load_lds_dwordx4 v136, s[30:31]
	ds_read_b128 v[242:245], v155 offset:54272
	ds_read_b128 v[246:249], v155 offset:55296
	s_add_u32 s30, s34, 0xa0000
	s_addc_u32 s31, s35, 0
	s_add_i32 m0, s2, 0xd000
	ds_read_b128 v[250:253], v155 offset:56320
	global_load_lds_dwordx4 v136, s[30:31]
	s_add_u32 s28, s28, 0x80
	s_addc_u32 s29, s29, 0
	s_waitcnt vmcnt(8) lgkmcnt(0)
	s_barrier
	v_mfma_f32_16x16x32_bf16 v[126:129], v[156:159], v[190:193], v[126:129]
	v_mfma_f32_16x16x32_bf16 v[126:129], v[160:163], v[194:197], v[126:129]
	v_mfma_f32_16x16x32_bf16 v[122:125], v[168:171], v[194:197], v[122:125]
	v_mfma_f32_16x16x32_bf16 v[122:125], v[164:167], v[190:193], v[122:125]
	v_mfma_f32_16x16x32_bf16 v[118:121], v[174:177], v[190:193], v[118:121]
	v_mfma_f32_16x16x32_bf16 v[118:121], v[178:181], v[194:197], v[118:121]
	v_mfma_f32_16x16x32_bf16 v[114:117], v[186:189], v[194:197], v[114:117]
	v_mfma_f32_16x16x32_bf16 v[114:117], v[182:185], v[190:193], v[114:117]
	v_mfma_f32_16x16x32_bf16 v[98:101], v[182:185], v[198:201], v[98:101]
	v_mfma_f32_16x16x32_bf16 v[98:101], v[186:189], v[202:205], v[98:101]
	v_mfma_f32_16x16x32_bf16 v[102:105], v[178:181], v[202:205], v[102:105]
	v_mfma_f32_16x16x32_bf16 v[102:105], v[174:177], v[198:201], v[102:105]
	v_mfma_f32_16x16x32_bf16 v[106:109], v[164:167], v[198:201], v[106:109]
	v_mfma_f32_16x16x32_bf16 v[106:109], v[168:171], v[202:205], v[106:109]
	v_mfma_f32_16x16x32_bf16 v[110:113], v[160:163], v[202:205], v[110:113]
	v_mfma_f32_16x16x32_bf16 v[110:113], v[156:159], v[198:201], v[110:113]
	v_mfma_f32_16x16x32_bf16 v[94:97], v[156:159], v[206:209], v[94:97]
	v_mfma_f32_16x16x32_bf16 v[94:97], v[160:163], v[210:213], v[94:97]
	v_mfma_f32_16x16x32_bf16 v[90:93], v[168:171], v[210:213], v[90:93]
	v_mfma_f32_16x16x32_bf16 v[90:93], v[164:167], v[206:209], v[90:93]
	v_mfma_f32_16x16x32_bf16 v[86:89], v[174:177], v[206:209], v[86:89]
	v_mfma_f32_16x16x32_bf16 v[86:89], v[178:181], v[210:213], v[86:89]
	v_mfma_f32_16x16x32_bf16 v[82:85], v[186:189], v[210:213], v[82:85]
	v_mfma_f32_16x16x32_bf16 v[82:85], v[182:185], v[206:209], v[82:85]
	v_mfma_f32_16x16x32_bf16 v[66:69], v[182:185], v[214:217], v[66:69]
	v_mfma_f32_16x16x32_bf16 v[66:69], v[186:189], v[218:221], v[66:69]
	v_mfma_f32_16x16x32_bf16 v[70:73], v[178:181], v[218:221], v[70:73]
	v_mfma_f32_16x16x32_bf16 v[70:73], v[174:177], v[214:217], v[70:73]
	v_mfma_f32_16x16x32_bf16 v[74:77], v[164:167], v[214:217], v[74:77]
	v_mfma_f32_16x16x32_bf16 v[74:77], v[168:171], v[218:221], v[74:77]
	v_mfma_f32_16x16x32_bf16 v[78:81], v[160:163], v[218:221], v[78:81]
	v_mfma_f32_16x16x32_bf16 v[78:81], v[156:159], v[214:217], v[78:81]
	v_mfma_f32_16x16x32_bf16 v[62:65], v[156:159], v[222:225], v[62:65]
	v_mfma_f32_16x16x32_bf16 v[62:65], v[160:163], v[226:229], v[62:65]
	v_mfma_f32_16x16x32_bf16 v[58:61], v[168:171], v[226:229], v[58:61]
	v_mfma_f32_16x16x32_bf16 v[58:61], v[164:167], v[222:225], v[58:61]
	v_mfma_f32_16x16x32_bf16 v[54:57], v[174:177], v[222:225], v[54:57]
	v_mfma_f32_16x16x32_bf16 v[54:57], v[178:181], v[226:229], v[54:57]
	v_mfma_f32_16x16x32_bf16 v[50:53], v[186:189], v[226:229], v[50:53]
	v_mfma_f32_16x16x32_bf16 v[50:53], v[182:185], v[222:225], v[50:53]
	v_mfma_f32_16x16x32_bf16 v[34:37], v[182:185], v[230:233], v[34:37]
	v_mfma_f32_16x16x32_bf16 v[34:37], v[186:189], v[234:237], v[34:37]
	v_mfma_f32_16x16x32_bf16 v[38:41], v[178:181], v[234:237], v[38:41]
	v_mfma_f32_16x16x32_bf16 v[38:41], v[174:177], v[230:233], v[38:41]
	v_mfma_f32_16x16x32_bf16 v[42:45], v[164:167], v[230:233], v[42:45]
	v_mfma_f32_16x16x32_bf16 v[42:45], v[168:171], v[234:237], v[42:45]
	v_mfma_f32_16x16x32_bf16 v[46:49], v[160:163], v[234:237], v[46:49]
	v_mfma_f32_16x16x32_bf16 v[46:49], v[156:159], v[230:233], v[46:49]
	v_mfma_f32_16x16x32_bf16 v[30:33], v[156:159], v[238:241], v[30:33]
	v_mfma_f32_16x16x32_bf16 v[30:33], v[160:163], v[242:245], v[30:33]
	v_mfma_f32_16x16x32_bf16 v[26:29], v[168:171], v[242:245], v[26:29]
	v_mfma_f32_16x16x32_bf16 v[26:29], v[164:167], v[238:241], v[26:29]
	v_mfma_f32_16x16x32_bf16 v[22:25], v[174:177], v[238:241], v[22:25]
	v_mfma_f32_16x16x32_bf16 v[22:25], v[178:181], v[242:245], v[22:25]
	v_mfma_f32_16x16x32_bf16 v[18:21], v[186:189], v[242:245], v[18:21]
	v_mfma_f32_16x16x32_bf16 v[18:21], v[182:185], v[238:241], v[18:21]
	v_mfma_f32_16x16x32_bf16 v[2:5], v[182:185], v[246:249], v[2:5]
	v_mfma_f32_16x16x32_bf16 v[2:5], v[186:189], v[250:253], v[2:5]
	v_mfma_f32_16x16x32_bf16 v[6:9], v[178:181], v[250:253], v[6:9]
	v_mfma_f32_16x16x32_bf16 v[6:9], v[174:177], v[246:249], v[6:9]
	v_mfma_f32_16x16x32_bf16 v[10:13], v[164:167], v[246:249], v[10:13]
	v_mfma_f32_16x16x32_bf16 v[10:13], v[168:171], v[250:253], v[10:13]
	v_mfma_f32_16x16x32_bf16 v[14:17], v[160:163], v[250:253], v[14:17]
	v_mfma_f32_16x16x32_bf16 v[14:17], v[156:159], v[246:249], v[14:17]
	s_waitcnt vmcnt(0)
	s_barrier
	s_add_i32 s49, s49, 1
; #define PG8_STAGE(bufoff, gbase, voff) do { _Pragma("unroll") for (int _i = 0; _i < 2; ++_i) \
;         __builtin_amdgcn_global_load_lds((const unsigned*)((const char*)(gbase) + (voff)[_i]), (PG8_LAS unsigned*)(lds + (bufoff) + ldsw + _i * 8192), 16, 0, 0); } while (0)
; #define PG8_LDA(dst, b, h) do { _Pragma("unroll") for (int m = 0; m < 4; ++m) _Pragma("unroll") for (int k = 0; k < 2; ++k) dst[m][k] = *(const PG8_LAS bf16x8*)(lds + PG8_SA(b, h) + aoff + m * 2048 + k * 1024); } while (0)
; #define PG8_LDB(dst, b, h) do { _Pragma("unroll") for (int n = 0; n < 2; ++n) _Pragma("unroll") for (int k = 0; k < 2; ++k) dst[n][k] = *(const PG8_LAS bf16x8*)(lds + PG8_SB(b, h) + boff + n * 2048 + k * 1024); } while (0)
; #define PG8_MMA(ai, bj, At, Bt) do { __builtin_amdgcn_s_setprio(1); _Pragma("unroll") for (int m = 0; m < 4; ++m) _Pragma("unroll") for (int n = 0; n < 2; ++n) _Pragma("unroll") for (int k = 0; k < 2; ++k) \
;         acc[ai][bj][m][n] = __builtin_amdgcn_mfma_f32_16x16x32_bf16(Bt[n][k], At[m][k], acc[ai][bj][m][n], 0, 0, 0); __builtin_amdgcn_s_setprio(0); } while (0)
; #define PG8_WAIT_V(n) asm volatile("s_waitcnt vmcnt(" #n ")" ::: "memory")
; template <class Epi, class Sched, bool ALIGN_EPI>
; __device__ __forceinline__ void gemm_phase(PG8_LAS unsigned char* lds, const Gemm g, const Sched& S, const Epi& E) {
;     ...
;             PG8_LDB(B0, 0, 0); PG8_LDB(B1, 0, 1); PG8_SCHED; PG8_LDA(At, 0, 0); PG8_STAGE(PG8_SA(1, 1), a1 + hstepA, voffA);
;             PG8_WAIT_V(8); PG8_WAIT_L(0); PG8_BAR; PG8_MMA(0, 0, At, B0); PG8_MMA(0, 1, At, B1); PG8_BAR; PG8_SCHED;
;             PG8_LDA(At, 0, 1); PG8_STAGE(PG8_SB(0, 0), b2, voffB); PG8_STAGE(PG8_SB(0, 1), b2 + hstepB, voffB); PG8_STAGE(PG8_SA(0, 0), a2, voffA);
;             PG8_WAIT_V(8); PG8_WAIT_L(0); PG8_BAR; PG8_MMA(1, 0, At, B0); PG8_MMA(1, 1, At, B1); PG8_BAR; PG8_SCHED;
;             PG8_LDB(B0, 1, 0); PG8_LDB(B1, 1, 1); PG8_SCHED; PG8_LDA(At, 1, 0); PG8_STAGE(PG8_SA(0, 1), a2 + hstepA, voffA);
;             PG8_WAIT_V(8); PG8_WAIT_L(0); PG8_BAR; PG8_MMA(0, 0, At, B0); PG8_MMA(0, 1, At, B1); PG8_BAR; PG8_SCHED;
;             PG8_LDA(At, 1, 1); PG8_STAGE(PG8_SB(1, 0), b3, voffB); PG8_STAGE(PG8_SB(1, 1), b3 + hstepB, voffB); PG8_STAGE(PG8_SA(1, 0), a3, voffA);
;             PG8_WAIT_V(8); PG8_WAIT_L(0); PG8_BAR; PG8_MMA(1, 0, At, B0); PG8_MMA(1, 1, At, B1); PG8_BAR; PG8_SCHED;
.Lp8k_B_loop:
	ds_read_b128 v[190:193], v155 offset:0
	ds_read_b128 v[194:197], v155 offset:1024
	s_add_i32 m0, s2, 0xa000
	ds_read_b128 v[198:201], v155 offset:2048
	global_load_lds_dwordx4 v132, s[28:29]
	ds_read_b128 v[202:205], v155 offset:3072
	ds_read_b128 v[206:209], v155 offset:4096
	s_add_u32 s30, s28, 0x20000
	s_addc_u32 s31, s29, 0
	s_add_i32 m0, s2, 0xb000
	ds_read_b128 v[210:213], v155 offset:5120
	global_load_lds_dwordx4 v132, s[30:31]
	ds_read_b128 v[214:217], v155 offset:6144
	ds_read_b128 v[218:221], v155 offset:7168
	s_add_u32 s30, s28, 0x80000
	s_addc_u32 s31, s29, 0
	s_add_i32 m0, s2, 0xe000
	ds_read_b128 v[156:159], v153 offset:0
	global_load_lds_dwordx4 v132, s[30:31]
	ds_read_b128 v[160:163], v153 offset:1024
	ds_read_b128 v[164:167], v153 offset:2048
	s_add_u32 s30, s28, 0xa0000
	s_addc_u32 s31, s29, 0
	s_add_i32 m0, s2, 0xf000
	ds_read_b128 v[168:171], v153 offset:3072
	global_load_lds_dwordx4 v132, s[30:31]
	ds_read_b128 v[174:177], v153 offset:16384
	ds_read_b128 v[178:181], v153 offset:17408
	s_add_u32 s34, s28, 0x80
	s_addc_u32 s35, s29, 0
	s_cmp_eq_u32 s49, 15
	s_cselect_b32 s34, s50, s34
	s_cselect_b32 s35, s51, s35
	s_add_i32 m0, s2, 0x0
	ds_read_b128 v[182:185], v153 offset:18432
	global_load_lds_dwordx4 v136, s[34:35]
	ds_read_b128 v[186:189], v153 offset:19456
	ds_read_b128 v[222:225], v155 offset:16384
	s_add_u32 s30, s34, 0x20000
	s_addc_u32 s31, s35, 0
	s_add_i32 m0, s2, 0x1000
	ds_read_b128 v[226:229], v155 offset:17408
	global_load_lds_dwordx4 v136, s[30:31]
	ds_read_b128 v[230:233], v155 offset:18432
	ds_read_b128 v[234:237], v155 offset:19456
	s_add_u32 s30, s34, 0x80000
	s_addc_u32 s31, s35, 0
	s_add_i32 m0, s2, 0x4000
	ds_read_b128 v[238:241], v155 offset:20480
	global_load_lds_dwordx4 v136, s[30:31]
	ds_read_b128 v[242:245], v155 offset:21504
	ds_read_b128 v[246:249], v155 offset:22528
	s_add_u32 s30, s34, 0xa0000
	s_addc_u32 s31, s35, 0
	s_add_i32 m0, s2, 0x5000
	ds_read_b128 v[250:253], v155 offset:23552
	global_load_lds_dwordx4 v136, s[30:31]
	s_add_u32 s28, s28, 0x80
	s_addc_u32 s29, s29, 0
	s_waitcnt vmcnt(8) lgkmcnt(0)
	s_barrier
	v_mfma_f32_16x16x32_bf16 v[126:129], v[156:159], v[190:193], v[126:129]
	v_mfma_f32_16x16x32_bf16 v[126:129], v[160:163], v[194:197], v[126:129]
	v_mfma_f32_16x16x32_bf16 v[122:125], v[168:171], v[194:197], v[122:125]
	v_mfma_f32_16x16x32_bf16 v[122:125], v[164:167], v[190:193], v[122:125]
	v_mfma_f32_16x16x32_bf16 v[118:121], v[174:177], v[190:193], v[118:121]
	v_mfma_f32_16x16x32_bf16 v[118:121], v[178:181], v[194:197], v[118:121]
	v_mfma_f32_16x16x32_bf16 v[114:117], v[186:189], v[194:197], v[114:117]
	v_mfma_f32_16x16x32_bf16 v[114:117], v[182:185], v[190:193], v[114:117]
	v_mfma_f32_16x16x32_bf16 v[98:101], v[182:185], v[198:201], v[98:101]
	v_mfma_f32_16x16x32_bf16 v[98:101], v[186:189], v[202:205], v[98:101]
	v_mfma_f32_16x16x32_bf16 v[102:105], v[178:181], v[202:205], v[102:105]
	v_mfma_f32_16x16x32_bf16 v[102:105], v[174:177], v[198:201], v[102:105]
	v_mfma_f32_16x16x32_bf16 v[106:109], v[164:167], v[198:201], v[106:109]
	v_mfma_f32_16x16x32_bf16 v[106:109], v[168:171], v[202:205], v[106:109]
	v_mfma_f32_16x16x32_bf16 v[110:113], v[160:163], v[202:205], v[110:113]
	v_mfma_f32_16x16x32_bf16 v[110:113], v[156:159], v[198:201], v[110:113]
	v_mfma_f32_16x16x32_bf16 v[94:97], v[156:159], v[206:209], v[94:97]
	v_mfma_f32_16x16x32_bf16 v[94:97], v[160:163], v[210:213], v[94:97]
	v_mfma_f32_16x16x32_bf16 v[90:93], v[168:171], v[210:213], v[90:93]
	v_mfma_f32_16x16x32_bf16 v[90:93], v[164:167], v[206:209], v[90:93]
	v_mfma_f32_16x16x32_bf16 v[86:89], v[174:177], v[206:209], v[86:89]
	v_mfma_f32_16x16x32_bf16 v[86:89], v[178:181], v[210:213], v[86:89]
	v_mfma_f32_16x16x32_bf16 v[82:85], v[186:189], v[210:213], v[82:85]
	v_mfma_f32_16x16x32_bf16 v[82:85], v[182:185], v[206:209], v[82:85]
	v_mfma_f32_16x16x32_bf16 v[66:69], v[182:185], v[214:217], v[66:69]
	v_mfma_f32_16x16x32_bf16 v[66:69], v[186:189], v[218:221], v[66:69]
	v_mfma_f32_16x16x32_bf16 v[70:73], v[178:181], v[218:221], v[70:73]
	v_mfma_f32_16x16x32_bf16 v[70:73], v[174:177], v[214:217], v[70:73]
	v_mfma_f32_16x16x32_bf16 v[74:77], v[164:167], v[214:217], v[74:77]
	v_mfma_f32_16x16x32_bf16 v[74:77], v[168:171], v[218:221], v[74:77]
	v_mfma_f32_16x16x32_bf16 v[78:81], v[160:163], v[218:221], v[78:81]
	v_mfma_f32_16x16x32_bf16 v[78:81], v[156:159], v[214:217], v[78:81]
	v_mfma_f32_16x16x32_bf16 v[62:65], v[156:159], v[222:225], v[62:65]
	v_mfma_f32_16x16x32_bf16 v[62:65], v[160:163], v[226:229], v[62:65]
	v_mfma_f32_16x16x32_bf16 v[58:61], v[168:171], v[226:229], v[58:61]
	v_mfma_f32_16x16x32_bf16 v[58:61], v[164:167], v[222:225], v[58:61]
	v_mfma_f32_16x16x32_bf16 v[54:57], v[174:177], v[222:225], v[54:57]
	v_mfma_f32_16x16x32_bf16 v[54:57], v[178:181], v[226:229], v[54:57]
	v_mfma_f32_16x16x32_bf16 v[50:53], v[186:189], v[226:229], v[50:53]
	v_mfma_f32_16x16x32_bf16 v[50:53], v[182:185], v[222:225], v[50:53]
	v_mfma_f32_16x16x32_bf16 v[34:37], v[182:185], v[230:233], v[34:37]
	v_mfma_f32_16x16x32_bf16 v[34:37], v[186:189], v[234:237], v[34:37]
	v_mfma_f32_16x16x32_bf16 v[38:41], v[178:181], v[234:237], v[38:41]
	v_mfma_f32_16x16x32_bf16 v[38:41], v[174:177], v[230:233], v[38:41]
	v_mfma_f32_16x16x32_bf16 v[42:45], v[164:167], v[230:233], v[42:45]
	v_mfma_f32_16x16x32_bf16 v[42:45], v[168:171], v[234:237], v[42:45]
	v_mfma_f32_16x16x32_bf16 v[46:49], v[160:163], v[234:237], v[46:49]
	v_mfma_f32_16x16x32_bf16 v[46:49], v[156:159], v[230:233], v[46:49]
	v_mfma_f32_16x16x32_bf16 v[30:33], v[156:159], v[238:241], v[30:33]
	v_mfma_f32_16x16x32_bf16 v[30:33], v[160:163], v[242:245], v[30:33]
	v_mfma_f32_16x16x32_bf16 v[26:29], v[168:171], v[242:245], v[26:29]
	v_mfma_f32_16x16x32_bf16 v[26:29], v[164:167], v[238:241], v[26:29]
	v_mfma_f32_16x16x32_bf16 v[22:25], v[174:177], v[238:241], v[22:25]
	v_mfma_f32_16x16x32_bf16 v[22:25], v[178:181], v[242:245], v[22:25]
	v_mfma_f32_16x16x32_bf16 v[18:21], v[186:189], v[242:245], v[18:21]
	v_mfma_f32_16x16x32_bf16 v[18:21], v[182:185], v[238:241], v[18:21]
	v_mfma_f32_16x16x32_bf16 v[2:5], v[182:185], v[246:249], v[2:5]
	v_mfma_f32_16x16x32_bf16 v[2:5], v[186:189], v[250:253], v[2:5]
	v_mfma_f32_16x16x32_bf16 v[6:9], v[178:181], v[250:253], v[6:9]
	v_mfma_f32_16x16x32_bf16 v[6:9], v[174:177], v[246:249], v[6:9]
	v_mfma_f32_16x16x32_bf16 v[10:13], v[164:167], v[246:249], v[10:13]
	v_mfma_f32_16x16x32_bf16 v[10:13], v[168:171], v[250:253], v[10:13]
	v_mfma_f32_16x16x32_bf16 v[14:17], v[160:163], v[250:253], v[14:17]
	v_mfma_f32_16x16x32_bf16 v[14:17], v[156:159], v[246:249], v[14:17]
	s_waitcnt vmcnt(0)
	s_barrier
; #define PG8_STAGE(bufoff, gbase, voff) do { _Pragma("unroll") for (int _i = 0; _i < 2; ++_i) \
;         __builtin_amdgcn_global_load_lds((const unsigned*)((const char*)(gbase) + (voff)[_i]), (PG8_LAS unsigned*)(lds + (bufoff) + ldsw + _i * 8192), 16, 0, 0); } while (0)
; #define PG8_LDA(dst, b, h) do { _Pragma("unroll") for (int m = 0; m < 4; ++m) _Pragma("unroll") for (int k = 0; k < 2; ++k) dst[m][k] = *(const PG8_LAS bf16x8*)(lds + PG8_SA(b, h) + aoff + m * 2048 + k * 1024); } while (0)
; #define PG8_LDB(dst, b, h) do { _Pragma("unroll") for (int n = 0; n < 2; ++n) _Pragma("unroll") for (int k = 0; k < 2; ++k) dst[n][k] = *(const PG8_LAS bf16x8*)(lds + PG8_SB(b, h) + boff + n * 2048 + k * 1024); } while (0)
; #define PG8_MMA(ai, bj, At, Bt) do { __builtin_amdgcn_s_setprio(1); _Pragma("unroll") for (int m = 0; m < 4; ++m) _Pragma("unroll") for (int n = 0; n < 2; ++n) _Pragma("unroll") for (int k = 0; k < 2; ++k) \
;         acc[ai][bj][m][n] = __builtin_amdgcn_mfma_f32_16x16x32_bf16(Bt[n][k], At[m][k], acc[ai][bj][m][n], 0, 0, 0); __builtin_amdgcn_s_setprio(0); } while (0)
; #define PG8_WAIT_V(n) asm volatile("s_waitcnt vmcnt(" #n ")" ::: "memory")
; #define PG8_WAIT_L(n) asm volatile("s_waitcnt lgkmcnt(" #n ")" ::: "memory")
; #define PG8_BAR __builtin_amdgcn_s_barrier()
; #define PG8_SCHED __builtin_amdgcn_sched_barrier(0)
; template <class Epi, class Sched, bool ALIGN_EPI>
; __device__ __forceinline__ void gemm_phase(PG8_LAS unsigned char* lds, const Gemm g, const Sched& S, const Epi& E) {
;     ...
;             PG8_LDA(At, 0, 1); PG8_STAGE(PG8_SB(0, 0), b2, voffB); PG8_STAGE(PG8_SB(0, 1), b2 + hstepB, voffB); PG8_STAGE(PG8_SA(0, 0), a2, voffA);
;             PG8_WAIT_V(8); PG8_WAIT_L(0); PG8_BAR; PG8_MMA(1, 0, At, B0); PG8_MMA(1, 1, At, B1); PG8_BAR; PG8_SCHED;
;             PG8_LDB(B0, 1, 0); PG8_LDB(B1, 1, 1); PG8_SCHED; PG8_LDA(At, 1, 0); PG8_STAGE(PG8_SA(0, 1), a2 + hstepA, voffA);
;             PG8_WAIT_V(8); PG8_WAIT_L(0); PG8_BAR; PG8_MMA(0, 0, At, B0); PG8_MMA(0, 1, At, B1); PG8_BAR; PG8_SCHED;
;             PG8_LDA(At, 1, 1); PG8_STAGE(PG8_SB(1, 0), b3, voffB); PG8_STAGE(PG8_SB(1, 1), b3 + hstepB, voffB); PG8_STAGE(PG8_SA(1, 0), a3, voffA);
;             PG8_WAIT_V(8); PG8_WAIT_L(0); PG8_BAR; PG8_MMA(1, 0, At, B0); PG8_MMA(1, 1, At, B1); PG8_BAR; PG8_SCHED;
;         }
	ds_read_b128 v[190:193], v155 offset:32768
	ds_read_b128 v[194:197], v155 offset:33792
	s_cmp_eq_u32 s49, 15
	s_cselect_b32 s28, s50, s28
	s_cselect_b32 s29, s51, s29
	s_add_i32 m0, s2, 0x2000
	ds_read_b128 v[198:201], v155 offset:34816
	global_load_lds_dwordx4 v132, s[28:29]
	ds_read_b128 v[202:205], v155 offset:35840
	ds_read_b128 v[206:209], v155 offset:36864
	s_add_u32 s30, s28, 0x20000
	s_addc_u32 s31, s29, 0
	s_add_i32 m0, s2, 0x3000
	ds_read_b128 v[210:213], v155 offset:37888
	global_load_lds_dwordx4 v132, s[30:31]
	ds_read_b128 v[214:217], v155 offset:38912
	ds_read_b128 v[218:221], v155 offset:39936
	s_add_u32 s30, s28, 0x80000
	s_addc_u32 s31, s29, 0
	s_add_i32 m0, s2, 0x6000
	ds_read_b128 v[156:159], v153 offset:32768
	global_load_lds_dwordx4 v132, s[30:31]
	ds_read_b128 v[160:163], v153 offset:33792
	ds_read_b128 v[164:167], v153 offset:34816
	s_add_u32 s30, s28, 0xa0000
	s_addc_u32 s31, s29, 0
	s_add_i32 m0, s2, 0x7000
	ds_read_b128 v[168:171], v153 offset:35840
	global_load_lds_dwordx4 v132, s[30:31]
	ds_read_b128 v[174:177], v153 offset:49152
	ds_read_b128 v[178:181], v153 offset:50176
	s_add_u32 s34, s28, 0x80
	s_addc_u32 s35, s29, 0
	s_add_i32 m0, s2, 0x8000
	ds_read_b128 v[182:185], v153 offset:51200
	global_load_lds_dwordx4 v136, s[34:35]
	ds_read_b128 v[186:189], v153 offset:52224
	ds_read_b128 v[222:225], v155 offset:49152
	s_add_u32 s30, s34, 0x20000
	s_addc_u32 s31, s35, 0
	s_add_i32 m0, s2, 0x9000
	ds_read_b128 v[226:229], v155 offset:50176
	global_load_lds_dwordx4 v136, s[30:31]
	ds_read_b128 v[230:233], v155 offset:51200
	ds_read_b128 v[234:237], v155 offset:52224
	s_add_u32 s30, s34, 0x80000
	s_addc_u32 s31, s35, 0
	s_add_i32 m0, s2, 0xc000
	ds_read_b128 v[238:241], v155 offset:53248
	global_load_lds_dwordx4 v136, s[30:31]
	ds_read_b128 v[242:245], v155 offset:54272
	ds_read_b128 v[246:249], v155 offset:55296
	s_add_u32 s30, s34, 0xa0000
	s_addc_u32 s31, s35, 0
	s_add_i32 m0, s2, 0xd000
	ds_read_b128 v[250:253], v155 offset:56320
	global_load_lds_dwordx4 v136, s[30:31]
	s_add_u32 s28, s28, 0x80
	s_addc_u32 s29, s29, 0
	s_waitcnt vmcnt(8) lgkmcnt(0)
	s_barrier
	v_mfma_f32_16x16x32_bf16 v[126:129], v[156:159], v[190:193], v[126:129]
	v_mfma_f32_16x16x32_bf16 v[126:129], v[160:163], v[194:197], v[126:129]
	v_mfma_f32_16x16x32_bf16 v[122:125], v[168:171], v[194:197], v[122:125]
	v_mfma_f32_16x16x32_bf16 v[122:125], v[164:167], v[190:193], v[122:125]
	v_mfma_f32_16x16x32_bf16 v[118:121], v[174:177], v[190:193], v[118:121]
	v_mfma_f32_16x16x32_bf16 v[118:121], v[178:181], v[194:197], v[118:121]
	v_mfma_f32_16x16x32_bf16 v[114:117], v[186:189], v[194:197], v[114:117]
	v_mfma_f32_16x16x32_bf16 v[114:117], v[182:185], v[190:193], v[114:117]
	v_mfma_f32_16x16x32_bf16 v[98:101], v[182:185], v[198:201], v[98:101]
	v_mfma_f32_16x16x32_bf16 v[98:101], v[186:189], v[202:205], v[98:101]
	v_mfma_f32_16x16x32_bf16 v[102:105], v[178:181], v[202:205], v[102:105]
	v_mfma_f32_16x16x32_bf16 v[102:105], v[174:177], v[198:201], v[102:105]
	v_mfma_f32_16x16x32_bf16 v[106:109], v[164:167], v[198:201], v[106:109]
	v_mfma_f32_16x16x32_bf16 v[106:109], v[168:171], v[202:205], v[106:109]
	v_mfma_f32_16x16x32_bf16 v[110:113], v[160:163], v[202:205], v[110:113]
	v_mfma_f32_16x16x32_bf16 v[110:113], v[156:159], v[198:201], v[110:113]
	v_mfma_f32_16x16x32_bf16 v[94:97], v[156:159], v[206:209], v[94:97]
	v_mfma_f32_16x16x32_bf16 v[94:97], v[160:163], v[210:213], v[94:97]
	v_mfma_f32_16x16x32_bf16 v[90:93], v[168:171], v[210:213], v[90:93]
	v_mfma_f32_16x16x32_bf16 v[90:93], v[164:167], v[206:209], v[90:93]
	v_mfma_f32_16x16x32_bf16 v[86:89], v[174:177], v[206:209], v[86:89]
	v_mfma_f32_16x16x32_bf16 v[86:89], v[178:181], v[210:213], v[86:89]
	v_mfma_f32_16x16x32_bf16 v[82:85], v[186:189], v[210:213], v[82:85]
	v_mfma_f32_16x16x32_bf16 v[82:85], v[182:185], v[206:209], v[82:85]
	v_mfma_f32_16x16x32_bf16 v[66:69], v[182:185], v[214:217], v[66:69]
	v_mfma_f32_16x16x32_bf16 v[66:69], v[186:189], v[218:221], v[66:69]
	v_mfma_f32_16x16x32_bf16 v[70:73], v[178:181], v[218:221], v[70:73]
	v_mfma_f32_16x16x32_bf16 v[70:73], v[174:177], v[214:217], v[70:73]
	v_mfma_f32_16x16x32_bf16 v[74:77], v[164:167], v[214:217], v[74:77]
	v_mfma_f32_16x16x32_bf16 v[74:77], v[168:171], v[218:221], v[74:77]
	v_mfma_f32_16x16x32_bf16 v[78:81], v[160:163], v[218:221], v[78:81]
	v_mfma_f32_16x16x32_bf16 v[78:81], v[156:159], v[214:217], v[78:81]
	v_mfma_f32_16x16x32_bf16 v[62:65], v[156:159], v[222:225], v[62:65]
	v_mfma_f32_16x16x32_bf16 v[62:65], v[160:163], v[226:229], v[62:65]
	v_mfma_f32_16x16x32_bf16 v[58:61], v[168:171], v[226:229], v[58:61]
	v_mfma_f32_16x16x32_bf16 v[58:61], v[164:167], v[222:225], v[58:61]
	v_mfma_f32_16x16x32_bf16 v[54:57], v[174:177], v[222:225], v[54:57]
	v_mfma_f32_16x16x32_bf16 v[54:57], v[178:181], v[226:229], v[54:57]
	v_mfma_f32_16x16x32_bf16 v[50:53], v[186:189], v[226:229], v[50:53]
	v_mfma_f32_16x16x32_bf16 v[50:53], v[182:185], v[222:225], v[50:53]
	v_mfma_f32_16x16x32_bf16 v[34:37], v[182:185], v[230:233], v[34:37]
	v_mfma_f32_16x16x32_bf16 v[34:37], v[186:189], v[234:237], v[34:37]
	v_mfma_f32_16x16x32_bf16 v[38:41], v[178:181], v[234:237], v[38:41]
	v_mfma_f32_16x16x32_bf16 v[38:41], v[174:177], v[230:233], v[38:41]
	v_mfma_f32_16x16x32_bf16 v[42:45], v[164:167], v[230:233], v[42:45]
	v_mfma_f32_16x16x32_bf16 v[42:45], v[168:171], v[234:237], v[42:45]
	v_mfma_f32_16x16x32_bf16 v[46:49], v[160:163], v[234:237], v[46:49]
	v_mfma_f32_16x16x32_bf16 v[46:49], v[156:159], v[230:233], v[46:49]
	v_mfma_f32_16x16x32_bf16 v[30:33], v[156:159], v[238:241], v[30:33]
	v_mfma_f32_16x16x32_bf16 v[30:33], v[160:163], v[242:245], v[30:33]
	v_mfma_f32_16x16x32_bf16 v[26:29], v[168:171], v[242:245], v[26:29]
	v_mfma_f32_16x16x32_bf16 v[26:29], v[164:167], v[238:241], v[26:29]
	v_mfma_f32_16x16x32_bf16 v[22:25], v[174:177], v[238:241], v[22:25]
	v_mfma_f32_16x16x32_bf16 v[22:25], v[178:181], v[242:245], v[22:25]
	v_mfma_f32_16x16x32_bf16 v[18:21], v[186:189], v[242:245], v[18:21]
	v_mfma_f32_16x16x32_bf16 v[18:21], v[182:185], v[238:241], v[18:21]
	v_mfma_f32_16x16x32_bf16 v[2:5], v[182:185], v[246:249], v[2:5]
	v_mfma_f32_16x16x32_bf16 v[2:5], v[186:189], v[250:253], v[2:5]
	v_mfma_f32_16x16x32_bf16 v[6:9], v[178:181], v[250:253], v[6:9]
	v_mfma_f32_16x16x32_bf16 v[6:9], v[174:177], v[246:249], v[6:9]
	v_mfma_f32_16x16x32_bf16 v[10:13], v[164:167], v[246:249], v[10:13]
	v_mfma_f32_16x16x32_bf16 v[10:13], v[168:171], v[250:253], v[10:13]
	v_mfma_f32_16x16x32_bf16 v[14:17], v[160:163], v[250:253], v[14:17]
	v_mfma_f32_16x16x32_bf16 v[14:17], v[156:159], v[246:249], v[14:17]
	s_waitcnt vmcnt(0)
	s_add_i32 s49, s49, 1
	s_cmp_lt_u32 s49, 16
	s_cbranch_scc0 .Lp8k_B_exit
	s_barrier
	s_branch .Lp8k_B_loop

; #define PG8_STAGE(bufoff, gbase, voff) do { _Pragma("unroll") for (int _i = 0; _i < 2; ++_i) \
;         __builtin_amdgcn_global_load_lds((const unsigned*)((const char*)(gbase) + (voff)[_i]), (PG8_LAS unsigned*)(lds + (bufoff) + ldsw + _i * 8192), 16, 0, 0); } while (0)
; #define PG8_LDA(dst, b, h) do { _Pragma("unroll") for (int m = 0; m < 4; ++m) _Pragma("unroll") for (int k = 0; k < 2; ++k) dst[m][k] = *(const PG8_LAS bf16x8*)(lds + PG8_SA(b, h) + aoff + m * 2048 + k * 1024); } while (0)
; #define PG8_LDB(dst, b, h) do { _Pragma("unroll") for (int n = 0; n < 2; ++n) _Pragma("unroll") for (int k = 0; k < 2; ++k) dst[n][k] = *(const PG8_LAS bf16x8*)(lds + PG8_SB(b, h) + boff + n * 2048 + k * 1024); } while (0)
; #define PG8_MMA(ai, bj, At, Bt) do { __builtin_amdgcn_s_setprio(1); _Pragma("unroll") for (int m = 0; m < 4; ++m) _Pragma("unroll") for (int n = 0; n < 2; ++n) _Pragma("unroll") for (int k = 0; k < 2; ++k) \
;         acc[ai][bj][m][n] = __builtin_amdgcn_mfma_f32_16x16x32_bf16(Bt[n][k], At[m][k], acc[ai][bj][m][n], 0, 0, 0); __builtin_amdgcn_s_setprio(0); } while (0)
; #define PG8_WAIT_V(n) asm volatile("s_waitcnt vmcnt(" #n ")" ::: "memory")
; template <class Epi, class Sched, bool ALIGN_EPI>
; __device__ __forceinline__ void gemm_phase(PG8_LAS unsigned char* lds, const Gemm g, const Sched& S, const Epi& E) {
;     ...
;             PG8_LDB(B0, 0, 0); PG8_LDB(B1, 0, 1); PG8_SCHED; PG8_LDA(At, 0, 0); PG8_STAGE(PG8_SA(1, 1), a1 + hstepA, voffA);
;             PG8_WAIT_V(8); PG8_WAIT_L(0); PG8_BAR; PG8_MMA(0, 0, At, B0); PG8_MMA(0, 1, At, B1); PG8_BAR; PG8_SCHED;
;             PG8_LDA(At, 0, 1); PG8_STAGE(PG8_SB(0, 0), b2, voffB); PG8_STAGE(PG8_SB(0, 1), b2 + hstepB, voffB); PG8_STAGE(PG8_SA(0, 0), a2, voffA);
;             PG8_WAIT_V(8); PG8_WAIT_L(0); PG8_BAR; PG8_MMA(1, 0, At, B0); PG8_MMA(1, 1, At, B1); PG8_BAR; PG8_SCHED;
;             PG8_LDB(B0, 1, 0); PG8_LDB(B1, 1, 1); PG8_SCHED; PG8_LDA(At, 1, 0); PG8_STAGE(PG8_SA(0, 1), a2 + hstepA, voffA);
;             PG8_WAIT_V(8); PG8_WAIT_L(0); PG8_BAR; PG8_MMA(0, 0, At, B0); PG8_MMA(0, 1, At, B1); PG8_BAR; PG8_SCHED;
;             PG8_LDA(At, 1, 1); PG8_STAGE(PG8_SB(1, 0), b3, voffB); PG8_STAGE(PG8_SB(1, 1), b3 + hstepB, voffB); PG8_STAGE(PG8_SA(1, 0), a3, voffA);
;             PG8_WAIT_V(8); PG8_WAIT_L(0); PG8_BAR; PG8_MMA(1, 0, At, B0); PG8_MMA(1, 1, At, B1); PG8_BAR; PG8_SCHED;
.Lp9k_A_first:
	s_add_u32 s28, s28, 0x80
	s_addc_u32 s29, s29, 0
	ds_read_b128 v[194:197], v157 offset:0
	ds_read_b128 v[198:201], v157 offset:1024
	s_add_i32 m0, s60, 0x18000
	ds_read_b128 v[202:205], v157 offset:2048
	global_load_lds_dwordx4 v132, s[28:29]
	ds_read_b128 v[206:209], v157 offset:3072
	ds_read_b128 v[210:213], v157 offset:4096
	s_add_i32 m0, s60, 0x1a000
	ds_read_b128 v[214:217], v157 offset:5120
	global_load_lds_dwordx4 v136, s[28:29]
	ds_read_b128 v[218:221], v157 offset:6144
	ds_read_b128 v[222:225], v157 offset:7168
	s_add_u32 s30, s28, 0x58000
	s_addc_u32 s31, s29, 0
	s_add_i32 m0, s60, 0x19000
	ds_read_b128 v[158:161], v155 offset:0
	global_load_lds_dwordx4 v132, s[30:31]
	ds_read_b128 v[162:165], v155 offset:1024
	ds_read_b128 v[166:169], v155 offset:2048
	s_add_i32 m0, s60, 0x1b000
	ds_read_b128 v[174:177], v155 offset:3072
	global_load_lds_dwordx4 v136, s[30:31]
	ds_read_b128 v[178:181], v155 offset:16384
	ds_read_b128 v[182:185], v155 offset:17408
	s_add_u32 s30, s28, 0x160000
	s_addc_u32 s31, s29, 0
	s_add_i32 m0, s60, 0x1c000
	ds_read_b128 v[186:189], v155 offset:18432
	global_load_lds_dwordx4 v132, s[30:31]
	ds_read_b128 v[190:193], v155 offset:19456
	ds_read_b128 v[226:229], v157 offset:16384
	s_add_i32 m0, s60, 0x1e000
	ds_read_b128 v[230:233], v157 offset:17408
	global_load_lds_dwordx4 v136, s[30:31]
	ds_read_b128 v[234:237], v157 offset:18432
	ds_read_b128 v[238:241], v157 offset:19456
	s_add_u32 s30, s28, 0x1b8000
	s_addc_u32 s31, s29, 0
	s_add_i32 m0, s60, 0x1d000
	ds_read_b128 v[242:245], v157 offset:20480
	global_load_lds_dwordx4 v132, s[30:31]
	ds_read_b128 v[246:249], v157 offset:21504
	ds_read_b128 v[250:253], v157 offset:22528
	s_add_i32 m0, s60, 0x1f000
	ds_read_b128 v[142:145], v157 offset:23552
	global_load_lds_dwordx4 v136, s[30:31]
	s_add_u32 s28, s28, 0x80
	s_addc_u32 s29, s29, 0
.Lp9k_A_entry:
	s_waitcnt vmcnt(8) lgkmcnt(0)
	s_barrier
	v_mfma_f32_16x16x32_bf16 v[126:129], v[158:161], v[194:197], 0
	v_mfma_f32_16x16x32_bf16 v[126:129], v[162:165], v[198:201], v[126:129]
	v_mfma_f32_16x16x32_bf16 v[122:125], v[174:177], v[198:201], 0
	v_mfma_f32_16x16x32_bf16 v[122:125], v[166:169], v[194:197], v[122:125]
	v_mfma_f32_16x16x32_bf16 v[114:117], v[178:181], v[194:197], 0
	v_mfma_f32_16x16x32_bf16 v[114:117], v[182:185], v[198:201], v[114:117]
	v_mfma_f32_16x16x32_bf16 v[106:109], v[190:193], v[198:201], 0
	v_mfma_f32_16x16x32_bf16 v[106:109], v[186:189], v[194:197], v[106:109]
	v_mfma_f32_16x16x32_bf16 v[90:93], v[186:189], v[202:205], 0
	v_mfma_f32_16x16x32_bf16 v[90:93], v[190:193], v[206:209], v[90:93]
	v_mfma_f32_16x16x32_bf16 v[98:101], v[182:185], v[206:209], 0
	v_mfma_f32_16x16x32_bf16 v[98:101], v[178:181], v[202:205], v[98:101]
	v_mfma_f32_16x16x32_bf16 v[110:113], v[166:169], v[202:205], 0
	v_mfma_f32_16x16x32_bf16 v[110:113], v[174:177], v[206:209], v[110:113]
	v_mfma_f32_16x16x32_bf16 v[118:121], v[162:165], v[206:209], 0
	v_mfma_f32_16x16x32_bf16 v[118:121], v[158:161], v[202:205], v[118:121]
	v_mfma_f32_16x16x32_bf16 v[102:105], v[158:161], v[210:213], 0
	v_mfma_f32_16x16x32_bf16 v[102:105], v[162:165], v[214:217], v[102:105]
	v_mfma_f32_16x16x32_bf16 v[94:97], v[174:177], v[214:217], 0
	v_mfma_f32_16x16x32_bf16 v[94:97], v[166:169], v[210:213], v[94:97]
	v_mfma_f32_16x16x32_bf16 v[82:85], v[178:181], v[210:213], 0
	v_mfma_f32_16x16x32_bf16 v[82:85], v[182:185], v[214:217], v[82:85]
	v_mfma_f32_16x16x32_bf16 v[74:77], v[190:193], v[214:217], 0
	v_mfma_f32_16x16x32_bf16 v[74:77], v[186:189], v[210:213], v[74:77]
	v_mfma_f32_16x16x32_bf16 v[66:69], v[186:189], v[218:221], 0
	v_mfma_f32_16x16x32_bf16 v[66:69], v[190:193], v[222:225], v[66:69]
	v_mfma_f32_16x16x32_bf16 v[70:73], v[182:185], v[222:225], 0
	v_mfma_f32_16x16x32_bf16 v[70:73], v[178:181], v[218:221], v[70:73]
	v_mfma_f32_16x16x32_bf16 v[78:81], v[166:169], v[218:221], 0
	v_mfma_f32_16x16x32_bf16 v[78:81], v[174:177], v[222:225], v[78:81]
	v_mfma_f32_16x16x32_bf16 v[86:89], v[162:165], v[222:225], 0
	v_mfma_f32_16x16x32_bf16 v[86:89], v[158:161], v[218:221], v[86:89]
	v_mfma_f32_16x16x32_bf16 v[62:65], v[158:161], v[226:229], 0
	v_mfma_f32_16x16x32_bf16 v[62:65], v[162:165], v[230:233], v[62:65]
	v_mfma_f32_16x16x32_bf16 v[58:61], v[174:177], v[230:233], 0
	v_mfma_f32_16x16x32_bf16 v[58:61], v[166:169], v[226:229], v[58:61]
	v_mfma_f32_16x16x32_bf16 v[50:53], v[178:181], v[226:229], 0
	v_mfma_f32_16x16x32_bf16 v[50:53], v[182:185], v[230:233], v[50:53]
	v_mfma_f32_16x16x32_bf16 v[42:45], v[190:193], v[230:233], 0
	v_mfma_f32_16x16x32_bf16 v[42:45], v[186:189], v[226:229], v[42:45]
	v_mfma_f32_16x16x32_bf16 v[26:29], v[186:189], v[234:237], 0
	v_mfma_f32_16x16x32_bf16 v[26:29], v[190:193], v[238:241], v[26:29]
	v_mfma_f32_16x16x32_bf16 v[34:37], v[182:185], v[238:241], 0
	v_mfma_f32_16x16x32_bf16 v[34:37], v[178:181], v[234:237], v[34:37]
	v_mfma_f32_16x16x32_bf16 v[46:49], v[166:169], v[234:237], 0
	v_mfma_f32_16x16x32_bf16 v[46:49], v[174:177], v[238:241], v[46:49]
	v_mfma_f32_16x16x32_bf16 v[54:57], v[162:165], v[238:241], 0
	v_mfma_f32_16x16x32_bf16 v[54:57], v[158:161], v[234:237], v[54:57]
	v_mfma_f32_16x16x32_bf16 v[38:41], v[158:161], v[242:245], 0
	v_mfma_f32_16x16x32_bf16 v[38:41], v[162:165], v[246:249], v[38:41]
	v_mfma_f32_16x16x32_bf16 v[30:33], v[174:177], v[246:249], 0
	v_mfma_f32_16x16x32_bf16 v[30:33], v[166:169], v[242:245], v[30:33]
	v_mfma_f32_16x16x32_bf16 v[18:21], v[178:181], v[242:245], 0
	v_mfma_f32_16x16x32_bf16 v[18:21], v[182:185], v[246:249], v[18:21]
	v_mfma_f32_16x16x32_bf16 v[10:13], v[190:193], v[246:249], 0
	v_mfma_f32_16x16x32_bf16 v[10:13], v[186:189], v[242:245], v[10:13]
	v_mfma_f32_16x16x32_bf16 v[2:5], v[186:189], v[250:253], 0
	v_mfma_f32_16x16x32_bf16 v[2:5], v[190:193], v[142:145], v[2:5]
	v_mfma_f32_16x16x32_bf16 v[6:9], v[182:185], v[142:145], 0
	v_mfma_f32_16x16x32_bf16 v[6:9], v[178:181], v[250:253], v[6:9]
	v_mfma_f32_16x16x32_bf16 v[14:17], v[166:169], v[250:253], 0
	v_mfma_f32_16x16x32_bf16 v[14:17], v[174:177], v[142:145], v[14:17]
	v_mfma_f32_16x16x32_bf16 v[22:25], v[162:165], v[142:145], 0
	v_mfma_f32_16x16x32_bf16 v[22:25], v[158:161], v[250:253], v[22:25]
	s_waitcnt vmcnt(0)
	s_barrier
; #define PG8_STAGE(bufoff, gbase, voff) do { _Pragma("unroll") for (int _i = 0; _i < 2; ++_i) \
;         __builtin_amdgcn_global_load_lds((const unsigned*)((const char*)(gbase) + (voff)[_i]), (PG8_LAS unsigned*)(lds + (bufoff) + ldsw + _i * 8192), 16, 0, 0); } while (0)
; #define PG8_LDA(dst, b, h) do { _Pragma("unroll") for (int m = 0; m < 4; ++m) _Pragma("unroll") for (int k = 0; k < 2; ++k) dst[m][k] = *(const PG8_LAS bf16x8*)(lds + PG8_SA(b, h) + aoff + m * 2048 + k * 1024); } while (0)
; #define PG8_LDB(dst, b, h) do { _Pragma("unroll") for (int n = 0; n < 2; ++n) _Pragma("unroll") for (int k = 0; k < 2; ++k) dst[n][k] = *(const PG8_LAS bf16x8*)(lds + PG8_SB(b, h) + boff + n * 2048 + k * 1024); } while (0)
; #define PG8_MMA(ai, bj, At, Bt) do { __builtin_amdgcn_s_setprio(1); _Pragma("unroll") for (int m = 0; m < 4; ++m) _Pragma("unroll") for (int n = 0; n < 2; ++n) _Pragma("unroll") for (int k = 0; k < 2; ++k) \
;         acc[ai][bj][m][n] = __builtin_amdgcn_mfma_f32_16x16x32_bf16(Bt[n][k], At[m][k], acc[ai][bj][m][n], 0, 0, 0); __builtin_amdgcn_s_setprio(0); } while (0)
; #define PG8_WAIT_V(n) asm volatile("s_waitcnt vmcnt(" #n ")" ::: "memory")
; #define PG8_WAIT_L(n) asm volatile("s_waitcnt lgkmcnt(" #n ")" ::: "memory")
; #define PG8_BAR __builtin_amdgcn_s_barrier()
; #define PG8_SCHED __builtin_amdgcn_sched_barrier(0)
; template <class Epi, class Sched, bool ALIGN_EPI>
; __device__ __forceinline__ void gemm_phase(PG8_LAS unsigned char* lds, const Gemm g, const Sched& S, const Epi& E) {
;     ...
;             PG8_LDA(At, 0, 1); PG8_STAGE(PG8_SB(0, 0), b2, voffB); PG8_STAGE(PG8_SB(0, 1), b2 + hstepB, voffB); PG8_STAGE(PG8_SA(0, 0), a2, voffA);
;             PG8_WAIT_V(8); PG8_WAIT_L(0); PG8_BAR; PG8_MMA(1, 0, At, B0); PG8_MMA(1, 1, At, B1); PG8_BAR; PG8_SCHED;
;             PG8_LDB(B0, 1, 0); PG8_LDB(B1, 1, 1); PG8_SCHED; PG8_LDA(At, 1, 0); PG8_STAGE(PG8_SA(0, 1), a2 + hstepA, voffA);
;             PG8_WAIT_V(8); PG8_WAIT_L(0); PG8_BAR; PG8_MMA(0, 0, At, B0); PG8_MMA(0, 1, At, B1); PG8_BAR; PG8_SCHED;
;             PG8_LDA(At, 1, 1); PG8_STAGE(PG8_SB(1, 0), b3, voffB); PG8_STAGE(PG8_SB(1, 1), b3 + hstepB, voffB); PG8_STAGE(PG8_SA(1, 0), a3, voffA);
;             PG8_WAIT_V(8); PG8_WAIT_L(0); PG8_BAR; PG8_MMA(1, 0, At, B0); PG8_MMA(1, 1, At, B1); PG8_BAR; PG8_SCHED;
	ds_read_b128 v[194:197], v157 offset:32768
	ds_read_b128 v[198:201], v157 offset:33792
	s_cmp_eq_u32 s57, 43
	s_cselect_b32 s28, s58, s28
	s_cselect_b32 s29, s59, s29
	s_add_i32 m0, s60, 0x10000
	ds_read_b128 v[202:205], v157 offset:34816
	global_load_lds_dwordx4 v132, s[28:29]
	ds_read_b128 v[206:209], v157 offset:35840
	ds_read_b128 v[210:213], v157 offset:36864
	s_add_i32 m0, s60, 0x12000
	ds_read_b128 v[214:217], v157 offset:37888
	global_load_lds_dwordx4 v136, s[28:29]
	ds_read_b128 v[218:221], v157 offset:38912
	ds_read_b128 v[222:225], v157 offset:39936
	s_add_u32 s30, s28, 0x58000
	s_addc_u32 s31, s29, 0
	s_add_i32 m0, s60, 0x11000
	ds_read_b128 v[158:161], v155 offset:32768
	global_load_lds_dwordx4 v132, s[30:31]
	ds_read_b128 v[162:165], v155 offset:33792
	ds_read_b128 v[166:169], v155 offset:34816
	s_add_i32 m0, s60, 0x13000
	ds_read_b128 v[174:177], v155 offset:35840
	global_load_lds_dwordx4 v136, s[30:31]
	ds_read_b128 v[178:181], v155 offset:49152
	ds_read_b128 v[182:185], v155 offset:50176
	s_add_u32 s30, s28, 0x160000
	s_addc_u32 s31, s29, 0
	s_add_i32 m0, s60, 0x14000
	ds_read_b128 v[186:189], v155 offset:51200
	global_load_lds_dwordx4 v132, s[30:31]
	ds_read_b128 v[190:193], v155 offset:52224
	ds_read_b128 v[226:229], v157 offset:49152
	s_add_i32 m0, s60, 0x16000
	ds_read_b128 v[230:233], v157 offset:50176
	global_load_lds_dwordx4 v136, s[30:31]
	ds_read_b128 v[234:237], v157 offset:51200
	ds_read_b128 v[238:241], v157 offset:52224
	s_add_u32 s30, s28, 0x1b8000
	s_addc_u32 s31, s29, 0
	s_add_i32 m0, s60, 0x15000
	ds_read_b128 v[242:245], v157 offset:53248
	global_load_lds_dwordx4 v132, s[30:31]
	ds_read_b128 v[246:249], v157 offset:54272
	ds_read_b128 v[250:253], v157 offset:55296
	s_add_i32 m0, s60, 0x17000
	ds_read_b128 v[142:145], v157 offset:56320
	global_load_lds_dwordx4 v136, s[30:31]
	s_add_u32 s28, s28, 0x80
	s_addc_u32 s29, s29, 0
	s_waitcnt vmcnt(8) lgkmcnt(0)
	s_barrier
	v_mfma_f32_16x16x32_bf16 v[126:129], v[158:161], v[194:197], v[126:129]
	v_mfma_f32_16x16x32_bf16 v[126:129], v[162:165], v[198:201], v[126:129]
	v_mfma_f32_16x16x32_bf16 v[122:125], v[174:177], v[198:201], v[122:125]
	v_mfma_f32_16x16x32_bf16 v[122:125], v[166:169], v[194:197], v[122:125]
	v_mfma_f32_16x16x32_bf16 v[114:117], v[178:181], v[194:197], v[114:117]
	v_mfma_f32_16x16x32_bf16 v[114:117], v[182:185], v[198:201], v[114:117]
	v_mfma_f32_16x16x32_bf16 v[106:109], v[190:193], v[198:201], v[106:109]
	v_mfma_f32_16x16x32_bf16 v[106:109], v[186:189], v[194:197], v[106:109]
	v_mfma_f32_16x16x32_bf16 v[90:93], v[186:189], v[202:205], v[90:93]
	v_mfma_f32_16x16x32_bf16 v[90:93], v[190:193], v[206:209], v[90:93]
	v_mfma_f32_16x16x32_bf16 v[98:101], v[182:185], v[206:209], v[98:101]
	v_mfma_f32_16x16x32_bf16 v[98:101], v[178:181], v[202:205], v[98:101]
	v_mfma_f32_16x16x32_bf16 v[110:113], v[166:169], v[202:205], v[110:113]
	v_mfma_f32_16x16x32_bf16 v[110:113], v[174:177], v[206:209], v[110:113]
	v_mfma_f32_16x16x32_bf16 v[118:121], v[162:165], v[206:209], v[118:121]
	v_mfma_f32_16x16x32_bf16 v[118:121], v[158:161], v[202:205], v[118:121]
	v_mfma_f32_16x16x32_bf16 v[102:105], v[158:161], v[210:213], v[102:105]
	v_mfma_f32_16x16x32_bf16 v[102:105], v[162:165], v[214:217], v[102:105]
	v_mfma_f32_16x16x32_bf16 v[94:97], v[174:177], v[214:217], v[94:97]
	v_mfma_f32_16x16x32_bf16 v[94:97], v[166:169], v[210:213], v[94:97]
	v_mfma_f32_16x16x32_bf16 v[82:85], v[178:181], v[210:213], v[82:85]
	v_mfma_f32_16x16x32_bf16 v[82:85], v[182:185], v[214:217], v[82:85]
	v_mfma_f32_16x16x32_bf16 v[74:77], v[190:193], v[214:217], v[74:77]
	v_mfma_f32_16x16x32_bf16 v[74:77], v[186:189], v[210:213], v[74:77]
	v_mfma_f32_16x16x32_bf16 v[66:69], v[186:189], v[218:221], v[66:69]
	v_mfma_f32_16x16x32_bf16 v[66:69], v[190:193], v[222:225], v[66:69]
	v_mfma_f32_16x16x32_bf16 v[70:73], v[182:185], v[222:225], v[70:73]
	v_mfma_f32_16x16x32_bf16 v[70:73], v[178:181], v[218:221], v[70:73]
	v_mfma_f32_16x16x32_bf16 v[78:81], v[166:169], v[218:221], v[78:81]
	v_mfma_f32_16x16x32_bf16 v[78:81], v[174:177], v[222:225], v[78:81]
	v_mfma_f32_16x16x32_bf16 v[86:89], v[162:165], v[222:225], v[86:89]
	v_mfma_f32_16x16x32_bf16 v[86:89], v[158:161], v[218:221], v[86:89]
	v_mfma_f32_16x16x32_bf16 v[62:65], v[158:161], v[226:229], v[62:65]
	v_mfma_f32_16x16x32_bf16 v[62:65], v[162:165], v[230:233], v[62:65]
	v_mfma_f32_16x16x32_bf16 v[58:61], v[174:177], v[230:233], v[58:61]
	v_mfma_f32_16x16x32_bf16 v[58:61], v[166:169], v[226:229], v[58:61]
	v_mfma_f32_16x16x32_bf16 v[50:53], v[178:181], v[226:229], v[50:53]
	v_mfma_f32_16x16x32_bf16 v[50:53], v[182:185], v[230:233], v[50:53]
	v_mfma_f32_16x16x32_bf16 v[42:45], v[190:193], v[230:233], v[42:45]
	v_mfma_f32_16x16x32_bf16 v[42:45], v[186:189], v[226:229], v[42:45]
	v_mfma_f32_16x16x32_bf16 v[26:29], v[186:189], v[234:237], v[26:29]
	v_mfma_f32_16x16x32_bf16 v[26:29], v[190:193], v[238:241], v[26:29]
	v_mfma_f32_16x16x32_bf16 v[34:37], v[182:185], v[238:241], v[34:37]
	v_mfma_f32_16x16x32_bf16 v[34:37], v[178:181], v[234:237], v[34:37]
	v_mfma_f32_16x16x32_bf16 v[46:49], v[166:169], v[234:237], v[46:49]
	v_mfma_f32_16x16x32_bf16 v[46:49], v[174:177], v[238:241], v[46:49]
	v_mfma_f32_16x16x32_bf16 v[54:57], v[162:165], v[238:241], v[54:57]
	v_mfma_f32_16x16x32_bf16 v[54:57], v[158:161], v[234:237], v[54:57]
	v_mfma_f32_16x16x32_bf16 v[38:41], v[158:161], v[242:245], v[38:41]
	v_mfma_f32_16x16x32_bf16 v[38:41], v[162:165], v[246:249], v[38:41]
	v_mfma_f32_16x16x32_bf16 v[30:33], v[174:177], v[246:249], v[30:33]
	v_mfma_f32_16x16x32_bf16 v[30:33], v[166:169], v[242:245], v[30:33]
	v_mfma_f32_16x16x32_bf16 v[18:21], v[178:181], v[242:245], v[18:21]
	v_mfma_f32_16x16x32_bf16 v[18:21], v[182:185], v[246:249], v[18:21]
	v_mfma_f32_16x16x32_bf16 v[10:13], v[190:193], v[246:249], v[10:13]
	v_mfma_f32_16x16x32_bf16 v[10:13], v[186:189], v[242:245], v[10:13]
	v_mfma_f32_16x16x32_bf16 v[2:5], v[186:189], v[250:253], v[2:5]
	v_mfma_f32_16x16x32_bf16 v[2:5], v[190:193], v[142:145], v[2:5]
	v_mfma_f32_16x16x32_bf16 v[6:9], v[182:185], v[142:145], v[6:9]
	v_mfma_f32_16x16x32_bf16 v[6:9], v[178:181], v[250:253], v[6:9]
	v_mfma_f32_16x16x32_bf16 v[14:17], v[166:169], v[250:253], v[14:17]
	v_mfma_f32_16x16x32_bf16 v[14:17], v[174:177], v[142:145], v[14:17]
	v_mfma_f32_16x16x32_bf16 v[22:25], v[162:165], v[142:145], v[22:25]
	v_mfma_f32_16x16x32_bf16 v[22:25], v[158:161], v[250:253], v[22:25]
	s_waitcnt vmcnt(0)
	s_barrier
	s_add_i32 s57, s57, 1
; #define PG8_STAGE(bufoff, gbase, voff) do { _Pragma("unroll") for (int _i = 0; _i < 2; ++_i) \
;         __builtin_amdgcn_global_load_lds((const unsigned*)((const char*)(gbase) + (voff)[_i]), (PG8_LAS unsigned*)(lds + (bufoff) + ldsw + _i * 8192), 16, 0, 0); } while (0)
; #define PG8_LDA(dst, b, h) do { _Pragma("unroll") for (int m = 0; m < 4; ++m) _Pragma("unroll") for (int k = 0; k < 2; ++k) dst[m][k] = *(const PG8_LAS bf16x8*)(lds + PG8_SA(b, h) + aoff + m * 2048 + k * 1024); } while (0)
; #define PG8_LDB(dst, b, h) do { _Pragma("unroll") for (int n = 0; n < 2; ++n) _Pragma("unroll") for (int k = 0; k < 2; ++k) dst[n][k] = *(const PG8_LAS bf16x8*)(lds + PG8_SB(b, h) + boff + n * 2048 + k * 1024); } while (0)
; #define PG8_MMA(ai, bj, At, Bt) do { __builtin_amdgcn_s_setprio(1); _Pragma("unroll") for (int m = 0; m < 4; ++m) _Pragma("unroll") for (int n = 0; n < 2; ++n) _Pragma("unroll") for (int k = 0; k < 2; ++k) \
;         acc[ai][bj][m][n] = __builtin_amdgcn_mfma_f32_16x16x32_bf16(Bt[n][k], At[m][k], acc[ai][bj][m][n], 0, 0, 0); __builtin_amdgcn_s_setprio(0); } while (0)
; #define PG8_WAIT_V(n) asm volatile("s_waitcnt vmcnt(" #n ")" ::: "memory")
; template <class Epi, class Sched, bool ALIGN_EPI>
; __device__ __forceinline__ void gemm_phase(PG8_LAS unsigned char* lds, const Gemm g, const Sched& S, const Epi& E) {
;     ...
;             PG8_LDB(B0, 0, 0); PG8_LDB(B1, 0, 1); PG8_SCHED; PG8_LDA(At, 0, 0); PG8_STAGE(PG8_SA(1, 1), a1 + hstepA, voffA);
;             PG8_WAIT_V(8); PG8_WAIT_L(0); PG8_BAR; PG8_MMA(0, 0, At, B0); PG8_MMA(0, 1, At, B1); PG8_BAR; PG8_SCHED;
;             PG8_LDA(At, 0, 1); PG8_STAGE(PG8_SB(0, 0), b2, voffB); PG8_STAGE(PG8_SB(0, 1), b2 + hstepB, voffB); PG8_STAGE(PG8_SA(0, 0), a2, voffA);
;             PG8_WAIT_V(8); PG8_WAIT_L(0); PG8_BAR; PG8_MMA(1, 0, At, B0); PG8_MMA(1, 1, At, B1); PG8_BAR; PG8_SCHED;
;             PG8_LDB(B0, 1, 0); PG8_LDB(B1, 1, 1); PG8_SCHED; PG8_LDA(At, 1, 0); PG8_STAGE(PG8_SA(0, 1), a2 + hstepA, voffA);
;             PG8_WAIT_V(8); PG8_WAIT_L(0); PG8_BAR; PG8_MMA(0, 0, At, B0); PG8_MMA(0, 1, At, B1); PG8_BAR; PG8_SCHED;
;             PG8_LDA(At, 1, 1); PG8_STAGE(PG8_SB(1, 0), b3, voffB); PG8_STAGE(PG8_SB(1, 1), b3 + hstepB, voffB); PG8_STAGE(PG8_SA(1, 0), a3, voffA);
;             PG8_WAIT_V(8); PG8_WAIT_L(0); PG8_BAR; PG8_MMA(1, 0, At, B0); PG8_MMA(1, 1, At, B1); PG8_BAR; PG8_SCHED;
.Lp9k_A_loop:
	ds_read_b128 v[194:197], v157 offset:0
	ds_read_b128 v[198:201], v157 offset:1024
	s_add_i32 m0, s60, 0x18000
	ds_read_b128 v[202:205], v157 offset:2048
	global_load_lds_dwordx4 v132, s[28:29]
	ds_read_b128 v[206:209], v157 offset:3072
	ds_read_b128 v[210:213], v157 offset:4096
	s_add_i32 m0, s60, 0x1a000
	ds_read_b128 v[214:217], v157 offset:5120
	global_load_lds_dwordx4 v136, s[28:29]
	ds_read_b128 v[218:221], v157 offset:6144
	ds_read_b128 v[222:225], v157 offset:7168
	s_add_u32 s30, s28, 0x58000
	s_addc_u32 s31, s29, 0
	s_add_i32 m0, s60, 0x19000
	ds_read_b128 v[158:161], v155 offset:0
	global_load_lds_dwordx4 v132, s[30:31]
	ds_read_b128 v[162:165], v155 offset:1024
	ds_read_b128 v[166:169], v155 offset:2048
	s_add_i32 m0, s60, 0x1b000
	ds_read_b128 v[174:177], v155 offset:3072
	global_load_lds_dwordx4 v136, s[30:31]
	ds_read_b128 v[178:181], v155 offset:16384
	ds_read_b128 v[182:185], v155 offset:17408
	s_add_u32 s30, s28, 0x160000
	s_addc_u32 s31, s29, 0
	s_add_i32 m0, s60, 0x1c000
	ds_read_b128 v[186:189], v155 offset:18432
	global_load_lds_dwordx4 v132, s[30:31]
	ds_read_b128 v[190:193], v155 offset:19456
	ds_read_b128 v[226:229], v157 offset:16384
	s_add_i32 m0, s60, 0x1e000
	ds_read_b128 v[230:233], v157 offset:17408
	global_load_lds_dwordx4 v136, s[30:31]
	ds_read_b128 v[234:237], v157 offset:18432
	ds_read_b128 v[238:241], v157 offset:19456
	s_add_u32 s30, s28, 0x1b8000
	s_addc_u32 s31, s29, 0
	s_add_i32 m0, s60, 0x1d000
	ds_read_b128 v[242:245], v157 offset:20480
	global_load_lds_dwordx4 v132, s[30:31]
	ds_read_b128 v[246:249], v157 offset:21504
	ds_read_b128 v[250:253], v157 offset:22528
	s_add_i32 m0, s60, 0x1f000
	ds_read_b128 v[142:145], v157 offset:23552
	global_load_lds_dwordx4 v136, s[30:31]
	s_add_u32 s28, s28, 0x80
	s_addc_u32 s29, s29, 0
	s_waitcnt vmcnt(8) lgkmcnt(0)
	s_barrier
	v_mfma_f32_16x16x32_bf16 v[126:129], v[158:161], v[194:197], v[126:129]
	v_mfma_f32_16x16x32_bf16 v[126:129], v[162:165], v[198:201], v[126:129]
	v_mfma_f32_16x16x32_bf16 v[122:125], v[174:177], v[198:201], v[122:125]
	v_mfma_f32_16x16x32_bf16 v[122:125], v[166:169], v[194:197], v[122:125]
	v_mfma_f32_16x16x32_bf16 v[114:117], v[178:181], v[194:197], v[114:117]
	v_mfma_f32_16x16x32_bf16 v[114:117], v[182:185], v[198:201], v[114:117]
	v_mfma_f32_16x16x32_bf16 v[106:109], v[190:193], v[198:201], v[106:109]
	v_mfma_f32_16x16x32_bf16 v[106:109], v[186:189], v[194:197], v[106:109]
	v_mfma_f32_16x16x32_bf16 v[90:93], v[186:189], v[202:205], v[90:93]
	v_mfma_f32_16x16x32_bf16 v[90:93], v[190:193], v[206:209], v[90:93]
	v_mfma_f32_16x16x32_bf16 v[98:101], v[182:185], v[206:209], v[98:101]
	v_mfma_f32_16x16x32_bf16 v[98:101], v[178:181], v[202:205], v[98:101]
	v_mfma_f32_16x16x32_bf16 v[110:113], v[166:169], v[202:205], v[110:113]
	v_mfma_f32_16x16x32_bf16 v[110:113], v[174:177], v[206:209], v[110:113]
	v_mfma_f32_16x16x32_bf16 v[118:121], v[162:165], v[206:209], v[118:121]
	v_mfma_f32_16x16x32_bf16 v[118:121], v[158:161], v[202:205], v[118:121]
	v_mfma_f32_16x16x32_bf16 v[102:105], v[158:161], v[210:213], v[102:105]
	v_mfma_f32_16x16x32_bf16 v[102:105], v[162:165], v[214:217], v[102:105]
	v_mfma_f32_16x16x32_bf16 v[94:97], v[174:177], v[214:217], v[94:97]
	v_mfma_f32_16x16x32_bf16 v[94:97], v[166:169], v[210:213], v[94:97]
	v_mfma_f32_16x16x32_bf16 v[82:85], v[178:181], v[210:213], v[82:85]
	v_mfma_f32_16x16x32_bf16 v[82:85], v[182:185], v[214:217], v[82:85]
	v_mfma_f32_16x16x32_bf16 v[74:77], v[190:193], v[214:217], v[74:77]
	v_mfma_f32_16x16x32_bf16 v[74:77], v[186:189], v[210:213], v[74:77]
	v_mfma_f32_16x16x32_bf16 v[66:69], v[186:189], v[218:221], v[66:69]
	v_mfma_f32_16x16x32_bf16 v[66:69], v[190:193], v[222:225], v[66:69]
	v_mfma_f32_16x16x32_bf16 v[70:73], v[182:185], v[222:225], v[70:73]
	v_mfma_f32_16x16x32_bf16 v[70:73], v[178:181], v[218:221], v[70:73]
	v_mfma_f32_16x16x32_bf16 v[78:81], v[166:169], v[218:221], v[78:81]
	v_mfma_f32_16x16x32_bf16 v[78:81], v[174:177], v[222:225], v[78:81]
	v_mfma_f32_16x16x32_bf16 v[86:89], v[162:165], v[222:225], v[86:89]
	v_mfma_f32_16x16x32_bf16 v[86:89], v[158:161], v[218:221], v[86:89]
	v_mfma_f32_16x16x32_bf16 v[62:65], v[158:161], v[226:229], v[62:65]
	v_mfma_f32_16x16x32_bf16 v[62:65], v[162:165], v[230:233], v[62:65]
	v_mfma_f32_16x16x32_bf16 v[58:61], v[174:177], v[230:233], v[58:61]
	v_mfma_f32_16x16x32_bf16 v[58:61], v[166:169], v[226:229], v[58:61]
	v_mfma_f32_16x16x32_bf16 v[50:53], v[178:181], v[226:229], v[50:53]
	v_mfma_f32_16x16x32_bf16 v[50:53], v[182:185], v[230:233], v[50:53]
	v_mfma_f32_16x16x32_bf16 v[42:45], v[190:193], v[230:233], v[42:45]
	v_mfma_f32_16x16x32_bf16 v[42:45], v[186:189], v[226:229], v[42:45]
	v_mfma_f32_16x16x32_bf16 v[26:29], v[186:189], v[234:237], v[26:29]
	v_mfma_f32_16x16x32_bf16 v[26:29], v[190:193], v[238:241], v[26:29]
	v_mfma_f32_16x16x32_bf16 v[34:37], v[182:185], v[238:241], v[34:37]
	v_mfma_f32_16x16x32_bf16 v[34:37], v[178:181], v[234:237], v[34:37]
	v_mfma_f32_16x16x32_bf16 v[46:49], v[166:169], v[234:237], v[46:49]
	v_mfma_f32_16x16x32_bf16 v[46:49], v[174:177], v[238:241], v[46:49]
	v_mfma_f32_16x16x32_bf16 v[54:57], v[162:165], v[238:241], v[54:57]
	v_mfma_f32_16x16x32_bf16 v[54:57], v[158:161], v[234:237], v[54:57]
	v_mfma_f32_16x16x32_bf16 v[38:41], v[158:161], v[242:245], v[38:41]
	v_mfma_f32_16x16x32_bf16 v[38:41], v[162:165], v[246:249], v[38:41]
	v_mfma_f32_16x16x32_bf16 v[30:33], v[174:177], v[246:249], v[30:33]
	v_mfma_f32_16x16x32_bf16 v[30:33], v[166:169], v[242:245], v[30:33]
	v_mfma_f32_16x16x32_bf16 v[18:21], v[178:181], v[242:245], v[18:21]
	v_mfma_f32_16x16x32_bf16 v[18:21], v[182:185], v[246:249], v[18:21]
	v_mfma_f32_16x16x32_bf16 v[10:13], v[190:193], v[246:249], v[10:13]
	v_mfma_f32_16x16x32_bf16 v[10:13], v[186:189], v[242:245], v[10:13]
	v_mfma_f32_16x16x32_bf16 v[2:5], v[186:189], v[250:253], v[2:5]
	v_mfma_f32_16x16x32_bf16 v[2:5], v[190:193], v[142:145], v[2:5]
	v_mfma_f32_16x16x32_bf16 v[6:9], v[182:185], v[142:145], v[6:9]
	v_mfma_f32_16x16x32_bf16 v[6:9], v[178:181], v[250:253], v[6:9]
	v_mfma_f32_16x16x32_bf16 v[14:17], v[166:169], v[250:253], v[14:17]
	v_mfma_f32_16x16x32_bf16 v[14:17], v[174:177], v[142:145], v[14:17]
	v_mfma_f32_16x16x32_bf16 v[22:25], v[162:165], v[142:145], v[22:25]
	v_mfma_f32_16x16x32_bf16 v[22:25], v[158:161], v[250:253], v[22:25]
	s_waitcnt vmcnt(0)
	s_barrier
; #define PG8_STAGE(bufoff, gbase, voff) do { _Pragma("unroll") for (int _i = 0; _i < 2; ++_i) \
;         __builtin_amdgcn_global_load_lds((const unsigned*)((const char*)(gbase) + (voff)[_i]), (PG8_LAS unsigned*)(lds + (bufoff) + ldsw + _i * 8192), 16, 0, 0); } while (0)
; #define PG8_LDA(dst, b, h) do { _Pragma("unroll") for (int m = 0; m < 4; ++m) _Pragma("unroll") for (int k = 0; k < 2; ++k) dst[m][k] = *(const PG8_LAS bf16x8*)(lds + PG8_SA(b, h) + aoff + m * 2048 + k * 1024); } while (0)
; #define PG8_LDB(dst, b, h) do { _Pragma("unroll") for (int n = 0; n < 2; ++n) _Pragma("unroll") for (int k = 0; k < 2; ++k) dst[n][k] = *(const PG8_LAS bf16x8*)(lds + PG8_SB(b, h) + boff + n * 2048 + k * 1024); } while (0)
; #define PG8_MMA(ai, bj, At, Bt) do { __builtin_amdgcn_s_setprio(1); _Pragma("unroll") for (int m = 0; m < 4; ++m) _Pragma("unroll") for (int n = 0; n < 2; ++n) _Pragma("unroll") for (int k = 0; k < 2; ++k) \
;         acc[ai][bj][m][n] = __builtin_amdgcn_mfma_f32_16x16x32_bf16(Bt[n][k], At[m][k], acc[ai][bj][m][n], 0, 0, 0); __builtin_amdgcn_s_setprio(0); } while (0)
; #define PG8_WAIT_V(n) asm volatile("s_waitcnt vmcnt(" #n ")" ::: "memory")
; #define PG8_WAIT_L(n) asm volatile("s_waitcnt lgkmcnt(" #n ")" ::: "memory")
; #define PG8_BAR __builtin_amdgcn_s_barrier()
; #define PG8_SCHED __builtin_amdgcn_sched_barrier(0)
; template <class Epi, class Sched, bool ALIGN_EPI>
; __device__ __forceinline__ void gemm_phase(PG8_LAS unsigned char* lds, const Gemm g, const Sched& S, const Epi& E) {
;     ...
;             PG8_LDA(At, 0, 1); PG8_STAGE(PG8_SB(0, 0), b2, voffB); PG8_STAGE(PG8_SB(0, 1), b2 + hstepB, voffB); PG8_STAGE(PG8_SA(0, 0), a2, voffA);
;             PG8_WAIT_V(8); PG8_WAIT_L(0); PG8_BAR; PG8_MMA(1, 0, At, B0); PG8_MMA(1, 1, At, B1); PG8_BAR; PG8_SCHED;
;             PG8_LDB(B0, 1, 0); PG8_LDB(B1, 1, 1); PG8_SCHED; PG8_LDA(At, 1, 0); PG8_STAGE(PG8_SA(0, 1), a2 + hstepA, voffA);
;             PG8_WAIT_V(8); PG8_WAIT_L(0); PG8_BAR; PG8_MMA(0, 0, At, B0); PG8_MMA(0, 1, At, B1); PG8_BAR; PG8_SCHED;
;             PG8_LDA(At, 1, 1); PG8_STAGE(PG8_SB(1, 0), b3, voffB); PG8_STAGE(PG8_SB(1, 1), b3 + hstepB, voffB); PG8_STAGE(PG8_SA(1, 0), a3, voffA);
;             PG8_WAIT_V(8); PG8_WAIT_L(0); PG8_BAR; PG8_MMA(1, 0, At, B0); PG8_MMA(1, 1, At, B1); PG8_BAR; PG8_SCHED;
	ds_read_b128 v[194:197], v157 offset:32768
	ds_read_b128 v[198:201], v157 offset:33792
	s_cmp_eq_u32 s57, 43
	s_cselect_b32 s28, s58, s28
	s_cselect_b32 s29, s59, s29
	s_add_i32 m0, s60, 0x10000
	ds_read_b128 v[202:205], v157 offset:34816
	global_load_lds_dwordx4 v132, s[28:29]
	ds_read_b128 v[206:209], v157 offset:35840
	ds_read_b128 v[210:213], v157 offset:36864
	s_add_i32 m0, s60, 0x12000
	ds_read_b128 v[214:217], v157 offset:37888
	global_load_lds_dwordx4 v136, s[28:29]
	ds_read_b128 v[218:221], v157 offset:38912
	ds_read_b128 v[222:225], v157 offset:39936
	s_add_u32 s30, s28, 0x58000
	s_addc_u32 s31, s29, 0
	s_add_i32 m0, s60, 0x11000
	ds_read_b128 v[158:161], v155 offset:32768
	global_load_lds_dwordx4 v132, s[30:31]
	ds_read_b128 v[162:165], v155 offset:33792
	ds_read_b128 v[166:169], v155 offset:34816
	s_add_i32 m0, s60, 0x13000
	ds_read_b128 v[174:177], v155 offset:35840
	global_load_lds_dwordx4 v136, s[30:31]
	ds_read_b128 v[178:181], v155 offset:49152
	ds_read_b128 v[182:185], v155 offset:50176
	s_add_u32 s30, s28, 0x160000
	s_addc_u32 s31, s29, 0
	s_add_i32 m0, s60, 0x14000
	ds_read_b128 v[186:189], v155 offset:51200
	global_load_lds_dwordx4 v132, s[30:31]
	ds_read_b128 v[190:193], v155 offset:52224
	ds_read_b128 v[226:229], v157 offset:49152
	s_add_i32 m0, s60, 0x16000
	ds_read_b128 v[230:233], v157 offset:50176
	global_load_lds_dwordx4 v136, s[30:31]
	ds_read_b128 v[234:237], v157 offset:51200
	ds_read_b128 v[238:241], v157 offset:52224
	s_add_u32 s30, s28, 0x1b8000
	s_addc_u32 s31, s29, 0
	s_add_i32 m0, s60, 0x15000
	ds_read_b128 v[242:245], v157 offset:53248
	global_load_lds_dwordx4 v132, s[30:31]
	ds_read_b128 v[246:249], v157 offset:54272
	ds_read_b128 v[250:253], v157 offset:55296
	s_add_i32 m0, s60, 0x17000
	ds_read_b128 v[142:145], v157 offset:56320
	global_load_lds_dwordx4 v136, s[30:31]
	s_add_u32 s28, s28, 0x80
	s_addc_u32 s29, s29, 0
	s_waitcnt vmcnt(8) lgkmcnt(0)
	s_barrier
; #define PG8_STAGE(bufoff, gbase, voff) do { _Pragma("unroll") for (int _i = 0; _i < 2; ++_i) \
;         __builtin_amdgcn_global_load_lds((const unsigned*)((const char*)(gbase) + (voff)[_i]), (PG8_LAS unsigned*)(lds + (bufoff) + ldsw + _i * 8192), 16, 0, 0); } while (0)
; #define PG8_LDA(dst, b, h) do { _Pragma("unroll") for (int m = 0; m < 4; ++m) _Pragma("unroll") for (int k = 0; k < 2; ++k) dst[m][k] = *(const PG8_LAS bf16x8*)(lds + PG8_SA(b, h) + aoff + m * 2048 + k * 1024); } while (0)
; #define PG8_MMA(ai, bj, At, Bt) do { __builtin_amdgcn_s_setprio(1); _Pragma("unroll") for (int m = 0; m < 4; ++m) _Pragma("unroll") for (int n = 0; n < 2; ++n) _Pragma("unroll") for (int k = 0; k < 2; ++k) \
;         acc[ai][bj][m][n] = __builtin_amdgcn_mfma_f32_16x16x32_bf16(Bt[n][k], At[m][k], acc[ai][bj][m][n], 0, 0, 0); __builtin_amdgcn_s_setprio(0); } while (0)
; #define PG8_WAIT_V(n) asm volatile("s_waitcnt vmcnt(" #n ")" ::: "memory")
; #define PG8_WAIT_L(n) asm volatile("s_waitcnt lgkmcnt(" #n ")" ::: "memory")
; #define PG8_BAR __builtin_amdgcn_s_barrier()
; #define PG8_SCHED __builtin_amdgcn_sched_barrier(0)
; template <class Epi, class Sched, bool ALIGN_EPI>
; __device__ __forceinline__ void gemm_phase(PG8_LAS unsigned char* lds, const Gemm g, const Sched& S, const Epi& E) {
;     ...
;             PG8_WAIT_V(8); PG8_WAIT_L(0); PG8_BAR; PG8_MMA(0, 0, At, B0); PG8_MMA(0, 1, At, B1); PG8_BAR; PG8_SCHED;
;             PG8_LDA(At, 1, 1); PG8_STAGE(PG8_SB(1, 0), b3, voffB); PG8_STAGE(PG8_SB(1, 1), b3 + hstepB, voffB); PG8_STAGE(PG8_SA(1, 0), a3, voffA);
;             PG8_WAIT_V(8); PG8_WAIT_L(0); PG8_BAR; PG8_MMA(1, 0, At, B0); PG8_MMA(1, 1, At, B1); PG8_BAR; PG8_SCHED;
;         }
	v_mfma_f32_16x16x32_bf16 v[126:129], v[158:161], v[194:197], v[126:129]
	v_mfma_f32_16x16x32_bf16 v[126:129], v[162:165], v[198:201], v[126:129]
	v_mfma_f32_16x16x32_bf16 v[122:125], v[174:177], v[198:201], v[122:125]
	v_mfma_f32_16x16x32_bf16 v[122:125], v[166:169], v[194:197], v[122:125]
	v_mfma_f32_16x16x32_bf16 v[114:117], v[178:181], v[194:197], v[114:117]
	v_mfma_f32_16x16x32_bf16 v[114:117], v[182:185], v[198:201], v[114:117]
	v_mfma_f32_16x16x32_bf16 v[106:109], v[190:193], v[198:201], v[106:109]
	v_mfma_f32_16x16x32_bf16 v[106:109], v[186:189], v[194:197], v[106:109]
	v_mfma_f32_16x16x32_bf16 v[90:93], v[186:189], v[202:205], v[90:93]
	v_mfma_f32_16x16x32_bf16 v[90:93], v[190:193], v[206:209], v[90:93]
	v_mfma_f32_16x16x32_bf16 v[98:101], v[182:185], v[206:209], v[98:101]
	v_mfma_f32_16x16x32_bf16 v[98:101], v[178:181], v[202:205], v[98:101]
	v_mfma_f32_16x16x32_bf16 v[110:113], v[166:169], v[202:205], v[110:113]
	v_mfma_f32_16x16x32_bf16 v[110:113], v[174:177], v[206:209], v[110:113]
	v_mfma_f32_16x16x32_bf16 v[118:121], v[162:165], v[206:209], v[118:121]
	v_mfma_f32_16x16x32_bf16 v[118:121], v[158:161], v[202:205], v[118:121]
	v_mfma_f32_16x16x32_bf16 v[102:105], v[158:161], v[210:213], v[102:105]
	v_mfma_f32_16x16x32_bf16 v[102:105], v[162:165], v[214:217], v[102:105]
	v_mfma_f32_16x16x32_bf16 v[94:97], v[174:177], v[214:217], v[94:97]
	v_mfma_f32_16x16x32_bf16 v[94:97], v[166:169], v[210:213], v[94:97]
	v_mfma_f32_16x16x32_bf16 v[82:85], v[178:181], v[210:213], v[82:85]
	v_mfma_f32_16x16x32_bf16 v[82:85], v[182:185], v[214:217], v[82:85]
	v_mfma_f32_16x16x32_bf16 v[74:77], v[190:193], v[214:217], v[74:77]
	v_mfma_f32_16x16x32_bf16 v[74:77], v[186:189], v[210:213], v[74:77]
	v_mfma_f32_16x16x32_bf16 v[66:69], v[186:189], v[218:221], v[66:69]
	v_mfma_f32_16x16x32_bf16 v[66:69], v[190:193], v[222:225], v[66:69]
	v_mfma_f32_16x16x32_bf16 v[70:73], v[182:185], v[222:225], v[70:73]
	v_mfma_f32_16x16x32_bf16 v[70:73], v[178:181], v[218:221], v[70:73]
	v_mfma_f32_16x16x32_bf16 v[78:81], v[166:169], v[218:221], v[78:81]
	v_mfma_f32_16x16x32_bf16 v[78:81], v[174:177], v[222:225], v[78:81]
	v_mfma_f32_16x16x32_bf16 v[86:89], v[162:165], v[222:225], v[86:89]
	v_mfma_f32_16x16x32_bf16 v[86:89], v[158:161], v[218:221], v[86:89]
	v_mfma_f32_16x16x32_bf16 v[62:65], v[158:161], v[226:229], v[62:65]
	v_mfma_f32_16x16x32_bf16 v[62:65], v[162:165], v[230:233], v[62:65]
	v_mfma_f32_16x16x32_bf16 v[58:61], v[174:177], v[230:233], v[58:61]
	v_mfma_f32_16x16x32_bf16 v[58:61], v[166:169], v[226:229], v[58:61]
	v_mfma_f32_16x16x32_bf16 v[50:53], v[178:181], v[226:229], v[50:53]
	v_mfma_f32_16x16x32_bf16 v[50:53], v[182:185], v[230:233], v[50:53]
	v_mfma_f32_16x16x32_bf16 v[42:45], v[190:193], v[230:233], v[42:45]
	v_mfma_f32_16x16x32_bf16 v[42:45], v[186:189], v[226:229], v[42:45]
	v_mfma_f32_16x16x32_bf16 v[26:29], v[186:189], v[234:237], v[26:29]
	v_mfma_f32_16x16x32_bf16 v[26:29], v[190:193], v[238:241], v[26:29]
	v_mfma_f32_16x16x32_bf16 v[34:37], v[182:185], v[238:241], v[34:37]
	v_mfma_f32_16x16x32_bf16 v[34:37], v[178:181], v[234:237], v[34:37]
	v_mfma_f32_16x16x32_bf16 v[46:49], v[166:169], v[234:237], v[46:49]
	v_mfma_f32_16x16x32_bf16 v[46:49], v[174:177], v[238:241], v[46:49]
	v_mfma_f32_16x16x32_bf16 v[54:57], v[162:165], v[238:241], v[54:57]
	v_mfma_f32_16x16x32_bf16 v[54:57], v[158:161], v[234:237], v[54:57]
	v_mfma_f32_16x16x32_bf16 v[38:41], v[158:161], v[242:245], v[38:41]
	v_mfma_f32_16x16x32_bf16 v[38:41], v[162:165], v[246:249], v[38:41]
	v_mfma_f32_16x16x32_bf16 v[30:33], v[174:177], v[246:249], v[30:33]
	v_mfma_f32_16x16x32_bf16 v[30:33], v[166:169], v[242:245], v[30:33]
	v_mfma_f32_16x16x32_bf16 v[18:21], v[178:181], v[242:245], v[18:21]
	v_mfma_f32_16x16x32_bf16 v[18:21], v[182:185], v[246:249], v[18:21]
	v_mfma_f32_16x16x32_bf16 v[10:13], v[190:193], v[246:249], v[10:13]
	v_mfma_f32_16x16x32_bf16 v[10:13], v[186:189], v[242:245], v[10:13]
	v_mfma_f32_16x16x32_bf16 v[2:5], v[186:189], v[250:253], v[2:5]
	v_mfma_f32_16x16x32_bf16 v[2:5], v[190:193], v[142:145], v[2:5]
	v_mfma_f32_16x16x32_bf16 v[6:9], v[182:185], v[142:145], v[6:9]
	v_mfma_f32_16x16x32_bf16 v[6:9], v[178:181], v[250:253], v[6:9]
	v_mfma_f32_16x16x32_bf16 v[14:17], v[166:169], v[250:253], v[14:17]
	v_mfma_f32_16x16x32_bf16 v[14:17], v[174:177], v[142:145], v[14:17]
	v_mfma_f32_16x16x32_bf16 v[22:25], v[162:165], v[142:145], v[22:25]
	v_mfma_f32_16x16x32_bf16 v[22:25], v[158:161], v[250:253], v[22:25]
	s_waitcnt vmcnt(0)
	s_barrier
	s_add_i32 s57, s57, 1
	s_cmp_lt_u32 s57, 44
	s_cbranch_scc1 .Lp9k_A_loop
	ds_read_b128 v[194:197], v157 offset:0
	ds_read_b128 v[198:201], v157 offset:1024
	s_add_i32 m0, s60, 0x18000
	ds_read_b128 v[202:205], v157 offset:2048
	global_load_lds_dwordx4 v132, s[28:29]
	ds_read_b128 v[206:209], v157 offset:3072
	ds_read_b128 v[210:213], v157 offset:4096
	s_add_i32 m0, s60, 0x1a000
	ds_read_b128 v[214:217], v157 offset:5120
	global_load_lds_dwordx4 v136, s[28:29]
	ds_read_b128 v[218:221], v157 offset:6144
	ds_read_b128 v[222:225], v157 offset:7168
	s_add_u32 s30, s28, 0x58000
	s_addc_u32 s31, s29, 0
	s_add_i32 m0, s60, 0x19000
	ds_read_b128 v[166:169], v155 offset:2048
	global_load_lds_dwordx4 v132, s[30:31]
	ds_read_b128 v[174:177], v155 offset:3072
	ds_read_b128 v[178:181], v155 offset:16384
	s_add_i32 m0, s60, 0x1b000
	ds_read_b128 v[182:185], v155 offset:17408
	global_load_lds_dwordx4 v136, s[30:31]
	ds_read_b128 v[186:189], v155 offset:18432
	ds_read_b128 v[190:193], v155 offset:19456
	s_add_u32 s30, s28, 0x160000
	s_addc_u32 s31, s29, 0
	s_add_i32 m0, s60, 0x1c000
	ds_read_b128 v[226:229], v157 offset:16384
	global_load_lds_dwordx4 v132, s[30:31]
	ds_read_b128 v[230:233], v157 offset:17408
	ds_read_b128 v[234:237], v157 offset:18432
	s_add_i32 m0, s60, 0x1e000
	ds_read_b128 v[238:241], v157 offset:19456
	global_load_lds_dwordx4 v136, s[30:31]
	ds_read_b128 v[242:245], v157 offset:20480
	ds_read_b128 v[246:249], v157 offset:21504
	s_add_u32 s30, s28, 0x1b8000
	s_addc_u32 s31, s29, 0
	s_add_i32 m0, s60, 0x1d000
	ds_read_b128 v[250:253], v157 offset:22528
	global_load_lds_dwordx4 v132, s[30:31]
	s_add_i32 m0, s60, 0x1f000
	s_nop 0
	global_load_lds_dwordx4 v136, s[30:31]
	s_add_u32 s28, s28, 0x80
	s_addc_u32 s29, s29, 0
	s_branch .Lp9k_done

; #define PG8_STAGE(bufoff, gbase, voff) do { _Pragma("unroll") for (int _i = 0; _i < 2; ++_i) \
;         __builtin_amdgcn_global_load_lds((const unsigned*)((const char*)(gbase) + (voff)[_i]), (PG8_LAS unsigned*)(lds + (bufoff) + ldsw + _i * 8192), 16, 0, 0); } while (0)
; #define PG8_LDA(dst, b, h) do { _Pragma("unroll") for (int m = 0; m < 4; ++m) _Pragma("unroll") for (int k = 0; k < 2; ++k) dst[m][k] = *(const PG8_LAS bf16x8*)(lds + PG8_SA(b, h) + aoff + m * 2048 + k * 1024); } while (0)
; #define PG8_LDB(dst, b, h) do { _Pragma("unroll") for (int n = 0; n < 2; ++n) _Pragma("unroll") for (int k = 0; k < 2; ++k) dst[n][k] = *(const PG8_LAS bf16x8*)(lds + PG8_SB(b, h) + boff + n * 2048 + k * 1024); } while (0)
; #define PG8_MMA(ai, bj, At, Bt) do { __builtin_amdgcn_s_setprio(1); _Pragma("unroll") for (int m = 0; m < 4; ++m) _Pragma("unroll") for (int n = 0; n < 2; ++n) _Pragma("unroll") for (int k = 0; k < 2; ++k) \
;         acc[ai][bj][m][n] = __builtin_amdgcn_mfma_f32_16x16x32_bf16(Bt[n][k], At[m][k], acc[ai][bj][m][n], 0, 0, 0); __builtin_amdgcn_s_setprio(0); } while (0)
; #define PG8_WAIT_V(n) asm volatile("s_waitcnt vmcnt(" #n ")" ::: "memory")
; template <class Epi, class Sched, bool ALIGN_EPI>
; __device__ __forceinline__ void gemm_phase(PG8_LAS unsigned char* lds, const Gemm g, const Sched& S, const Epi& E) {
;     ...
;             PG8_LDB(B0, 0, 0); PG8_LDB(B1, 0, 1); PG8_SCHED; PG8_LDA(At, 0, 0); PG8_STAGE(PG8_SA(1, 1), a1 + hstepA, voffA);
;             PG8_WAIT_V(8); PG8_WAIT_L(0); PG8_BAR; PG8_MMA(0, 0, At, B0); PG8_MMA(0, 1, At, B1); PG8_BAR; PG8_SCHED;
;             PG8_LDA(At, 0, 1); PG8_STAGE(PG8_SB(0, 0), b2, voffB); PG8_STAGE(PG8_SB(0, 1), b2 + hstepB, voffB); PG8_STAGE(PG8_SA(0, 0), a2, voffA);
;             PG8_WAIT_V(8); PG8_WAIT_L(0); PG8_BAR; PG8_MMA(1, 0, At, B0); PG8_MMA(1, 1, At, B1); PG8_BAR; PG8_SCHED;
;             PG8_LDB(B0, 1, 0); PG8_LDB(B1, 1, 1); PG8_SCHED; PG8_LDA(At, 1, 0); PG8_STAGE(PG8_SA(0, 1), a2 + hstepA, voffA);
;             PG8_WAIT_V(8); PG8_WAIT_L(0); PG8_BAR; PG8_MMA(0, 0, At, B0); PG8_MMA(0, 1, At, B1); PG8_BAR; PG8_SCHED;
;             PG8_LDA(At, 1, 1); PG8_STAGE(PG8_SB(1, 0), b3, voffB); PG8_STAGE(PG8_SB(1, 1), b3 + hstepB, voffB); PG8_STAGE(PG8_SA(1, 0), a3, voffA);
;             PG8_WAIT_V(8); PG8_WAIT_L(0); PG8_BAR; PG8_MMA(1, 0, At, B0); PG8_MMA(1, 1, At, B1); PG8_BAR; PG8_SCHED;
.Lp9k_B_nobar:
	ds_read_b128 v[194:197], v157 offset:0
	ds_read_b128 v[198:201], v157 offset:1024
	s_add_i32 m0, s60, 0xa000
	ds_read_b128 v[202:205], v157 offset:2048
	global_load_lds_dwordx4 v134, s[28:29]
	ds_read_b128 v[206:209], v157 offset:3072
	ds_read_b128 v[210:213], v157 offset:4096
	s_add_u32 s30, s28, 0x58000
	s_addc_u32 s31, s29, 0
	s_add_i32 m0, s60, 0xb000
	ds_read_b128 v[214:217], v157 offset:5120
	global_load_lds_dwordx4 v134, s[30:31]
	ds_read_b128 v[218:221], v157 offset:6144
	ds_read_b128 v[222:225], v157 offset:7168
	s_add_u32 s30, s28, 0x160000
	s_addc_u32 s31, s29, 0
	s_add_i32 m0, s60, 0xe000
	ds_read_b128 v[158:161], v155 offset:0
	global_load_lds_dwordx4 v134, s[30:31]
	ds_read_b128 v[162:165], v155 offset:1024
	ds_read_b128 v[166:169], v155 offset:2048
	s_add_u32 s30, s28, 0x1b8000
	s_addc_u32 s31, s29, 0
	s_add_i32 m0, s60, 0xf000
	ds_read_b128 v[174:177], v155 offset:3072
	global_load_lds_dwordx4 v134, s[30:31]
	ds_read_b128 v[178:181], v155 offset:16384
	ds_read_b128 v[182:185], v155 offset:17408
	s_add_u32 s34, s28, 0x80
	s_addc_u32 s35, s29, 0
	s_cmp_eq_u32 s57, 43
	s_cselect_b32 s34, s58, s34
	s_cselect_b32 s35, s59, s35
	s_add_i32 m0, s60, 0x0
	ds_read_b128 v[186:189], v155 offset:18432
	global_load_lds_dwordx4 v130, s[34:35]
	ds_read_b128 v[190:193], v155 offset:19456
	ds_read_b128 v[226:229], v157 offset:16384
	s_add_u32 s30, s34, 0x58000
	s_addc_u32 s31, s35, 0
	s_add_i32 m0, s60, 0x1000
	ds_read_b128 v[230:233], v157 offset:17408
	global_load_lds_dwordx4 v130, s[30:31]
	ds_read_b128 v[234:237], v157 offset:18432
	ds_read_b128 v[238:241], v157 offset:19456
	s_add_u32 s30, s34, 0x160000
	s_addc_u32 s31, s35, 0
	s_add_i32 m0, s60, 0x4000
	ds_read_b128 v[242:245], v157 offset:20480
	global_load_lds_dwordx4 v130, s[30:31]
	ds_read_b128 v[246:249], v157 offset:21504
	ds_read_b128 v[250:253], v157 offset:22528
	s_add_u32 s30, s34, 0x1b8000
	s_addc_u32 s31, s35, 0
	s_add_i32 m0, s60, 0x5000
	ds_read_b128 v[142:145], v157 offset:23552
	global_load_lds_dwordx4 v130, s[30:31]
	s_add_u32 s28, s28, 0x80
	s_addc_u32 s29, s29, 0
	s_waitcnt vmcnt(8) lgkmcnt(0)
	s_barrier
	v_mfma_f32_16x16x32_bf16 v[126:129], v[158:161], v[194:197], 0
	v_mfma_f32_16x16x32_bf16 v[126:129], v[162:165], v[198:201], v[126:129]
	v_mfma_f32_16x16x32_bf16 v[122:125], v[174:177], v[198:201], 0
	v_mfma_f32_16x16x32_bf16 v[122:125], v[166:169], v[194:197], v[122:125]
	v_mfma_f32_16x16x32_bf16 v[114:117], v[178:181], v[194:197], 0
	v_mfma_f32_16x16x32_bf16 v[114:117], v[182:185], v[198:201], v[114:117]
	v_mfma_f32_16x16x32_bf16 v[106:109], v[190:193], v[198:201], 0
	v_mfma_f32_16x16x32_bf16 v[106:109], v[186:189], v[194:197], v[106:109]
	v_mfma_f32_16x16x32_bf16 v[90:93], v[186:189], v[202:205], 0
	v_mfma_f32_16x16x32_bf16 v[90:93], v[190:193], v[206:209], v[90:93]
	v_mfma_f32_16x16x32_bf16 v[98:101], v[182:185], v[206:209], 0
	v_mfma_f32_16x16x32_bf16 v[98:101], v[178:181], v[202:205], v[98:101]
	v_mfma_f32_16x16x32_bf16 v[110:113], v[166:169], v[202:205], 0
	v_mfma_f32_16x16x32_bf16 v[110:113], v[174:177], v[206:209], v[110:113]
	v_mfma_f32_16x16x32_bf16 v[118:121], v[162:165], v[206:209], 0
	v_mfma_f32_16x16x32_bf16 v[118:121], v[158:161], v[202:205], v[118:121]
	v_mfma_f32_16x16x32_bf16 v[102:105], v[158:161], v[210:213], 0
	v_mfma_f32_16x16x32_bf16 v[102:105], v[162:165], v[214:217], v[102:105]
	v_mfma_f32_16x16x32_bf16 v[94:97], v[174:177], v[214:217], 0
	v_mfma_f32_16x16x32_bf16 v[94:97], v[166:169], v[210:213], v[94:97]
	v_mfma_f32_16x16x32_bf16 v[82:85], v[178:181], v[210:213], 0
	v_mfma_f32_16x16x32_bf16 v[82:85], v[182:185], v[214:217], v[82:85]
	v_mfma_f32_16x16x32_bf16 v[74:77], v[190:193], v[214:217], 0
	v_mfma_f32_16x16x32_bf16 v[74:77], v[186:189], v[210:213], v[74:77]
	v_mfma_f32_16x16x32_bf16 v[66:69], v[186:189], v[218:221], 0
	v_mfma_f32_16x16x32_bf16 v[66:69], v[190:193], v[222:225], v[66:69]
	v_mfma_f32_16x16x32_bf16 v[70:73], v[182:185], v[222:225], 0
	v_mfma_f32_16x16x32_bf16 v[70:73], v[178:181], v[218:221], v[70:73]
	v_mfma_f32_16x16x32_bf16 v[78:81], v[166:169], v[218:221], 0
	v_mfma_f32_16x16x32_bf16 v[78:81], v[174:177], v[222:225], v[78:81]
	v_mfma_f32_16x16x32_bf16 v[86:89], v[162:165], v[222:225], 0
	v_mfma_f32_16x16x32_bf16 v[86:89], v[158:161], v[218:221], v[86:89]
	v_mfma_f32_16x16x32_bf16 v[62:65], v[158:161], v[226:229], 0
	v_mfma_f32_16x16x32_bf16 v[62:65], v[162:165], v[230:233], v[62:65]
	v_mfma_f32_16x16x32_bf16 v[58:61], v[174:177], v[230:233], 0
	v_mfma_f32_16x16x32_bf16 v[58:61], v[166:169], v[226:229], v[58:61]
	v_mfma_f32_16x16x32_bf16 v[50:53], v[178:181], v[226:229], 0
	v_mfma_f32_16x16x32_bf16 v[50:53], v[182:185], v[230:233], v[50:53]
	v_mfma_f32_16x16x32_bf16 v[42:45], v[190:193], v[230:233], 0
	v_mfma_f32_16x16x32_bf16 v[42:45], v[186:189], v[226:229], v[42:45]
	v_mfma_f32_16x16x32_bf16 v[26:29], v[186:189], v[234:237], 0
	v_mfma_f32_16x16x32_bf16 v[26:29], v[190:193], v[238:241], v[26:29]
	v_mfma_f32_16x16x32_bf16 v[34:37], v[182:185], v[238:241], 0
	v_mfma_f32_16x16x32_bf16 v[34:37], v[178:181], v[234:237], v[34:37]
	v_mfma_f32_16x16x32_bf16 v[46:49], v[166:169], v[234:237], 0
	v_mfma_f32_16x16x32_bf16 v[46:49], v[174:177], v[238:241], v[46:49]
	v_mfma_f32_16x16x32_bf16 v[54:57], v[162:165], v[238:241], 0
	v_mfma_f32_16x16x32_bf16 v[54:57], v[158:161], v[234:237], v[54:57]
	v_mfma_f32_16x16x32_bf16 v[38:41], v[158:161], v[242:245], 0
	v_mfma_f32_16x16x32_bf16 v[38:41], v[162:165], v[246:249], v[38:41]
	v_mfma_f32_16x16x32_bf16 v[30:33], v[174:177], v[246:249], 0
	v_mfma_f32_16x16x32_bf16 v[30:33], v[166:169], v[242:245], v[30:33]
	v_mfma_f32_16x16x32_bf16 v[18:21], v[178:181], v[242:245], 0
	v_mfma_f32_16x16x32_bf16 v[18:21], v[182:185], v[246:249], v[18:21]
	v_mfma_f32_16x16x32_bf16 v[10:13], v[190:193], v[246:249], 0
	v_mfma_f32_16x16x32_bf16 v[10:13], v[186:189], v[242:245], v[10:13]
	v_mfma_f32_16x16x32_bf16 v[2:5], v[186:189], v[250:253], 0
	v_mfma_f32_16x16x32_bf16 v[2:5], v[190:193], v[142:145], v[2:5]
	v_mfma_f32_16x16x32_bf16 v[6:9], v[182:185], v[142:145], 0
	v_mfma_f32_16x16x32_bf16 v[6:9], v[178:181], v[250:253], v[6:9]
	v_mfma_f32_16x16x32_bf16 v[14:17], v[166:169], v[250:253], 0
	v_mfma_f32_16x16x32_bf16 v[14:17], v[174:177], v[142:145], v[14:17]
	v_mfma_f32_16x16x32_bf16 v[22:25], v[162:165], v[142:145], 0
	v_mfma_f32_16x16x32_bf16 v[22:25], v[158:161], v[250:253], v[22:25]
	s_waitcnt vmcnt(0)
	s_barrier
; #define PG8_STAGE(bufoff, gbase, voff) do { _Pragma("unroll") for (int _i = 0; _i < 2; ++_i) \
;         __builtin_amdgcn_global_load_lds((const unsigned*)((const char*)(gbase) + (voff)[_i]), (PG8_LAS unsigned*)(lds + (bufoff) + ldsw + _i * 8192), 16, 0, 0); } while (0)
; #define PG8_LDA(dst, b, h) do { _Pragma("unroll") for (int m = 0; m < 4; ++m) _Pragma("unroll") for (int k = 0; k < 2; ++k) dst[m][k] = *(const PG8_LAS bf16x8*)(lds + PG8_SA(b, h) + aoff + m * 2048 + k * 1024); } while (0)
; #define PG8_LDB(dst, b, h) do { _Pragma("unroll") for (int n = 0; n < 2; ++n) _Pragma("unroll") for (int k = 0; k < 2; ++k) dst[n][k] = *(const PG8_LAS bf16x8*)(lds + PG8_SB(b, h) + boff + n * 2048 + k * 1024); } while (0)
; #define PG8_MMA(ai, bj, At, Bt) do { __builtin_amdgcn_s_setprio(1); _Pragma("unroll") for (int m = 0; m < 4; ++m) _Pragma("unroll") for (int n = 0; n < 2; ++n) _Pragma("unroll") for (int k = 0; k < 2; ++k) \
;         acc[ai][bj][m][n] = __builtin_amdgcn_mfma_f32_16x16x32_bf16(Bt[n][k], At[m][k], acc[ai][bj][m][n], 0, 0, 0); __builtin_amdgcn_s_setprio(0); } while (0)
; #define PG8_WAIT_V(n) asm volatile("s_waitcnt vmcnt(" #n ")" ::: "memory")
; #define PG8_WAIT_L(n) asm volatile("s_waitcnt lgkmcnt(" #n ")" ::: "memory")
; #define PG8_BAR __builtin_amdgcn_s_barrier()
; #define PG8_SCHED __builtin_amdgcn_sched_barrier(0)
; template <class Epi, class Sched, bool ALIGN_EPI>
; __device__ __forceinline__ void gemm_phase(PG8_LAS unsigned char* lds, const Gemm g, const Sched& S, const Epi& E) {
;     ...
;             PG8_LDA(At, 0, 1); PG8_STAGE(PG8_SB(0, 0), b2, voffB); PG8_STAGE(PG8_SB(0, 1), b2 + hstepB, voffB); PG8_STAGE(PG8_SA(0, 0), a2, voffA);
;             PG8_WAIT_V(8); PG8_WAIT_L(0); PG8_BAR; PG8_MMA(1, 0, At, B0); PG8_MMA(1, 1, At, B1); PG8_BAR; PG8_SCHED;
;             PG8_LDB(B0, 1, 0); PG8_LDB(B1, 1, 1); PG8_SCHED; PG8_LDA(At, 1, 0); PG8_STAGE(PG8_SA(0, 1), a2 + hstepA, voffA);
;             PG8_WAIT_V(8); PG8_WAIT_L(0); PG8_BAR; PG8_MMA(0, 0, At, B0); PG8_MMA(0, 1, At, B1); PG8_BAR; PG8_SCHED;
;             PG8_LDA(At, 1, 1); PG8_STAGE(PG8_SB(1, 0), b3, voffB); PG8_STAGE(PG8_SB(1, 1), b3 + hstepB, voffB); PG8_STAGE(PG8_SA(1, 0), a3, voffA);
;             PG8_WAIT_V(8); PG8_WAIT_L(0); PG8_BAR; PG8_MMA(1, 0, At, B0); PG8_MMA(1, 1, At, B1); PG8_BAR; PG8_SCHED;
	ds_read_b128 v[194:197], v157 offset:32768
	ds_read_b128 v[198:201], v157 offset:33792
	s_cmp_eq_u32 s57, 43
	s_cselect_b32 s28, s58, s28
	s_cselect_b32 s29, s59, s29
	s_add_i32 m0, s60, 0x2000
	ds_read_b128 v[202:205], v157 offset:34816
	global_load_lds_dwordx4 v134, s[28:29]
	ds_read_b128 v[206:209], v157 offset:35840
	ds_read_b128 v[210:213], v157 offset:36864
	s_add_u32 s30, s28, 0x58000
	s_addc_u32 s31, s29, 0
	s_add_i32 m0, s60, 0x3000
	ds_read_b128 v[214:217], v157 offset:37888
	global_load_lds_dwordx4 v134, s[30:31]
	ds_read_b128 v[218:221], v157 offset:38912
	ds_read_b128 v[222:225], v157 offset:39936
	s_add_u32 s30, s28, 0x160000
	s_addc_u32 s31, s29, 0
	s_add_i32 m0, s60, 0x6000
	ds_read_b128 v[158:161], v155 offset:32768
	global_load_lds_dwordx4 v134, s[30:31]
	ds_read_b128 v[162:165], v155 offset:33792
	ds_read_b128 v[166:169], v155 offset:34816
	s_add_u32 s30, s28, 0x1b8000
	s_addc_u32 s31, s29, 0
	s_add_i32 m0, s60, 0x7000
	ds_read_b128 v[174:177], v155 offset:35840
	global_load_lds_dwordx4 v134, s[30:31]
	ds_read_b128 v[178:181], v155 offset:49152
	ds_read_b128 v[182:185], v155 offset:50176
	s_add_u32 s34, s28, 0x80
	s_addc_u32 s35, s29, 0
	s_add_i32 m0, s60, 0x8000
	ds_read_b128 v[186:189], v155 offset:51200
	global_load_lds_dwordx4 v130, s[34:35]
	ds_read_b128 v[190:193], v155 offset:52224
	ds_read_b128 v[226:229], v157 offset:49152
	s_add_u32 s30, s34, 0x58000
	s_addc_u32 s31, s35, 0
	s_add_i32 m0, s60, 0x9000
	ds_read_b128 v[230:233], v157 offset:50176
	global_load_lds_dwordx4 v130, s[30:31]
	ds_read_b128 v[234:237], v157 offset:51200
	ds_read_b128 v[238:241], v157 offset:52224
	s_add_u32 s30, s34, 0x160000
	s_addc_u32 s31, s35, 0
	s_add_i32 m0, s60, 0xc000
	ds_read_b128 v[242:245], v157 offset:53248
	global_load_lds_dwordx4 v130, s[30:31]
	ds_read_b128 v[246:249], v157 offset:54272
	ds_read_b128 v[250:253], v157 offset:55296
	s_add_u32 s30, s34, 0x1b8000
	s_addc_u32 s31, s35, 0
	s_add_i32 m0, s60, 0xd000
	ds_read_b128 v[142:145], v157 offset:56320
	global_load_lds_dwordx4 v130, s[30:31]
	s_add_u32 s28, s28, 0x80
	s_addc_u32 s29, s29, 0
	s_waitcnt vmcnt(8) lgkmcnt(0)
	s_barrier
	v_mfma_f32_16x16x32_bf16 v[126:129], v[158:161], v[194:197], v[126:129]
	v_mfma_f32_16x16x32_bf16 v[126:129], v[162:165], v[198:201], v[126:129]
	v_mfma_f32_16x16x32_bf16 v[122:125], v[174:177], v[198:201], v[122:125]
	v_mfma_f32_16x16x32_bf16 v[122:125], v[166:169], v[194:197], v[122:125]
	v_mfma_f32_16x16x32_bf16 v[114:117], v[178:181], v[194:197], v[114:117]
	v_mfma_f32_16x16x32_bf16 v[114:117], v[182:185], v[198:201], v[114:117]
	v_mfma_f32_16x16x32_bf16 v[106:109], v[190:193], v[198:201], v[106:109]
	v_mfma_f32_16x16x32_bf16 v[106:109], v[186:189], v[194:197], v[106:109]
	v_mfma_f32_16x16x32_bf16 v[90:93], v[186:189], v[202:205], v[90:93]
	v_mfma_f32_16x16x32_bf16 v[90:93], v[190:193], v[206:209], v[90:93]
	v_mfma_f32_16x16x32_bf16 v[98:101], v[182:185], v[206:209], v[98:101]
	v_mfma_f32_16x16x32_bf16 v[98:101], v[178:181], v[202:205], v[98:101]
	v_mfma_f32_16x16x32_bf16 v[110:113], v[166:169], v[202:205], v[110:113]
	v_mfma_f32_16x16x32_bf16 v[110:113], v[174:177], v[206:209], v[110:113]
	v_mfma_f32_16x16x32_bf16 v[118:121], v[162:165], v[206:209], v[118:121]
	v_mfma_f32_16x16x32_bf16 v[118:121], v[158:161], v[202:205], v[118:121]
	v_mfma_f32_16x16x32_bf16 v[102:105], v[158:161], v[210:213], v[102:105]
	v_mfma_f32_16x16x32_bf16 v[102:105], v[162:165], v[214:217], v[102:105]
	v_mfma_f32_16x16x32_bf16 v[94:97], v[174:177], v[214:217], v[94:97]
	v_mfma_f32_16x16x32_bf16 v[94:97], v[166:169], v[210:213], v[94:97]
	v_mfma_f32_16x16x32_bf16 v[82:85], v[178:181], v[210:213], v[82:85]
	v_mfma_f32_16x16x32_bf16 v[82:85], v[182:185], v[214:217], v[82:85]
	v_mfma_f32_16x16x32_bf16 v[74:77], v[190:193], v[214:217], v[74:77]
	v_mfma_f32_16x16x32_bf16 v[74:77], v[186:189], v[210:213], v[74:77]
	v_mfma_f32_16x16x32_bf16 v[66:69], v[186:189], v[218:221], v[66:69]
	v_mfma_f32_16x16x32_bf16 v[66:69], v[190:193], v[222:225], v[66:69]
	v_mfma_f32_16x16x32_bf16 v[70:73], v[182:185], v[222:225], v[70:73]
	v_mfma_f32_16x16x32_bf16 v[70:73], v[178:181], v[218:221], v[70:73]
	v_mfma_f32_16x16x32_bf16 v[78:81], v[166:169], v[218:221], v[78:81]
	v_mfma_f32_16x16x32_bf16 v[78:81], v[174:177], v[222:225], v[78:81]
	v_mfma_f32_16x16x32_bf16 v[86:89], v[162:165], v[222:225], v[86:89]
	v_mfma_f32_16x16x32_bf16 v[86:89], v[158:161], v[218:221], v[86:89]
	v_mfma_f32_16x16x32_bf16 v[62:65], v[158:161], v[226:229], v[62:65]
	v_mfma_f32_16x16x32_bf16 v[62:65], v[162:165], v[230:233], v[62:65]
	v_mfma_f32_16x16x32_bf16 v[58:61], v[174:177], v[230:233], v[58:61]
	v_mfma_f32_16x16x32_bf16 v[58:61], v[166:169], v[226:229], v[58:61]
	v_mfma_f32_16x16x32_bf16 v[50:53], v[178:181], v[226:229], v[50:53]
	v_mfma_f32_16x16x32_bf16 v[50:53], v[182:185], v[230:233], v[50:53]
	v_mfma_f32_16x16x32_bf16 v[42:45], v[190:193], v[230:233], v[42:45]
	v_mfma_f32_16x16x32_bf16 v[42:45], v[186:189], v[226:229], v[42:45]
	v_mfma_f32_16x16x32_bf16 v[26:29], v[186:189], v[234:237], v[26:29]
	v_mfma_f32_16x16x32_bf16 v[26:29], v[190:193], v[238:241], v[26:29]
	v_mfma_f32_16x16x32_bf16 v[34:37], v[182:185], v[238:241], v[34:37]
	v_mfma_f32_16x16x32_bf16 v[34:37], v[178:181], v[234:237], v[34:37]
	v_mfma_f32_16x16x32_bf16 v[46:49], v[166:169], v[234:237], v[46:49]
	v_mfma_f32_16x16x32_bf16 v[46:49], v[174:177], v[238:241], v[46:49]
	v_mfma_f32_16x16x32_bf16 v[54:57], v[162:165], v[238:241], v[54:57]
	v_mfma_f32_16x16x32_bf16 v[54:57], v[158:161], v[234:237], v[54:57]
	v_mfma_f32_16x16x32_bf16 v[38:41], v[158:161], v[242:245], v[38:41]
	v_mfma_f32_16x16x32_bf16 v[38:41], v[162:165], v[246:249], v[38:41]
	v_mfma_f32_16x16x32_bf16 v[30:33], v[174:177], v[246:249], v[30:33]
	v_mfma_f32_16x16x32_bf16 v[30:33], v[166:169], v[242:245], v[30:33]
	v_mfma_f32_16x16x32_bf16 v[18:21], v[178:181], v[242:245], v[18:21]
	v_mfma_f32_16x16x32_bf16 v[18:21], v[182:185], v[246:249], v[18:21]
	v_mfma_f32_16x16x32_bf16 v[10:13], v[190:193], v[246:249], v[10:13]
	v_mfma_f32_16x16x32_bf16 v[10:13], v[186:189], v[242:245], v[10:13]
	v_mfma_f32_16x16x32_bf16 v[2:5], v[186:189], v[250:253], v[2:5]
	v_mfma_f32_16x16x32_bf16 v[2:5], v[190:193], v[142:145], v[2:5]
	v_mfma_f32_16x16x32_bf16 v[6:9], v[182:185], v[142:145], v[6:9]
	v_mfma_f32_16x16x32_bf16 v[6:9], v[178:181], v[250:253], v[6:9]
	v_mfma_f32_16x16x32_bf16 v[14:17], v[166:169], v[250:253], v[14:17]
	v_mfma_f32_16x16x32_bf16 v[14:17], v[174:177], v[142:145], v[14:17]
	v_mfma_f32_16x16x32_bf16 v[22:25], v[162:165], v[142:145], v[22:25]
	v_mfma_f32_16x16x32_bf16 v[22:25], v[158:161], v[250:253], v[22:25]
	s_waitcnt vmcnt(0)
	s_barrier
	s_add_i32 s57, s57, 1
; #define PG8_STAGE(bufoff, gbase, voff) do { _Pragma("unroll") for (int _i = 0; _i < 2; ++_i) \
;         __builtin_amdgcn_global_load_lds((const unsigned*)((const char*)(gbase) + (voff)[_i]), (PG8_LAS unsigned*)(lds + (bufoff) + ldsw + _i * 8192), 16, 0, 0); } while (0)
; #define PG8_LDA(dst, b, h) do { _Pragma("unroll") for (int m = 0; m < 4; ++m) _Pragma("unroll") for (int k = 0; k < 2; ++k) dst[m][k] = *(const PG8_LAS bf16x8*)(lds + PG8_SA(b, h) + aoff + m * 2048 + k * 1024); } while (0)
; #define PG8_LDB(dst, b, h) do { _Pragma("unroll") for (int n = 0; n < 2; ++n) _Pragma("unroll") for (int k = 0; k < 2; ++k) dst[n][k] = *(const PG8_LAS bf16x8*)(lds + PG8_SB(b, h) + boff + n * 2048 + k * 1024); } while (0)
; #define PG8_MMA(ai, bj, At, Bt) do { __builtin_amdgcn_s_setprio(1); _Pragma("unroll") for (int m = 0; m < 4; ++m) _Pragma("unroll") for (int n = 0; n < 2; ++n) _Pragma("unroll") for (int k = 0; k < 2; ++k) \
;         acc[ai][bj][m][n] = __builtin_amdgcn_mfma_f32_16x16x32_bf16(Bt[n][k], At[m][k], acc[ai][bj][m][n], 0, 0, 0); __builtin_amdgcn_s_setprio(0); } while (0)
; #define PG8_WAIT_V(n) asm volatile("s_waitcnt vmcnt(" #n ")" ::: "memory")
; template <class Epi, class Sched, bool ALIGN_EPI>
; __device__ __forceinline__ void gemm_phase(PG8_LAS unsigned char* lds, const Gemm g, const Sched& S, const Epi& E) {
;     ...
;             PG8_LDB(B0, 0, 0); PG8_LDB(B1, 0, 1); PG8_SCHED; PG8_LDA(At, 0, 0); PG8_STAGE(PG8_SA(1, 1), a1 + hstepA, voffA);
;             PG8_WAIT_V(8); PG8_WAIT_L(0); PG8_BAR; PG8_MMA(0, 0, At, B0); PG8_MMA(0, 1, At, B1); PG8_BAR; PG8_SCHED;
;             PG8_LDA(At, 0, 1); PG8_STAGE(PG8_SB(0, 0), b2, voffB); PG8_STAGE(PG8_SB(0, 1), b2 + hstepB, voffB); PG8_STAGE(PG8_SA(0, 0), a2, voffA);
;             PG8_WAIT_V(8); PG8_WAIT_L(0); PG8_BAR; PG8_MMA(1, 0, At, B0); PG8_MMA(1, 1, At, B1); PG8_BAR; PG8_SCHED;
;             PG8_LDB(B0, 1, 0); PG8_LDB(B1, 1, 1); PG8_SCHED; PG8_LDA(At, 1, 0); PG8_STAGE(PG8_SA(0, 1), a2 + hstepA, voffA);
;             PG8_WAIT_V(8); PG8_WAIT_L(0); PG8_BAR; PG8_MMA(0, 0, At, B0); PG8_MMA(0, 1, At, B1); PG8_BAR; PG8_SCHED;
;             PG8_LDA(At, 1, 1); PG8_STAGE(PG8_SB(1, 0), b3, voffB); PG8_STAGE(PG8_SB(1, 1), b3 + hstepB, voffB); PG8_STAGE(PG8_SA(1, 0), a3, voffA);
;             PG8_WAIT_V(8); PG8_WAIT_L(0); PG8_BAR; PG8_MMA(1, 0, At, B0); PG8_MMA(1, 1, At, B1); PG8_BAR; PG8_SCHED;
.Lp9k_B_loop:
	ds_read_b128 v[194:197], v157 offset:0
	ds_read_b128 v[198:201], v157 offset:1024
	s_add_i32 m0, s60, 0xa000
	ds_read_b128 v[202:205], v157 offset:2048
	global_load_lds_dwordx4 v134, s[28:29]
	ds_read_b128 v[206:209], v157 offset:3072
	ds_read_b128 v[210:213], v157 offset:4096
	s_add_u32 s30, s28, 0x58000
	s_addc_u32 s31, s29, 0
	s_add_i32 m0, s60, 0xb000
	ds_read_b128 v[214:217], v157 offset:5120
	global_load_lds_dwordx4 v134, s[30:31]
	ds_read_b128 v[218:221], v157 offset:6144
	ds_read_b128 v[222:225], v157 offset:7168
	s_add_u32 s30, s28, 0x160000
	s_addc_u32 s31, s29, 0
	s_add_i32 m0, s60, 0xe000
	ds_read_b128 v[158:161], v155 offset:0
	global_load_lds_dwordx4 v134, s[30:31]
	ds_read_b128 v[162:165], v155 offset:1024
	ds_read_b128 v[166:169], v155 offset:2048
	s_add_u32 s30, s28, 0x1b8000
	s_addc_u32 s31, s29, 0
	s_add_i32 m0, s60, 0xf000
	ds_read_b128 v[174:177], v155 offset:3072
	global_load_lds_dwordx4 v134, s[30:31]
	ds_read_b128 v[178:181], v155 offset:16384
	ds_read_b128 v[182:185], v155 offset:17408
	s_add_u32 s34, s28, 0x80
	s_addc_u32 s35, s29, 0
	s_cmp_eq_u32 s57, 43
	s_cselect_b32 s34, s58, s34
	s_cselect_b32 s35, s59, s35
	s_add_i32 m0, s60, 0x0
	ds_read_b128 v[186:189], v155 offset:18432
	global_load_lds_dwordx4 v130, s[34:35]
	ds_read_b128 v[190:193], v155 offset:19456
	ds_read_b128 v[226:229], v157 offset:16384
	s_add_u32 s30, s34, 0x58000
	s_addc_u32 s31, s35, 0
	s_add_i32 m0, s60, 0x1000
	ds_read_b128 v[230:233], v157 offset:17408
	global_load_lds_dwordx4 v130, s[30:31]
	ds_read_b128 v[234:237], v157 offset:18432
	ds_read_b128 v[238:241], v157 offset:19456
	s_add_u32 s30, s34, 0x160000
	s_addc_u32 s31, s35, 0
	s_add_i32 m0, s60, 0x4000
	ds_read_b128 v[242:245], v157 offset:20480
	global_load_lds_dwordx4 v130, s[30:31]
	ds_read_b128 v[246:249], v157 offset:21504
	ds_read_b128 v[250:253], v157 offset:22528
	s_add_u32 s30, s34, 0x1b8000
	s_addc_u32 s31, s35, 0
	s_add_i32 m0, s60, 0x5000
	ds_read_b128 v[142:145], v157 offset:23552
	global_load_lds_dwordx4 v130, s[30:31]
	s_add_u32 s28, s28, 0x80
	s_addc_u32 s29, s29, 0
	s_waitcnt vmcnt(8) lgkmcnt(0)
	s_barrier
	v_mfma_f32_16x16x32_bf16 v[126:129], v[158:161], v[194:197], v[126:129]
	v_mfma_f32_16x16x32_bf16 v[126:129], v[162:165], v[198:201], v[126:129]
	v_mfma_f32_16x16x32_bf16 v[122:125], v[174:177], v[198:201], v[122:125]
	v_mfma_f32_16x16x32_bf16 v[122:125], v[166:169], v[194:197], v[122:125]
	v_mfma_f32_16x16x32_bf16 v[114:117], v[178:181], v[194:197], v[114:117]
	v_mfma_f32_16x16x32_bf16 v[114:117], v[182:185], v[198:201], v[114:117]
	v_mfma_f32_16x16x32_bf16 v[106:109], v[190:193], v[198:201], v[106:109]
	v_mfma_f32_16x16x32_bf16 v[106:109], v[186:189], v[194:197], v[106:109]
	v_mfma_f32_16x16x32_bf16 v[90:93], v[186:189], v[202:205], v[90:93]
	v_mfma_f32_16x16x32_bf16 v[90:93], v[190:193], v[206:209], v[90:93]
	v_mfma_f32_16x16x32_bf16 v[98:101], v[182:185], v[206:209], v[98:101]
	v_mfma_f32_16x16x32_bf16 v[98:101], v[178:181], v[202:205], v[98:101]
	v_mfma_f32_16x16x32_bf16 v[110:113], v[166:169], v[202:205], v[110:113]
	v_mfma_f32_16x16x32_bf16 v[110:113], v[174:177], v[206:209], v[110:113]
	v_mfma_f32_16x16x32_bf16 v[118:121], v[162:165], v[206:209], v[118:121]
	v_mfma_f32_16x16x32_bf16 v[118:121], v[158:161], v[202:205], v[118:121]
	v_mfma_f32_16x16x32_bf16 v[102:105], v[158:161], v[210:213], v[102:105]
	v_mfma_f32_16x16x32_bf16 v[102:105], v[162:165], v[214:217], v[102:105]
	v_mfma_f32_16x16x32_bf16 v[94:97], v[174:177], v[214:217], v[94:97]
	v_mfma_f32_16x16x32_bf16 v[94:97], v[166:169], v[210:213], v[94:97]
	v_mfma_f32_16x16x32_bf16 v[82:85], v[178:181], v[210:213], v[82:85]
	v_mfma_f32_16x16x32_bf16 v[82:85], v[182:185], v[214:217], v[82:85]
	v_mfma_f32_16x16x32_bf16 v[74:77], v[190:193], v[214:217], v[74:77]
	v_mfma_f32_16x16x32_bf16 v[74:77], v[186:189], v[210:213], v[74:77]
	v_mfma_f32_16x16x32_bf16 v[66:69], v[186:189], v[218:221], v[66:69]
	v_mfma_f32_16x16x32_bf16 v[66:69], v[190:193], v[222:225], v[66:69]
	v_mfma_f32_16x16x32_bf16 v[70:73], v[182:185], v[222:225], v[70:73]
	v_mfma_f32_16x16x32_bf16 v[70:73], v[178:181], v[218:221], v[70:73]
	v_mfma_f32_16x16x32_bf16 v[78:81], v[166:169], v[218:221], v[78:81]
	v_mfma_f32_16x16x32_bf16 v[78:81], v[174:177], v[222:225], v[78:81]
	v_mfma_f32_16x16x32_bf16 v[86:89], v[162:165], v[222:225], v[86:89]
	v_mfma_f32_16x16x32_bf16 v[86:89], v[158:161], v[218:221], v[86:89]
	v_mfma_f32_16x16x32_bf16 v[62:65], v[158:161], v[226:229], v[62:65]
	v_mfma_f32_16x16x32_bf16 v[62:65], v[162:165], v[230:233], v[62:65]
	v_mfma_f32_16x16x32_bf16 v[58:61], v[174:177], v[230:233], v[58:61]
	v_mfma_f32_16x16x32_bf16 v[58:61], v[166:169], v[226:229], v[58:61]
	v_mfma_f32_16x16x32_bf16 v[50:53], v[178:181], v[226:229], v[50:53]
	v_mfma_f32_16x16x32_bf16 v[50:53], v[182:185], v[230:233], v[50:53]
	v_mfma_f32_16x16x32_bf16 v[42:45], v[190:193], v[230:233], v[42:45]
	v_mfma_f32_16x16x32_bf16 v[42:45], v[186:189], v[226:229], v[42:45]
	v_mfma_f32_16x16x32_bf16 v[26:29], v[186:189], v[234:237], v[26:29]
	v_mfma_f32_16x16x32_bf16 v[26:29], v[190:193], v[238:241], v[26:29]
	v_mfma_f32_16x16x32_bf16 v[34:37], v[182:185], v[238:241], v[34:37]
	v_mfma_f32_16x16x32_bf16 v[34:37], v[178:181], v[234:237], v[34:37]
	v_mfma_f32_16x16x32_bf16 v[46:49], v[166:169], v[234:237], v[46:49]
	v_mfma_f32_16x16x32_bf16 v[46:49], v[174:177], v[238:241], v[46:49]
	v_mfma_f32_16x16x32_bf16 v[54:57], v[162:165], v[238:241], v[54:57]
	v_mfma_f32_16x16x32_bf16 v[54:57], v[158:161], v[234:237], v[54:57]
	v_mfma_f32_16x16x32_bf16 v[38:41], v[158:161], v[242:245], v[38:41]
	v_mfma_f32_16x16x32_bf16 v[38:41], v[162:165], v[246:249], v[38:41]
	v_mfma_f32_16x16x32_bf16 v[30:33], v[174:177], v[246:249], v[30:33]
	v_mfma_f32_16x16x32_bf16 v[30:33], v[166:169], v[242:245], v[30:33]
	v_mfma_f32_16x16x32_bf16 v[18:21], v[178:181], v[242:245], v[18:21]
	v_mfma_f32_16x16x32_bf16 v[18:21], v[182:185], v[246:249], v[18:21]
	v_mfma_f32_16x16x32_bf16 v[10:13], v[190:193], v[246:249], v[10:13]
	v_mfma_f32_16x16x32_bf16 v[10:13], v[186:189], v[242:245], v[10:13]
	v_mfma_f32_16x16x32_bf16 v[2:5], v[186:189], v[250:253], v[2:5]
	v_mfma_f32_16x16x32_bf16 v[2:5], v[190:193], v[142:145], v[2:5]
	v_mfma_f32_16x16x32_bf16 v[6:9], v[182:185], v[142:145], v[6:9]
	v_mfma_f32_16x16x32_bf16 v[6:9], v[178:181], v[250:253], v[6:9]
	v_mfma_f32_16x16x32_bf16 v[14:17], v[166:169], v[250:253], v[14:17]
	v_mfma_f32_16x16x32_bf16 v[14:17], v[174:177], v[142:145], v[14:17]
	v_mfma_f32_16x16x32_bf16 v[22:25], v[162:165], v[142:145], v[22:25]
	v_mfma_f32_16x16x32_bf16 v[22:25], v[158:161], v[250:253], v[22:25]
	s_waitcnt vmcnt(0)
	s_barrier
; #define PG8_STAGE(bufoff, gbase, voff) do { _Pragma("unroll") for (int _i = 0; _i < 2; ++_i) \
;         __builtin_amdgcn_global_load_lds((const unsigned*)((const char*)(gbase) + (voff)[_i]), (PG8_LAS unsigned*)(lds + (bufoff) + ldsw + _i * 8192), 16, 0, 0); } while (0)
; #define PG8_LDA(dst, b, h) do { _Pragma("unroll") for (int m = 0; m < 4; ++m) _Pragma("unroll") for (int k = 0; k < 2; ++k) dst[m][k] = *(const PG8_LAS bf16x8*)(lds + PG8_SA(b, h) + aoff + m * 2048 + k * 1024); } while (0)
; #define PG8_LDB(dst, b, h) do { _Pragma("unroll") for (int n = 0; n < 2; ++n) _Pragma("unroll") for (int k = 0; k < 2; ++k) dst[n][k] = *(const PG8_LAS bf16x8*)(lds + PG8_SB(b, h) + boff + n * 2048 + k * 1024); } while (0)
; #define PG8_MMA(ai, bj, At, Bt) do { __builtin_amdgcn_s_setprio(1); _Pragma("unroll") for (int m = 0; m < 4; ++m) _Pragma("unroll") for (int n = 0; n < 2; ++n) _Pragma("unroll") for (int k = 0; k < 2; ++k) \
;         acc[ai][bj][m][n] = __builtin_amdgcn_mfma_f32_16x16x32_bf16(Bt[n][k], At[m][k], acc[ai][bj][m][n], 0, 0, 0); __builtin_amdgcn_s_setprio(0); } while (0)
; #define PG8_WAIT_V(n) asm volatile("s_waitcnt vmcnt(" #n ")" ::: "memory")
; #define PG8_WAIT_L(n) asm volatile("s_waitcnt lgkmcnt(" #n ")" ::: "memory")
; #define PG8_BAR __builtin_amdgcn_s_barrier()
; #define PG8_SCHED __builtin_amdgcn_sched_barrier(0)
; template <class Epi, class Sched, bool ALIGN_EPI>
; __device__ __forceinline__ void gemm_phase(PG8_LAS unsigned char* lds, const Gemm g, const Sched& S, const Epi& E) {
;     ...
;             PG8_LDA(At, 0, 1); PG8_STAGE(PG8_SB(0, 0), b2, voffB); PG8_STAGE(PG8_SB(0, 1), b2 + hstepB, voffB); PG8_STAGE(PG8_SA(0, 0), a2, voffA);
;             PG8_WAIT_V(8); PG8_WAIT_L(0); PG8_BAR; PG8_MMA(1, 0, At, B0); PG8_MMA(1, 1, At, B1); PG8_BAR; PG8_SCHED;
;             PG8_LDB(B0, 1, 0); PG8_LDB(B1, 1, 1); PG8_SCHED; PG8_LDA(At, 1, 0); PG8_STAGE(PG8_SA(0, 1), a2 + hstepA, voffA);
;             PG8_WAIT_V(8); PG8_WAIT_L(0); PG8_BAR; PG8_MMA(0, 0, At, B0); PG8_MMA(0, 1, At, B1); PG8_BAR; PG8_SCHED;
;             PG8_LDA(At, 1, 1); PG8_STAGE(PG8_SB(1, 0), b3, voffB); PG8_STAGE(PG8_SB(1, 1), b3 + hstepB, voffB); PG8_STAGE(PG8_SA(1, 0), a3, voffA);
;             PG8_WAIT_V(8); PG8_WAIT_L(0); PG8_BAR; PG8_MMA(1, 0, At, B0); PG8_MMA(1, 1, At, B1); PG8_BAR; PG8_SCHED;
;         }
	ds_read_b128 v[194:197], v157 offset:32768
	ds_read_b128 v[198:201], v157 offset:33792
	s_cmp_eq_u32 s57, 43
	s_cselect_b32 s28, s58, s28
	s_cselect_b32 s29, s59, s29
	s_add_i32 m0, s60, 0x2000
	ds_read_b128 v[202:205], v157 offset:34816
	global_load_lds_dwordx4 v134, s[28:29]
	ds_read_b128 v[206:209], v157 offset:35840
	ds_read_b128 v[210:213], v157 offset:36864
	s_add_u32 s30, s28, 0x58000
	s_addc_u32 s31, s29, 0
	s_add_i32 m0, s60, 0x3000
	ds_read_b128 v[214:217], v157 offset:37888
	global_load_lds_dwordx4 v134, s[30:31]
	ds_read_b128 v[218:221], v157 offset:38912
	ds_read_b128 v[222:225], v157 offset:39936
	s_add_u32 s30, s28, 0x160000
	s_addc_u32 s31, s29, 0
	s_add_i32 m0, s60, 0x6000
	ds_read_b128 v[158:161], v155 offset:32768
	global_load_lds_dwordx4 v134, s[30:31]
	ds_read_b128 v[162:165], v155 offset:33792
	ds_read_b128 v[166:169], v155 offset:34816
	s_add_u32 s30, s28, 0x1b8000
	s_addc_u32 s31, s29, 0
	s_add_i32 m0, s60, 0x7000
	ds_read_b128 v[174:177], v155 offset:35840
	global_load_lds_dwordx4 v134, s[30:31]
	ds_read_b128 v[178:181], v155 offset:49152
	ds_read_b128 v[182:185], v155 offset:50176
	s_add_u32 s34, s28, 0x80
	s_addc_u32 s35, s29, 0
	s_add_i32 m0, s60, 0x8000
	ds_read_b128 v[186:189], v155 offset:51200
	global_load_lds_dwordx4 v130, s[34:35]
	ds_read_b128 v[190:193], v155 offset:52224
	ds_read_b128 v[226:229], v157 offset:49152
	s_add_u32 s30, s34, 0x58000
	s_addc_u32 s31, s35, 0
	s_add_i32 m0, s60, 0x9000
	ds_read_b128 v[230:233], v157 offset:50176
	global_load_lds_dwordx4 v130, s[30:31]
	ds_read_b128 v[234:237], v157 offset:51200
	ds_read_b128 v[238:241], v157 offset:52224
	s_add_u32 s30, s34, 0x160000
	s_addc_u32 s31, s35, 0
	s_add_i32 m0, s60, 0xc000
	ds_read_b128 v[242:245], v157 offset:53248
	global_load_lds_dwordx4 v130, s[30:31]
	ds_read_b128 v[246:249], v157 offset:54272
	ds_read_b128 v[250:253], v157 offset:55296
	s_add_u32 s30, s34, 0x1b8000
	s_addc_u32 s31, s35, 0
	s_add_i32 m0, s60, 0xd000
	ds_read_b128 v[142:145], v157 offset:56320
	global_load_lds_dwordx4 v130, s[30:31]
	s_add_u32 s28, s28, 0x80
	s_addc_u32 s29, s29, 0
	s_waitcnt vmcnt(8) lgkmcnt(0)
	s_barrier
	v_mfma_f32_16x16x32_bf16 v[126:129], v[158:161], v[194:197], v[126:129]
	v_mfma_f32_16x16x32_bf16 v[126:129], v[162:165], v[198:201], v[126:129]
	v_mfma_f32_16x16x32_bf16 v[122:125], v[174:177], v[198:201], v[122:125]
	v_mfma_f32_16x16x32_bf16 v[122:125], v[166:169], v[194:197], v[122:125]
	v_mfma_f32_16x16x32_bf16 v[114:117], v[178:181], v[194:197], v[114:117]
	v_mfma_f32_16x16x32_bf16 v[114:117], v[182:185], v[198:201], v[114:117]
	v_mfma_f32_16x16x32_bf16 v[106:109], v[190:193], v[198:201], v[106:109]
	v_mfma_f32_16x16x32_bf16 v[106:109], v[186:189], v[194:197], v[106:109]
	v_mfma_f32_16x16x32_bf16 v[90:93], v[186:189], v[202:205], v[90:93]
	v_mfma_f32_16x16x32_bf16 v[90:93], v[190:193], v[206:209], v[90:93]
	v_mfma_f32_16x16x32_bf16 v[98:101], v[182:185], v[206:209], v[98:101]
	v_mfma_f32_16x16x32_bf16 v[98:101], v[178:181], v[202:205], v[98:101]
	v_mfma_f32_16x16x32_bf16 v[110:113], v[166:169], v[202:205], v[110:113]
	v_mfma_f32_16x16x32_bf16 v[110:113], v[174:177], v[206:209], v[110:113]
	v_mfma_f32_16x16x32_bf16 v[118:121], v[162:165], v[206:209], v[118:121]
	v_mfma_f32_16x16x32_bf16 v[118:121], v[158:161], v[202:205], v[118:121]
	v_mfma_f32_16x16x32_bf16 v[102:105], v[158:161], v[210:213], v[102:105]
	v_mfma_f32_16x16x32_bf16 v[102:105], v[162:165], v[214:217], v[102:105]
	v_mfma_f32_16x16x32_bf16 v[94:97], v[174:177], v[214:217], v[94:97]
	v_mfma_f32_16x16x32_bf16 v[94:97], v[166:169], v[210:213], v[94:97]
	v_mfma_f32_16x16x32_bf16 v[82:85], v[178:181], v[210:213], v[82:85]
	v_mfma_f32_16x16x32_bf16 v[82:85], v[182:185], v[214:217], v[82:85]
	v_mfma_f32_16x16x32_bf16 v[74:77], v[190:193], v[214:217], v[74:77]
	v_mfma_f32_16x16x32_bf16 v[74:77], v[186:189], v[210:213], v[74:77]
	v_mfma_f32_16x16x32_bf16 v[66:69], v[186:189], v[218:221], v[66:69]
	v_mfma_f32_16x16x32_bf16 v[66:69], v[190:193], v[222:225], v[66:69]
	v_mfma_f32_16x16x32_bf16 v[70:73], v[182:185], v[222:225], v[70:73]
	v_mfma_f32_16x16x32_bf16 v[70:73], v[178:181], v[218:221], v[70:73]
	v_mfma_f32_16x16x32_bf16 v[78:81], v[166:169], v[218:221], v[78:81]
	v_mfma_f32_16x16x32_bf16 v[78:81], v[174:177], v[222:225], v[78:81]
	v_mfma_f32_16x16x32_bf16 v[86:89], v[162:165], v[222:225], v[86:89]
	v_mfma_f32_16x16x32_bf16 v[86:89], v[158:161], v[218:221], v[86:89]
	v_mfma_f32_16x16x32_bf16 v[62:65], v[158:161], v[226:229], v[62:65]
	v_mfma_f32_16x16x32_bf16 v[62:65], v[162:165], v[230:233], v[62:65]
	v_mfma_f32_16x16x32_bf16 v[58:61], v[174:177], v[230:233], v[58:61]
	v_mfma_f32_16x16x32_bf16 v[58:61], v[166:169], v[226:229], v[58:61]
	v_mfma_f32_16x16x32_bf16 v[50:53], v[178:181], v[226:229], v[50:53]
	v_mfma_f32_16x16x32_bf16 v[50:53], v[182:185], v[230:233], v[50:53]
	v_mfma_f32_16x16x32_bf16 v[42:45], v[190:193], v[230:233], v[42:45]
	v_mfma_f32_16x16x32_bf16 v[42:45], v[186:189], v[226:229], v[42:45]
	v_mfma_f32_16x16x32_bf16 v[26:29], v[186:189], v[234:237], v[26:29]
	v_mfma_f32_16x16x32_bf16 v[26:29], v[190:193], v[238:241], v[26:29]
	v_mfma_f32_16x16x32_bf16 v[34:37], v[182:185], v[238:241], v[34:37]
	v_mfma_f32_16x16x32_bf16 v[34:37], v[178:181], v[234:237], v[34:37]
	v_mfma_f32_16x16x32_bf16 v[46:49], v[166:169], v[234:237], v[46:49]
	v_mfma_f32_16x16x32_bf16 v[46:49], v[174:177], v[238:241], v[46:49]
	v_mfma_f32_16x16x32_bf16 v[54:57], v[162:165], v[238:241], v[54:57]
	v_mfma_f32_16x16x32_bf16 v[54:57], v[158:161], v[234:237], v[54:57]
	v_mfma_f32_16x16x32_bf16 v[38:41], v[158:161], v[242:245], v[38:41]
	v_mfma_f32_16x16x32_bf16 v[38:41], v[162:165], v[246:249], v[38:41]
	v_mfma_f32_16x16x32_bf16 v[30:33], v[174:177], v[246:249], v[30:33]
	v_mfma_f32_16x16x32_bf16 v[30:33], v[166:169], v[242:245], v[30:33]
	v_mfma_f32_16x16x32_bf16 v[18:21], v[178:181], v[242:245], v[18:21]
	v_mfma_f32_16x16x32_bf16 v[18:21], v[182:185], v[246:249], v[18:21]
	v_mfma_f32_16x16x32_bf16 v[10:13], v[190:193], v[246:249], v[10:13]
	v_mfma_f32_16x16x32_bf16 v[10:13], v[186:189], v[242:245], v[10:13]
	v_mfma_f32_16x16x32_bf16 v[2:5], v[186:189], v[250:253], v[2:5]
	v_mfma_f32_16x16x32_bf16 v[2:5], v[190:193], v[142:145], v[2:5]
	v_mfma_f32_16x16x32_bf16 v[6:9], v[182:185], v[142:145], v[6:9]
	v_mfma_f32_16x16x32_bf16 v[6:9], v[178:181], v[250:253], v[6:9]
	v_mfma_f32_16x16x32_bf16 v[14:17], v[166:169], v[250:253], v[14:17]
	v_mfma_f32_16x16x32_bf16 v[14:17], v[174:177], v[142:145], v[14:17]
	v_mfma_f32_16x16x32_bf16 v[22:25], v[162:165], v[142:145], v[22:25]
	v_mfma_f32_16x16x32_bf16 v[22:25], v[158:161], v[250:253], v[22:25]
	s_waitcnt vmcnt(0)
	s_add_i32 s57, s57, 1
	s_cmp_lt_u32 s57, 44
	s_cbranch_scc0 .Lp9k_B_exit
	s_barrier
	s_branch .Lp9k_B_loop
